# st2 epilogue tail packed (pk mul/fma, one cvt_pk + d16_hi store, precomputed store addresses); st1 skips the unused rv-row prefetch
# baseline (speedup 1.0000x reference)
; HD float2 cmul(float2 a, float2 b){ return make_float2(a.x*b.x - a.y*b.y, a.x*b.y + a.y*b.x); }
; HD float2 cmulc(float2 a, float2 b){ return make_float2(a.x*b.x + a.y*b.y, a.y*b.x - a.x*b.y); }
; template<bool INV, bool NOTW>
; HD void bf4c(float2* Z, int i0, int i1, int i2, int i3, float2 w1, float2 w2, float2 w3){
;   float2 a0=Z[i0], a1=Z[i1], a2=Z[i2], a3=Z[i3];
;   if (INV && !NOTW){ a1=cmulc(a1,w1); a2=cmulc(a2,w2); a3=cmulc(a3,w3); }
;   float2 s02=make_float2(a0.x+a2.x,a0.y+a2.y), d02=make_float2(a0.x-a2.x,a0.y-a2.y);
;   float2 s13=make_float2(a1.x+a3.x,a1.y+a3.y), d13=make_float2(a1.x-a3.x,a1.y-a3.y);
;   float2 y0=make_float2(s02.x+s13.x,s02.y+s13.y), y2=make_float2(s02.x-s13.x,s02.y-s13.y);
;   float2 ym=make_float2(d02.x+d13.y,d02.y-d13.x);
;   float2 yp=make_float2(d02.x-d13.y,d02.y+d13.x);
;   float2 y1, y3;
;   if (INV){ y1=yp; y3=ym; } else if (NOTW){ y1=ym; y3=yp; } else { y1=cmul(ym,w1); y2=cmul(y2,w2); y3=cmul(yp,w3); }
;   Z[i0]=y0; Z[i1]=y1; Z[i2]=y2; Z[i3]=y3;
; }
; template<bool INV, int LQ, bool BARRIER=true>
; HD void fft_pass(float2* Z, const float2* twA, const float2* twB, int tid){
;     ...
;   } else {
;     int j=tid&(q-1); int base0=((tid>>LQ)<<(LQ+2))+j;
;     float2 w1=make_float2(1.f,0.f), w2=w1, w3=w1;
;     if (LQ>0){ int k=j*tws; w1=cmul(twA[k>>6],twB[k&63]); w2=cmul(w1,w1); w3=cmul(w2,w1); }
;     _Pragma("unroll") for (int i=0;i<8;++i){ int base=base0+i*2048; bf4c<INV,(LQ==0)>(Z,base,base+q,base+2*q,base+3*q,w1,w2,w3); }
;   }
.Lmy_skip_lq2:
	v_add_u32_e32 v14, 0x4000, v169
	v_add_u32_e32 v15, 0x8000, v169
	v_add_u32_e32 v16, 0xc000, v169
	v_add_u32_e32 v17, 0x4000, v186
	v_add_u32_e32 v18, 0x8000, v186
	v_add_u32_e32 v19, 0xc000, v186
	s_mov_b64 s[12:13], -1
	s_and_b64 vcc, exec, s[68:69]
	s_cbranch_vccz .LBB0_1344
	s_cmp_lg_u32 s89, 1
	s_cselect_b64 s[50:51], -1, 0
	s_cmp_eq_u32 s89, 1
	s_cselect_b32 s69, s77, s79
	s_cselect_b32 s68, s76, s78
	v_mov_b32_e32 v68, 0x3f6c835e
	v_mov_b32_e32 v69, 0x3ec3ef15
	v_mov_b32_e32 v70, 0x3f3504f3
	v_mov_b32_e32 v71, 0x3f3504f3
	v_lshrrev_b32_e32 v225, 6, v154
	v_bfe_u32 v226, v154, 4, 2
	v_lshlrev_b32_e32 v225, 8, v225
	v_lshl_add_u32 v225, v226, 11, v225
	v_and_b32_e32 v226, 15, v154
	v_lshl_add_u32 v225, v226, 4, v225
	v_lshlrev_b32_e32 v222, 3, v225
	v_add_u32_e32 v223, 0x10000, v222
	v_lshlrev_b32_e32 v224, 2, v225
	v_bfe_u32 v225, v154, 1, 1
	v_cmp_eq_u32_e64 s[98:99], 1, v225
	v_lshlrev_b32_e32 v225, 4, v225
	s_nop 3
	v_add_u32_e32 v74, v222, v225
	v_sub_u32_e32 v75, v222, v225
	v_add_u32_e32 v80, v222, v225
	v_sub_u32_e32 v81, v222, v225
	ds_read_b128 v[0:3], v74 offset:0
	ds_read_b128 v[4:7], v75 offset:16
	ds_read_b128 v[8:11], v80 offset:32
	ds_read_b128 v[12:15], v81 offset:48
	ds_read_b128 v[16:19], v74 offset:64
	ds_read_b128 v[20:23], v75 offset:80
	ds_read_b128 v[24:27], v80 offset:96
	ds_read_b128 v[28:31], v81 offset:112
	s_waitcnt lgkmcnt(0)
	s_mov_b64 exec, s[98:99]
	v_swap_b32 v0, v4
	v_swap_b32 v1, v5
	v_swap_b32 v2, v6
	v_swap_b32 v3, v7
	v_swap_b32 v8, v12
	v_swap_b32 v9, v13
	v_swap_b32 v10, v14
	v_swap_b32 v11, v15
	v_swap_b32 v16, v20
	v_swap_b32 v17, v21
	v_swap_b32 v18, v22
	v_swap_b32 v19, v23
	v_swap_b32 v24, v28
	v_swap_b32 v25, v29
	v_swap_b32 v26, v30
	v_swap_b32 v27, v31
	s_mov_b64 exec, -1
	v_pk_add_f32 v[58:59], v[0:1], v[16:17]
	v_pk_add_f32 v[60:61], v[0:1], v[16:17] neg_lo:[0,1] neg_hi:[0,1]
	v_pk_add_f32 v[62:63], v[8:9], v[24:25]
	v_pk_add_f32 v[64:65], v[8:9], v[24:25] neg_lo:[0,1] neg_hi:[0,1]
	v_pk_add_f32 v[0:1], v[58:59], v[62:63]
	v_pk_add_f32 v[16:17], v[58:59], v[62:63] neg_lo:[0,1] neg_hi:[0,1]
	v_pk_add_f32 v[8:9], v[60:61], v[64:65] op_sel:[0,1] op_sel_hi:[1,0] neg_hi:[0,1]
	v_pk_add_f32 v[24:25], v[60:61], v[64:65] op_sel:[0,1] op_sel_hi:[1,0] neg_lo:[0,1]
	v_pk_add_f32 v[58:59], v[2:3], v[18:19]
	v_pk_add_f32 v[60:61], v[2:3], v[18:19] neg_lo:[0,1] neg_hi:[0,1]
	v_pk_add_f32 v[62:63], v[10:11], v[26:27]
	v_pk_add_f32 v[64:65], v[10:11], v[26:27] neg_lo:[0,1] neg_hi:[0,1]
	v_pk_add_f32 v[2:3], v[58:59], v[62:63]
	v_pk_add_f32 v[18:19], v[58:59], v[62:63] neg_lo:[0,1] neg_hi:[0,1]
	v_pk_add_f32 v[10:11], v[60:61], v[64:65] op_sel:[0,1] op_sel_hi:[1,0] neg_hi:[0,1]
	v_pk_add_f32 v[26:27], v[60:61], v[64:65] op_sel:[0,1] op_sel_hi:[1,0] neg_lo:[0,1]
	v_pk_mul_f32 v[66:67], v[10:11], v[68:69] op_sel:[1,1] op_sel_hi:[1,0] neg_lo:[0,1] neg_hi:[0,0]
	v_pk_fma_f32 v[10:11], v[10:11], v[68:69], v[66:67] op_sel:[0,0,0] op_sel_hi:[0,1,1] neg_lo:[0,0,1] neg_hi:[0,1,0]
	v_pk_mul_f32 v[66:67], v[18:19], v[70:71] op_sel:[1,1] op_sel_hi:[1,0] neg_lo:[0,1] neg_hi:[0,0]
	v_pk_fma_f32 v[18:19], v[18:19], v[70:71], v[66:67] op_sel:[0,0,0] op_sel_hi:[0,1,1] neg_lo:[0,0,1] neg_hi:[0,1,0]
	v_pk_mul_f32 v[66:67], v[26:27], v[68:69] op_sel:[1,0] op_sel_hi:[1,1] neg_lo:[0,1] neg_hi:[0,0]
	v_pk_fma_f32 v[26:27], v[26:27], v[68:69], v[66:67] op_sel:[0,1,0] op_sel_hi:[0,0,1] neg_lo:[0,0,1] neg_hi:[0,1,0]
	v_pk_add_f32 v[58:59], v[4:5], v[20:21]
	v_pk_add_f32 v[60:61], v[4:5], v[20:21] neg_lo:[0,1] neg_hi:[0,1]
	v_pk_add_f32 v[62:63], v[12:13], v[28:29]
	v_pk_add_f32 v[64:65], v[12:13], v[28:29] neg_lo:[0,1] neg_hi:[0,1]
	v_pk_add_f32 v[4:5], v[58:59], v[62:63]
	v_pk_add_f32 v[20:21], v[58:59], v[62:63] neg_lo:[0,1] neg_hi:[0,1]
	v_pk_add_f32 v[12:13], v[60:61], v[64:65] op_sel:[0,1] op_sel_hi:[1,0] neg_hi:[0,1]
	v_pk_add_f32 v[28:29], v[60:61], v[64:65] op_sel:[0,1] op_sel_hi:[1,0] neg_lo:[0,1]
	v_pk_mul_f32 v[66:67], v[12:13], v[70:71] op_sel:[1,1] op_sel_hi:[1,0] neg_lo:[0,1] neg_hi:[0,0]
	v_pk_fma_f32 v[12:13], v[12:13], v[70:71], v[66:67] op_sel:[0,0,0] op_sel_hi:[0,1,1] neg_lo:[0,0,1] neg_hi:[0,1,0]
	v_pk_add_f32 v[20:21], v[20:21], 0 op_sel:[1,0] op_sel_hi:[0,0] neg_hi:[1,0]
	v_pk_mul_f32 v[66:67], v[28:29], v[70:71] op_sel:[1,1] op_sel_hi:[1,0] neg_lo:[0,1] neg_hi:[0,1]
	v_pk_fma_f32 v[28:29], v[28:29], v[70:71], v[66:67] op_sel:[0,0,0] op_sel_hi:[0,1,1] neg_lo:[0,1,1] neg_hi:[0,1,0]
	v_pk_add_f32 v[58:59], v[6:7], v[22:23]
	v_pk_add_f32 v[60:61], v[6:7], v[22:23] neg_lo:[0,1] neg_hi:[0,1]
	v_pk_add_f32 v[62:63], v[14:15], v[30:31]
	v_pk_add_f32 v[64:65], v[14:15], v[30:31] neg_lo:[0,1] neg_hi:[0,1]
	v_pk_add_f32 v[6:7], v[58:59], v[62:63]
	v_pk_add_f32 v[22:23], v[58:59], v[62:63] neg_lo:[0,1] neg_hi:[0,1]
	v_pk_add_f32 v[14:15], v[60:61], v[64:65] op_sel:[0,1] op_sel_hi:[1,0] neg_hi:[0,1]
	v_pk_add_f32 v[30:31], v[60:61], v[64:65] op_sel:[0,1] op_sel_hi:[1,0] neg_lo:[0,1]
	v_pk_mul_f32 v[66:67], v[14:15], v[68:69] op_sel:[1,0] op_sel_hi:[1,1] neg_lo:[0,1] neg_hi:[0,0]
	v_pk_fma_f32 v[14:15], v[14:15], v[68:69], v[66:67] op_sel:[0,1,0] op_sel_hi:[0,0,1] neg_lo:[0,0,1] neg_hi:[0,1,0]
	v_pk_mul_f32 v[66:67], v[22:23], v[70:71] op_sel:[1,1] op_sel_hi:[1,0] neg_lo:[0,1] neg_hi:[0,1]
	v_pk_fma_f32 v[22:23], v[22:23], v[70:71], v[66:67] op_sel:[0,0,0] op_sel_hi:[0,1,1] neg_lo:[0,1,1] neg_hi:[0,1,0]
	v_pk_mul_f32 v[66:67], v[30:31], v[68:69] op_sel:[1,1] op_sel_hi:[1,0] neg_lo:[0,0] neg_hi:[0,1]
	v_pk_fma_f32 v[30:31], v[30:31], v[68:69], v[66:67] op_sel:[0,0,0] op_sel_hi:[0,1,1] neg_lo:[0,1,1] neg_hi:[0,0,0]
	v_pk_add_f32 v[58:59], v[0:1], v[4:5]
	v_pk_add_f32 v[60:61], v[0:1], v[4:5] neg_lo:[0,1] neg_hi:[0,1]
; HD float2 cmul(float2 a, float2 b){ return make_float2(a.x*b.x - a.y*b.y, a.x*b.y + a.y*b.x); }
; __device__ __forceinline__ void fft_mid(float2* Z, const f16x2* Hp, int tid){
;   _Pragma("unroll 4") for (int i=0;i<8;++i){ int base=(tid<<2)+i*2048;
;     u32x4 hw=*(const u32x4*)(Hp+base);
;     unsigned hw0=hw[0], hw1=hw[1], hw2=hw[2], hw3=hw[3];
;     float2 a0=Z[base], a1=Z[base+1], a2=Z[base+2], a3=Z[base+3];
;     float2 s02=make_float2(a0.x+a2.x,a0.y+a2.y), d02=make_float2(a0.x-a2.x,a0.y-a2.y);
;     float2 s13=make_float2(a1.x+a3.x,a1.y+a3.y), d13=make_float2(a1.x-a3.x,a1.y-a3.y);
;     float2 y0=make_float2(s02.x+s13.x,s02.y+s13.y), y2=make_float2(s02.x-s13.x,s02.y-s13.y);
;     float2 y1=make_float2(d02.x+d13.y,d02.y-d13.x);
;     float2 y3=make_float2(d02.x-d13.y,d02.y+d13.x);
;     f16x2 h0=__builtin_bit_cast(f16x2,hw0), h1=__builtin_bit_cast(f16x2,hw1), h2=__builtin_bit_cast(f16x2,hw2), h3=__builtin_bit_cast(f16x2,hw3);
;     float2 b0=cmul(y0,make_float2((float)h0[0],(float)h0[1])), b1=cmul(y1,make_float2((float)h1[0],(float)h1[1]));
;     float2 b2=cmul(y2,make_float2((float)h2[0],(float)h2[1])), b3=cmul(y3,make_float2((float)h3[0],(float)h3[1]));
	v_pk_add_f32 v[62:63], v[2:3], v[6:7]
	v_pk_add_f32 v[64:65], v[2:3], v[6:7] neg_lo:[0,1] neg_hi:[0,1]
	v_pk_add_f32 v[0:1], v[58:59], v[62:63]
	v_pk_add_f32 v[4:5], v[58:59], v[62:63] neg_lo:[0,1] neg_hi:[0,1]
	v_pk_add_f32 v[2:3], v[60:61], v[64:65] op_sel:[0,1] op_sel_hi:[1,0] neg_hi:[0,1]
	v_pk_add_f32 v[6:7], v[60:61], v[64:65] op_sel:[0,1] op_sel_hi:[1,0] neg_lo:[0,1]
	v_pk_add_f32 v[58:59], v[8:9], v[12:13]
	v_pk_add_f32 v[60:61], v[8:9], v[12:13] neg_lo:[0,1] neg_hi:[0,1]
	v_pk_add_f32 v[62:63], v[10:11], v[14:15]
	v_pk_add_f32 v[64:65], v[10:11], v[14:15] neg_lo:[0,1] neg_hi:[0,1]
	v_pk_add_f32 v[8:9], v[58:59], v[62:63]
	v_pk_add_f32 v[12:13], v[58:59], v[62:63] neg_lo:[0,1] neg_hi:[0,1]
	v_pk_add_f32 v[10:11], v[60:61], v[64:65] op_sel:[0,1] op_sel_hi:[1,0] neg_hi:[0,1]
	v_pk_add_f32 v[14:15], v[60:61], v[64:65] op_sel:[0,1] op_sel_hi:[1,0] neg_lo:[0,1]
	v_pk_add_f32 v[58:59], v[16:17], v[20:21]
	v_pk_add_f32 v[60:61], v[16:17], v[20:21] neg_lo:[0,1] neg_hi:[0,1]
	v_pk_add_f32 v[62:63], v[18:19], v[22:23]
	v_pk_add_f32 v[64:65], v[18:19], v[22:23] neg_lo:[0,1] neg_hi:[0,1]
	v_pk_add_f32 v[16:17], v[58:59], v[62:63]
	v_pk_add_f32 v[20:21], v[58:59], v[62:63] neg_lo:[0,1] neg_hi:[0,1]
	v_pk_add_f32 v[18:19], v[60:61], v[64:65] op_sel:[0,1] op_sel_hi:[1,0] neg_hi:[0,1]
	v_pk_add_f32 v[22:23], v[60:61], v[64:65] op_sel:[0,1] op_sel_hi:[1,0] neg_lo:[0,1]
	v_pk_add_f32 v[58:59], v[24:25], v[28:29]
	v_pk_add_f32 v[60:61], v[24:25], v[28:29] neg_lo:[0,1] neg_hi:[0,1]
	v_pk_add_f32 v[62:63], v[26:27], v[30:31]
	v_pk_add_f32 v[64:65], v[26:27], v[30:31] neg_lo:[0,1] neg_hi:[0,1]
	v_pk_add_f32 v[24:25], v[58:59], v[62:63]
	v_pk_add_f32 v[28:29], v[58:59], v[62:63] neg_lo:[0,1] neg_hi:[0,1]
	v_pk_add_f32 v[26:27], v[60:61], v[64:65] op_sel:[0,1] op_sel_hi:[1,0] neg_hi:[0,1]
	v_pk_add_f32 v[30:31], v[60:61], v[64:65] op_sel:[0,1] op_sel_hi:[1,0] neg_lo:[0,1]
	s_waitcnt vmcnt(0)
	v_cvt_f32_f16_e32 v72, v170
	v_cvt_f32_f16_sdwa v73, v170 dst_sel:DWORD dst_unused:UNUSED_PAD src0_sel:WORD_1
	s_nop 0
	v_pk_mul_f32 v[66:67], v[0:1], v[72:73] op_sel:[1,1] op_sel_hi:[1,0]
	v_pk_fma_f32 v[0:1], v[0:1], v[72:73], v[66:67] op_sel:[0,0,0] op_sel_hi:[0,1,1] neg_lo:[0,0,1]
	v_cvt_f32_f16_e32 v72, v171
	v_cvt_f32_f16_sdwa v73, v171 dst_sel:DWORD dst_unused:UNUSED_PAD src0_sel:WORD_1
	s_nop 0
	v_pk_mul_f32 v[66:67], v[2:3], v[72:73] op_sel:[1,1] op_sel_hi:[1,0]
	v_pk_fma_f32 v[2:3], v[2:3], v[72:73], v[66:67] op_sel:[0,0,0] op_sel_hi:[0,1,1] neg_lo:[0,0,1]
	v_cvt_f32_f16_e32 v72, v172
	v_cvt_f32_f16_sdwa v73, v172 dst_sel:DWORD dst_unused:UNUSED_PAD src0_sel:WORD_1
	s_nop 0
	v_pk_mul_f32 v[66:67], v[4:5], v[72:73] op_sel:[1,1] op_sel_hi:[1,0]
	v_pk_fma_f32 v[4:5], v[4:5], v[72:73], v[66:67] op_sel:[0,0,0] op_sel_hi:[0,1,1] neg_lo:[0,0,1]
	v_cvt_f32_f16_e32 v72, v173
	v_cvt_f32_f16_sdwa v73, v173 dst_sel:DWORD dst_unused:UNUSED_PAD src0_sel:WORD_1
	s_nop 0
	v_pk_mul_f32 v[66:67], v[6:7], v[72:73] op_sel:[1,1] op_sel_hi:[1,0]
	v_pk_fma_f32 v[6:7], v[6:7], v[72:73], v[66:67] op_sel:[0,0,0] op_sel_hi:[0,1,1] neg_lo:[0,0,1]
	v_cvt_f32_f16_e32 v72, v174
	v_cvt_f32_f16_sdwa v73, v174 dst_sel:DWORD dst_unused:UNUSED_PAD src0_sel:WORD_1
	s_nop 0
	v_pk_mul_f32 v[66:67], v[8:9], v[72:73] op_sel:[1,1] op_sel_hi:[1,0]
	v_pk_fma_f32 v[8:9], v[8:9], v[72:73], v[66:67] op_sel:[0,0,0] op_sel_hi:[0,1,1] neg_lo:[0,0,1]
	v_cvt_f32_f16_e32 v72, v175
	v_cvt_f32_f16_sdwa v73, v175 dst_sel:DWORD dst_unused:UNUSED_PAD src0_sel:WORD_1
	s_nop 0
	v_pk_mul_f32 v[66:67], v[10:11], v[72:73] op_sel:[1,1] op_sel_hi:[1,0]
	v_pk_fma_f32 v[10:11], v[10:11], v[72:73], v[66:67] op_sel:[0,0,0] op_sel_hi:[0,1,1] neg_lo:[0,0,1]
	v_cvt_f32_f16_e32 v72, v176
	v_cvt_f32_f16_sdwa v73, v176 dst_sel:DWORD dst_unused:UNUSED_PAD src0_sel:WORD_1
	s_nop 0
	v_pk_mul_f32 v[66:67], v[12:13], v[72:73] op_sel:[1,1] op_sel_hi:[1,0]
	v_pk_fma_f32 v[12:13], v[12:13], v[72:73], v[66:67] op_sel:[0,0,0] op_sel_hi:[0,1,1] neg_lo:[0,0,1]
	v_cvt_f32_f16_e32 v72, v177
	v_cvt_f32_f16_sdwa v73, v177 dst_sel:DWORD dst_unused:UNUSED_PAD src0_sel:WORD_1
	s_nop 0
	v_pk_mul_f32 v[66:67], v[14:15], v[72:73] op_sel:[1,1] op_sel_hi:[1,0]
	v_pk_fma_f32 v[14:15], v[14:15], v[72:73], v[66:67] op_sel:[0,0,0] op_sel_hi:[0,1,1] neg_lo:[0,0,1]
	v_cvt_f32_f16_e32 v72, v178
	v_cvt_f32_f16_sdwa v73, v178 dst_sel:DWORD dst_unused:UNUSED_PAD src0_sel:WORD_1
	s_nop 0
	v_pk_mul_f32 v[66:67], v[16:17], v[72:73] op_sel:[1,1] op_sel_hi:[1,0]
	v_pk_fma_f32 v[16:17], v[16:17], v[72:73], v[66:67] op_sel:[0,0,0] op_sel_hi:[0,1,1] neg_lo:[0,0,1]
	v_cvt_f32_f16_e32 v72, v179
	v_cvt_f32_f16_sdwa v73, v179 dst_sel:DWORD dst_unused:UNUSED_PAD src0_sel:WORD_1
	s_nop 0
	v_pk_mul_f32 v[66:67], v[18:19], v[72:73] op_sel:[1,1] op_sel_hi:[1,0]
	v_pk_fma_f32 v[18:19], v[18:19], v[72:73], v[66:67] op_sel:[0,0,0] op_sel_hi:[0,1,1] neg_lo:[0,0,1]
	v_cvt_f32_f16_e32 v72, v180
	v_cvt_f32_f16_sdwa v73, v180 dst_sel:DWORD dst_unused:UNUSED_PAD src0_sel:WORD_1
	s_nop 0
	v_pk_mul_f32 v[66:67], v[20:21], v[72:73] op_sel:[1,1] op_sel_hi:[1,0]
	v_pk_fma_f32 v[20:21], v[20:21], v[72:73], v[66:67] op_sel:[0,0,0] op_sel_hi:[0,1,1] neg_lo:[0,0,1]
	v_cvt_f32_f16_e32 v72, v181
	v_cvt_f32_f16_sdwa v73, v181 dst_sel:DWORD dst_unused:UNUSED_PAD src0_sel:WORD_1
	s_nop 0
	v_pk_mul_f32 v[66:67], v[22:23], v[72:73] op_sel:[1,1] op_sel_hi:[1,0]
	v_pk_fma_f32 v[22:23], v[22:23], v[72:73], v[66:67] op_sel:[0,0,0] op_sel_hi:[0,1,1] neg_lo:[0,0,1]
	v_cvt_f32_f16_e32 v72, v182
	v_cvt_f32_f16_sdwa v73, v182 dst_sel:DWORD dst_unused:UNUSED_PAD src0_sel:WORD_1
	s_nop 0
	v_pk_mul_f32 v[66:67], v[24:25], v[72:73] op_sel:[1,1] op_sel_hi:[1,0]
	v_pk_fma_f32 v[24:25], v[24:25], v[72:73], v[66:67] op_sel:[0,0,0] op_sel_hi:[0,1,1] neg_lo:[0,0,1]
; HD float2 cmul(float2 a, float2 b){ return make_float2(a.x*b.x - a.y*b.y, a.x*b.y + a.y*b.x); }
; HD float2 cmulc(float2 a, float2 b){ return make_float2(a.x*b.x + a.y*b.y, a.y*b.x - a.x*b.y); }
; template<bool INV, bool NOTW>
; HD void bf4c(float2* Z, int i0, int i1, int i2, int i3, float2 w1, float2 w2, float2 w3){
;   float2 a0=Z[i0], a1=Z[i1], a2=Z[i2], a3=Z[i3];
;   if (INV && !NOTW){ a1=cmulc(a1,w1); a2=cmulc(a2,w2); a3=cmulc(a3,w3); }
;   float2 s02=make_float2(a0.x+a2.x,a0.y+a2.y), d02=make_float2(a0.x-a2.x,a0.y-a2.y);
;   float2 s13=make_float2(a1.x+a3.x,a1.y+a3.y), d13=make_float2(a1.x-a3.x,a1.y-a3.y);
;   float2 y0=make_float2(s02.x+s13.x,s02.y+s13.y), y2=make_float2(s02.x-s13.x,s02.y-s13.y);
;   float2 ym=make_float2(d02.x+d13.y,d02.y-d13.x);
;   float2 yp=make_float2(d02.x-d13.y,d02.y+d13.x);
;   float2 y1, y3;
;   if (INV){ y1=yp; y3=ym; } else if (NOTW){ y1=ym; y3=yp; } else { y1=cmul(ym,w1); y2=cmul(y2,w2); y3=cmul(yp,w3); }
;   Z[i0]=y0; Z[i1]=y1; Z[i2]=y2; Z[i3]=y3;
; }
; __device__ __forceinline__ void fft_mid(float2* Z, const f16x2* Hp, int tid){
;     ...
;     float2 t02=make_float2(b0.x+b2.x,b0.y+b2.y), e02=make_float2(b0.x-b2.x,b0.y-b2.y);
;     float2 t13=make_float2(b1.x+b3.x,b1.y+b3.y), e13=make_float2(b1.x-b3.x,b1.y-b3.y);
;     Z[base]=make_float2(t02.x+t13.x,t02.y+t13.y); Z[base+2]=make_float2(t02.x-t13.x,t02.y-t13.y);
;     Z[base+1]=make_float2(e02.x-e13.y,e02.y+e13.x);
;     Z[base+3]=make_float2(e02.x+e13.y,e02.y-e13.x);
	v_cvt_f32_f16_e32 v72, v183
	v_cvt_f32_f16_sdwa v73, v183 dst_sel:DWORD dst_unused:UNUSED_PAD src0_sel:WORD_1
	s_nop 0
	v_pk_mul_f32 v[66:67], v[26:27], v[72:73] op_sel:[1,1] op_sel_hi:[1,0]
	v_pk_fma_f32 v[26:27], v[26:27], v[72:73], v[66:67] op_sel:[0,0,0] op_sel_hi:[0,1,1] neg_lo:[0,0,1]
	v_cvt_f32_f16_e32 v72, v184
	v_cvt_f32_f16_sdwa v73, v184 dst_sel:DWORD dst_unused:UNUSED_PAD src0_sel:WORD_1
	s_nop 0
	v_pk_mul_f32 v[66:67], v[28:29], v[72:73] op_sel:[1,1] op_sel_hi:[1,0]
	v_pk_fma_f32 v[28:29], v[28:29], v[72:73], v[66:67] op_sel:[0,0,0] op_sel_hi:[0,1,1] neg_lo:[0,0,1]
	v_cvt_f32_f16_e32 v72, v185
	v_cvt_f32_f16_sdwa v73, v185 dst_sel:DWORD dst_unused:UNUSED_PAD src0_sel:WORD_1
	s_nop 0
	v_pk_mul_f32 v[66:67], v[30:31], v[72:73] op_sel:[1,1] op_sel_hi:[1,0]
	v_pk_fma_f32 v[30:31], v[30:31], v[72:73], v[66:67] op_sel:[0,0,0] op_sel_hi:[0,1,1] neg_lo:[0,0,1]
	v_pk_add_f32 v[58:59], v[0:1], v[4:5]
	v_pk_add_f32 v[60:61], v[0:1], v[4:5] neg_lo:[0,1] neg_hi:[0,1]
	v_pk_add_f32 v[62:63], v[2:3], v[6:7]
	v_pk_add_f32 v[64:65], v[2:3], v[6:7] neg_lo:[0,1] neg_hi:[0,1]
	v_pk_add_f32 v[0:1], v[58:59], v[62:63]
	v_pk_add_f32 v[4:5], v[58:59], v[62:63] neg_lo:[0,1] neg_hi:[0,1]
	v_pk_add_f32 v[2:3], v[60:61], v[64:65] op_sel:[0,1] op_sel_hi:[1,0] neg_lo:[0,1]
	v_pk_add_f32 v[6:7], v[60:61], v[64:65] op_sel:[0,1] op_sel_hi:[1,0] neg_hi:[0,1]
	v_pk_add_f32 v[58:59], v[8:9], v[12:13]
	v_pk_add_f32 v[60:61], v[8:9], v[12:13] neg_lo:[0,1] neg_hi:[0,1]
	v_pk_add_f32 v[62:63], v[10:11], v[14:15]
	v_pk_add_f32 v[64:65], v[10:11], v[14:15] neg_lo:[0,1] neg_hi:[0,1]
	v_pk_add_f32 v[8:9], v[58:59], v[62:63]
	v_pk_add_f32 v[12:13], v[58:59], v[62:63] neg_lo:[0,1] neg_hi:[0,1]
	v_pk_add_f32 v[10:11], v[60:61], v[64:65] op_sel:[0,1] op_sel_hi:[1,0] neg_lo:[0,1]
	v_pk_add_f32 v[14:15], v[60:61], v[64:65] op_sel:[0,1] op_sel_hi:[1,0] neg_hi:[0,1]
	v_pk_add_f32 v[58:59], v[16:17], v[20:21]
	v_pk_add_f32 v[60:61], v[16:17], v[20:21] neg_lo:[0,1] neg_hi:[0,1]
	v_pk_add_f32 v[62:63], v[18:19], v[22:23]
	v_pk_add_f32 v[64:65], v[18:19], v[22:23] neg_lo:[0,1] neg_hi:[0,1]
	v_pk_add_f32 v[16:17], v[58:59], v[62:63]
	v_pk_add_f32 v[20:21], v[58:59], v[62:63] neg_lo:[0,1] neg_hi:[0,1]
	v_pk_add_f32 v[18:19], v[60:61], v[64:65] op_sel:[0,1] op_sel_hi:[1,0] neg_lo:[0,1]
	v_pk_add_f32 v[22:23], v[60:61], v[64:65] op_sel:[0,1] op_sel_hi:[1,0] neg_hi:[0,1]
	v_pk_add_f32 v[58:59], v[24:25], v[28:29]
	v_pk_add_f32 v[60:61], v[24:25], v[28:29] neg_lo:[0,1] neg_hi:[0,1]
	v_pk_add_f32 v[62:63], v[26:27], v[30:31]
	v_pk_add_f32 v[64:65], v[26:27], v[30:31] neg_lo:[0,1] neg_hi:[0,1]
	v_pk_add_f32 v[24:25], v[58:59], v[62:63]
	v_pk_add_f32 v[28:29], v[58:59], v[62:63] neg_lo:[0,1] neg_hi:[0,1]
	v_pk_add_f32 v[26:27], v[60:61], v[64:65] op_sel:[0,1] op_sel_hi:[1,0] neg_lo:[0,1]
	v_pk_add_f32 v[30:31], v[60:61], v[64:65] op_sel:[0,1] op_sel_hi:[1,0] neg_hi:[0,1]
	v_pk_add_f32 v[58:59], v[0:1], v[16:17]
	v_pk_add_f32 v[60:61], v[0:1], v[16:17] neg_lo:[0,1] neg_hi:[0,1]
	v_pk_add_f32 v[62:63], v[8:9], v[24:25]
	v_pk_add_f32 v[64:65], v[8:9], v[24:25] neg_lo:[0,1] neg_hi:[0,1]
	v_pk_add_f32 v[0:1], v[58:59], v[62:63]
	v_pk_add_f32 v[16:17], v[58:59], v[62:63] neg_lo:[0,1] neg_hi:[0,1]
	v_pk_add_f32 v[8:9], v[60:61], v[64:65] op_sel:[0,1] op_sel_hi:[1,0] neg_lo:[0,1]
	v_pk_add_f32 v[24:25], v[60:61], v[64:65] op_sel:[0,1] op_sel_hi:[1,0] neg_hi:[0,1]
	v_pk_mul_f32 v[66:67], v[10:11], v[68:69] op_sel:[1,1] op_sel_hi:[1,0] neg_lo:[0,0] neg_hi:[0,0]
	v_pk_fma_f32 v[10:11], v[10:11], v[68:69], v[66:67] op_sel:[0,0,0] op_sel_hi:[0,1,1] neg_lo:[0,0,1] neg_hi:[0,0,0]
	v_pk_mul_f32 v[66:67], v[18:19], v[70:71] op_sel:[1,1] op_sel_hi:[1,0] neg_lo:[0,0] neg_hi:[0,0]
	v_pk_fma_f32 v[18:19], v[18:19], v[70:71], v[66:67] op_sel:[0,0,0] op_sel_hi:[0,1,1] neg_lo:[0,0,1] neg_hi:[0,0,0]
	v_pk_mul_f32 v[66:67], v[26:27], v[68:69] op_sel:[1,0] op_sel_hi:[1,1] neg_lo:[0,0] neg_hi:[0,0]
	v_pk_fma_f32 v[26:27], v[26:27], v[68:69], v[66:67] op_sel:[0,1,0] op_sel_hi:[0,0,1] neg_lo:[0,0,1] neg_hi:[0,0,0]
	v_pk_add_f32 v[58:59], v[2:3], v[18:19]
	v_pk_add_f32 v[60:61], v[2:3], v[18:19] neg_lo:[0,1] neg_hi:[0,1]
	v_pk_add_f32 v[62:63], v[10:11], v[26:27]
	v_pk_add_f32 v[64:65], v[10:11], v[26:27] neg_lo:[0,1] neg_hi:[0,1]
	v_pk_add_f32 v[2:3], v[58:59], v[62:63]
	v_pk_add_f32 v[18:19], v[58:59], v[62:63] neg_lo:[0,1] neg_hi:[0,1]
	v_pk_add_f32 v[10:11], v[60:61], v[64:65] op_sel:[0,1] op_sel_hi:[1,0] neg_lo:[0,1]
	v_pk_add_f32 v[26:27], v[60:61], v[64:65] op_sel:[0,1] op_sel_hi:[1,0] neg_hi:[0,1]
	v_pk_mul_f32 v[66:67], v[12:13], v[70:71] op_sel:[1,1] op_sel_hi:[1,0] neg_lo:[0,0] neg_hi:[0,0]
	v_pk_fma_f32 v[12:13], v[12:13], v[70:71], v[66:67] op_sel:[0,0,0] op_sel_hi:[0,1,1] neg_lo:[0,0,1] neg_hi:[0,0,0]
	v_pk_add_f32 v[20:21], v[20:21], 0 op_sel:[1,0] op_sel_hi:[0,0] neg_lo:[1,0]
	v_pk_mul_f32 v[66:67], v[28:29], v[70:71] op_sel:[1,1] op_sel_hi:[1,0] neg_lo:[0,0] neg_hi:[0,1]
	v_pk_fma_f32 v[28:29], v[28:29], v[70:71], v[66:67] op_sel:[0,0,0] op_sel_hi:[0,1,1] neg_lo:[0,1,1] neg_hi:[0,0,0]
	v_pk_add_f32 v[58:59], v[4:5], v[20:21]
	v_pk_add_f32 v[60:61], v[4:5], v[20:21] neg_lo:[0,1] neg_hi:[0,1]
	v_pk_add_f32 v[62:63], v[12:13], v[28:29]
	v_pk_add_f32 v[64:65], v[12:13], v[28:29] neg_lo:[0,1] neg_hi:[0,1]
	v_pk_add_f32 v[4:5], v[58:59], v[62:63]
	v_pk_add_f32 v[20:21], v[58:59], v[62:63] neg_lo:[0,1] neg_hi:[0,1]
	v_pk_add_f32 v[12:13], v[60:61], v[64:65] op_sel:[0,1] op_sel_hi:[1,0] neg_lo:[0,1]
	v_pk_add_f32 v[28:29], v[60:61], v[64:65] op_sel:[0,1] op_sel_hi:[1,0] neg_hi:[0,1]
	v_pk_mul_f32 v[66:67], v[14:15], v[68:69] op_sel:[1,0] op_sel_hi:[1,1] neg_lo:[0,0] neg_hi:[0,0]
; HD float2 cmul(float2 a, float2 b){ return make_float2(a.x*b.x - a.y*b.y, a.x*b.y + a.y*b.x); }
; template<bool INV, int LQ, bool BARRIER=true>
; HD void fft_pass(float2* Z, const float2* twA, const float2* twB, int tid){
;     ...
;   } else {
;     int j=tid&(q-1); int base0=((tid>>LQ)<<(LQ+2))+j;
;     float2 w1=make_float2(1.f,0.f), w2=w1, w3=w1;
;     if (LQ>0){ int k=j*tws; w1=cmul(twA[k>>6],twB[k&63]); w2=cmul(w1,w1); w3=cmul(w2,w1); }
;     _Pragma("unroll") for (int i=0;i<8;++i){ int base=base0+i*2048; bf4c<INV,(LQ==0)>(Z,base,base+q,base+2*q,base+3*q,w1,w2,w3); }
;   }
;   if (BARRIER) __syncthreads(); else asm volatile("s_waitcnt lgkmcnt(0)" ::: "memory");
; __device__ __forceinline__ void fft_mid(float2* Z, const f16x2* Hp, int tid){
;   _Pragma("unroll 4") for (int i=0;i<8;++i){ int base=(tid<<2)+i*2048;
;     u32x4 hw=*(const u32x4*)(Hp+base);
;     unsigned hw0=hw[0], hw1=hw[1], hw2=hw[2], hw3=hw[3];
;     float2 a0=Z[base], a1=Z[base+1], a2=Z[base+2], a3=Z[base+3];
;     float2 s02=make_float2(a0.x+a2.x,a0.y+a2.y), d02=make_float2(a0.x-a2.x,a0.y-a2.y);
;     float2 s13=make_float2(a1.x+a3.x,a1.y+a3.y), d13=make_float2(a1.x-a3.x,a1.y-a3.y);
;     float2 y0=make_float2(s02.x+s13.x,s02.y+s13.y), y2=make_float2(s02.x-s13.x,s02.y-s13.y);
;     float2 y1=make_float2(d02.x+d13.y,d02.y-d13.x);
;     float2 y3=make_float2(d02.x-d13.y,d02.y+d13.x);
	v_pk_fma_f32 v[14:15], v[14:15], v[68:69], v[66:67] op_sel:[0,1,0] op_sel_hi:[0,0,1] neg_lo:[0,0,1] neg_hi:[0,0,0]
	v_pk_mul_f32 v[66:67], v[22:23], v[70:71] op_sel:[1,1] op_sel_hi:[1,0] neg_lo:[0,0] neg_hi:[0,1]
	v_pk_fma_f32 v[22:23], v[22:23], v[70:71], v[66:67] op_sel:[0,0,0] op_sel_hi:[0,1,1] neg_lo:[0,1,1] neg_hi:[0,0,0]
	v_pk_mul_f32 v[66:67], v[30:31], v[68:69] op_sel:[1,1] op_sel_hi:[1,0] neg_lo:[0,1] neg_hi:[0,1]
	v_pk_fma_f32 v[30:31], v[30:31], v[68:69], v[66:67] op_sel:[0,0,0] op_sel_hi:[0,1,1] neg_lo:[0,1,1] neg_hi:[0,1,0]
	v_pk_add_f32 v[58:59], v[6:7], v[22:23]
	v_pk_add_f32 v[60:61], v[6:7], v[22:23] neg_lo:[0,1] neg_hi:[0,1]
	v_pk_add_f32 v[62:63], v[14:15], v[30:31]
	v_pk_add_f32 v[64:65], v[14:15], v[30:31] neg_lo:[0,1] neg_hi:[0,1]
	v_pk_add_f32 v[6:7], v[58:59], v[62:63]
	v_pk_add_f32 v[22:23], v[58:59], v[62:63] neg_lo:[0,1] neg_hi:[0,1]
	v_pk_add_f32 v[14:15], v[60:61], v[64:65] op_sel:[0,1] op_sel_hi:[1,0] neg_lo:[0,1]
	v_pk_add_f32 v[30:31], v[60:61], v[64:65] op_sel:[0,1] op_sel_hi:[1,0] neg_hi:[0,1]
	s_mov_b64 exec, s[98:99]
	v_swap_b32 v0, v4
	v_swap_b32 v1, v5
	v_swap_b32 v2, v6
	v_swap_b32 v3, v7
	v_swap_b32 v8, v12
	v_swap_b32 v9, v13
	v_swap_b32 v10, v14
	v_swap_b32 v11, v15
	v_swap_b32 v16, v20
	v_swap_b32 v17, v21
	v_swap_b32 v18, v22
	v_swap_b32 v19, v23
	v_swap_b32 v24, v28
	v_swap_b32 v25, v29
	v_swap_b32 v26, v30
	v_swap_b32 v27, v31
	s_mov_b64 exec, -1
	ds_write_b128 v74, v[0:3] offset:0
	ds_write_b128 v75, v[4:7] offset:16
	ds_write_b128 v80, v[8:11] offset:32
	ds_write_b128 v81, v[12:15] offset:48
	ds_write_b128 v74, v[16:19] offset:64
	ds_write_b128 v75, v[20:23] offset:80
	ds_write_b128 v80, v[24:27] offset:96
	ds_write_b128 v81, v[28:31] offset:112
	v_add_u32_e32 v74, v223, v225
	v_sub_u32_e32 v75, v223, v225
	v_add_u32_e32 v80, v223, v225
	v_sub_u32_e32 v81, v223, v225
	ds_read_b128 v[0:3], v74 offset:0
	ds_read_b128 v[4:7], v75 offset:16
	ds_read_b128 v[8:11], v80 offset:32
	ds_read_b128 v[12:15], v81 offset:48
	ds_read_b128 v[16:19], v74 offset:64
	ds_read_b128 v[20:23], v75 offset:80
	ds_read_b128 v[24:27], v80 offset:96
	ds_read_b128 v[28:31], v81 offset:112
	s_waitcnt lgkmcnt(0)
	s_mov_b64 exec, s[98:99]
	v_swap_b32 v0, v4
	v_swap_b32 v1, v5
	v_swap_b32 v2, v6
	v_swap_b32 v3, v7
	v_swap_b32 v8, v12
	v_swap_b32 v9, v13
	v_swap_b32 v10, v14
	v_swap_b32 v11, v15
	v_swap_b32 v16, v20
	v_swap_b32 v17, v21
	v_swap_b32 v18, v22
	v_swap_b32 v19, v23
	v_swap_b32 v24, v28
	v_swap_b32 v25, v29
	v_swap_b32 v26, v30
	v_swap_b32 v27, v31
	s_mov_b64 exec, -1
	v_pk_add_f32 v[58:59], v[0:1], v[16:17]
	v_pk_add_f32 v[60:61], v[0:1], v[16:17] neg_lo:[0,1] neg_hi:[0,1]
	v_pk_add_f32 v[62:63], v[8:9], v[24:25]
	v_pk_add_f32 v[64:65], v[8:9], v[24:25] neg_lo:[0,1] neg_hi:[0,1]
	v_pk_add_f32 v[0:1], v[58:59], v[62:63]
	v_pk_add_f32 v[16:17], v[58:59], v[62:63] neg_lo:[0,1] neg_hi:[0,1]
	v_pk_add_f32 v[8:9], v[60:61], v[64:65] op_sel:[0,1] op_sel_hi:[1,0] neg_hi:[0,1]
	v_pk_add_f32 v[24:25], v[60:61], v[64:65] op_sel:[0,1] op_sel_hi:[1,0] neg_lo:[0,1]
	v_pk_add_f32 v[58:59], v[2:3], v[18:19]
	v_pk_add_f32 v[60:61], v[2:3], v[18:19] neg_lo:[0,1] neg_hi:[0,1]
	v_pk_add_f32 v[62:63], v[10:11], v[26:27]
	v_pk_add_f32 v[64:65], v[10:11], v[26:27] neg_lo:[0,1] neg_hi:[0,1]
	v_pk_add_f32 v[2:3], v[58:59], v[62:63]
	v_pk_add_f32 v[18:19], v[58:59], v[62:63] neg_lo:[0,1] neg_hi:[0,1]
	v_pk_add_f32 v[10:11], v[60:61], v[64:65] op_sel:[0,1] op_sel_hi:[1,0] neg_hi:[0,1]
	v_pk_add_f32 v[26:27], v[60:61], v[64:65] op_sel:[0,1] op_sel_hi:[1,0] neg_lo:[0,1]
	v_pk_mul_f32 v[66:67], v[10:11], v[68:69] op_sel:[1,1] op_sel_hi:[1,0] neg_lo:[0,1] neg_hi:[0,0]
	v_pk_fma_f32 v[10:11], v[10:11], v[68:69], v[66:67] op_sel:[0,0,0] op_sel_hi:[0,1,1] neg_lo:[0,0,1] neg_hi:[0,1,0]
	v_pk_mul_f32 v[66:67], v[18:19], v[70:71] op_sel:[1,1] op_sel_hi:[1,0] neg_lo:[0,1] neg_hi:[0,0]
	v_pk_fma_f32 v[18:19], v[18:19], v[70:71], v[66:67] op_sel:[0,0,0] op_sel_hi:[0,1,1] neg_lo:[0,0,1] neg_hi:[0,1,0]
	v_pk_mul_f32 v[66:67], v[26:27], v[68:69] op_sel:[1,0] op_sel_hi:[1,1] neg_lo:[0,1] neg_hi:[0,0]
	v_pk_fma_f32 v[26:27], v[26:27], v[68:69], v[66:67] op_sel:[0,1,0] op_sel_hi:[0,0,1] neg_lo:[0,0,1] neg_hi:[0,1,0]
	v_pk_add_f32 v[58:59], v[4:5], v[20:21]
	v_pk_add_f32 v[60:61], v[4:5], v[20:21] neg_lo:[0,1] neg_hi:[0,1]
	v_pk_add_f32 v[62:63], v[12:13], v[28:29]
	v_pk_add_f32 v[64:65], v[12:13], v[28:29] neg_lo:[0,1] neg_hi:[0,1]
	v_pk_add_f32 v[4:5], v[58:59], v[62:63]
	v_pk_add_f32 v[20:21], v[58:59], v[62:63] neg_lo:[0,1] neg_hi:[0,1]
	v_pk_add_f32 v[12:13], v[60:61], v[64:65] op_sel:[0,1] op_sel_hi:[1,0] neg_hi:[0,1]
	v_pk_add_f32 v[28:29], v[60:61], v[64:65] op_sel:[0,1] op_sel_hi:[1,0] neg_lo:[0,1]
	v_pk_mul_f32 v[66:67], v[12:13], v[70:71] op_sel:[1,1] op_sel_hi:[1,0] neg_lo:[0,1] neg_hi:[0,0]
	v_pk_fma_f32 v[12:13], v[12:13], v[70:71], v[66:67] op_sel:[0,0,0] op_sel_hi:[0,1,1] neg_lo:[0,0,1] neg_hi:[0,1,0]
	v_pk_add_f32 v[20:21], v[20:21], 0 op_sel:[1,0] op_sel_hi:[0,0] neg_hi:[1,0]
	v_pk_mul_f32 v[66:67], v[28:29], v[70:71] op_sel:[1,1] op_sel_hi:[1,0] neg_lo:[0,1] neg_hi:[0,1]
	v_pk_fma_f32 v[28:29], v[28:29], v[70:71], v[66:67] op_sel:[0,0,0] op_sel_hi:[0,1,1] neg_lo:[0,1,1] neg_hi:[0,1,0]
	v_pk_add_f32 v[58:59], v[6:7], v[22:23]
	v_pk_add_f32 v[60:61], v[6:7], v[22:23] neg_lo:[0,1] neg_hi:[0,1]
	v_pk_add_f32 v[62:63], v[14:15], v[30:31]
	v_pk_add_f32 v[64:65], v[14:15], v[30:31] neg_lo:[0,1] neg_hi:[0,1]
	v_pk_add_f32 v[6:7], v[58:59], v[62:63]
	v_pk_add_f32 v[22:23], v[58:59], v[62:63] neg_lo:[0,1] neg_hi:[0,1]
	v_pk_add_f32 v[14:15], v[60:61], v[64:65] op_sel:[0,1] op_sel_hi:[1,0] neg_hi:[0,1]
	v_pk_add_f32 v[30:31], v[60:61], v[64:65] op_sel:[0,1] op_sel_hi:[1,0] neg_lo:[0,1]
; HD float2 cmul(float2 a, float2 b){ return make_float2(a.x*b.x - a.y*b.y, a.x*b.y + a.y*b.x); }
; __device__ __forceinline__ void fft_mid(float2* Z, const f16x2* Hp, int tid){
;   _Pragma("unroll 4") for (int i=0;i<8;++i){ int base=(tid<<2)+i*2048;
;     u32x4 hw=*(const u32x4*)(Hp+base);
;     unsigned hw0=hw[0], hw1=hw[1], hw2=hw[2], hw3=hw[3];
;     float2 a0=Z[base], a1=Z[base+1], a2=Z[base+2], a3=Z[base+3];
;     float2 s02=make_float2(a0.x+a2.x,a0.y+a2.y), d02=make_float2(a0.x-a2.x,a0.y-a2.y);
;     float2 s13=make_float2(a1.x+a3.x,a1.y+a3.y), d13=make_float2(a1.x-a3.x,a1.y-a3.y);
;     float2 y0=make_float2(s02.x+s13.x,s02.y+s13.y), y2=make_float2(s02.x-s13.x,s02.y-s13.y);
;     float2 y1=make_float2(d02.x+d13.y,d02.y-d13.x);
;     float2 y3=make_float2(d02.x-d13.y,d02.y+d13.x);
;     f16x2 h0=__builtin_bit_cast(f16x2,hw0), h1=__builtin_bit_cast(f16x2,hw1), h2=__builtin_bit_cast(f16x2,hw2), h3=__builtin_bit_cast(f16x2,hw3);
;     float2 b0=cmul(y0,make_float2((float)h0[0],(float)h0[1])), b1=cmul(y1,make_float2((float)h1[0],(float)h1[1]));
;     float2 b2=cmul(y2,make_float2((float)h2[0],(float)h2[1])), b3=cmul(y3,make_float2((float)h3[0],(float)h3[1]));
	v_pk_mul_f32 v[66:67], v[14:15], v[68:69] op_sel:[1,0] op_sel_hi:[1,1] neg_lo:[0,1] neg_hi:[0,0]
	v_pk_fma_f32 v[14:15], v[14:15], v[68:69], v[66:67] op_sel:[0,1,0] op_sel_hi:[0,0,1] neg_lo:[0,0,1] neg_hi:[0,1,0]
	v_pk_mul_f32 v[66:67], v[22:23], v[70:71] op_sel:[1,1] op_sel_hi:[1,0] neg_lo:[0,1] neg_hi:[0,1]
	v_pk_fma_f32 v[22:23], v[22:23], v[70:71], v[66:67] op_sel:[0,0,0] op_sel_hi:[0,1,1] neg_lo:[0,1,1] neg_hi:[0,1,0]
	v_pk_mul_f32 v[66:67], v[30:31], v[68:69] op_sel:[1,1] op_sel_hi:[1,0] neg_lo:[0,0] neg_hi:[0,1]
	v_pk_fma_f32 v[30:31], v[30:31], v[68:69], v[66:67] op_sel:[0,0,0] op_sel_hi:[0,1,1] neg_lo:[0,1,1] neg_hi:[0,0,0]
	v_pk_add_f32 v[58:59], v[0:1], v[4:5]
	v_pk_add_f32 v[60:61], v[0:1], v[4:5] neg_lo:[0,1] neg_hi:[0,1]
	v_pk_add_f32 v[62:63], v[2:3], v[6:7]
	v_pk_add_f32 v[64:65], v[2:3], v[6:7] neg_lo:[0,1] neg_hi:[0,1]
	v_pk_add_f32 v[0:1], v[58:59], v[62:63]
	v_pk_add_f32 v[4:5], v[58:59], v[62:63] neg_lo:[0,1] neg_hi:[0,1]
	v_pk_add_f32 v[2:3], v[60:61], v[64:65] op_sel:[0,1] op_sel_hi:[1,0] neg_hi:[0,1]
	v_pk_add_f32 v[6:7], v[60:61], v[64:65] op_sel:[0,1] op_sel_hi:[1,0] neg_lo:[0,1]
	v_pk_add_f32 v[58:59], v[8:9], v[12:13]
	v_pk_add_f32 v[60:61], v[8:9], v[12:13] neg_lo:[0,1] neg_hi:[0,1]
	v_pk_add_f32 v[62:63], v[10:11], v[14:15]
	v_pk_add_f32 v[64:65], v[10:11], v[14:15] neg_lo:[0,1] neg_hi:[0,1]
	v_pk_add_f32 v[8:9], v[58:59], v[62:63]
	v_pk_add_f32 v[12:13], v[58:59], v[62:63] neg_lo:[0,1] neg_hi:[0,1]
	v_pk_add_f32 v[10:11], v[60:61], v[64:65] op_sel:[0,1] op_sel_hi:[1,0] neg_hi:[0,1]
	v_pk_add_f32 v[14:15], v[60:61], v[64:65] op_sel:[0,1] op_sel_hi:[1,0] neg_lo:[0,1]
	v_pk_add_f32 v[58:59], v[16:17], v[20:21]
	v_pk_add_f32 v[60:61], v[16:17], v[20:21] neg_lo:[0,1] neg_hi:[0,1]
	v_pk_add_f32 v[62:63], v[18:19], v[22:23]
	v_pk_add_f32 v[64:65], v[18:19], v[22:23] neg_lo:[0,1] neg_hi:[0,1]
	v_pk_add_f32 v[16:17], v[58:59], v[62:63]
	v_pk_add_f32 v[20:21], v[58:59], v[62:63] neg_lo:[0,1] neg_hi:[0,1]
	v_pk_add_f32 v[18:19], v[60:61], v[64:65] op_sel:[0,1] op_sel_hi:[1,0] neg_hi:[0,1]
	v_pk_add_f32 v[22:23], v[60:61], v[64:65] op_sel:[0,1] op_sel_hi:[1,0] neg_lo:[0,1]
	v_pk_add_f32 v[58:59], v[24:25], v[28:29]
	v_pk_add_f32 v[60:61], v[24:25], v[28:29] neg_lo:[0,1] neg_hi:[0,1]
	v_pk_add_f32 v[62:63], v[26:27], v[30:31]
	v_pk_add_f32 v[64:65], v[26:27], v[30:31] neg_lo:[0,1] neg_hi:[0,1]
	v_pk_add_f32 v[24:25], v[58:59], v[62:63]
	v_pk_add_f32 v[28:29], v[58:59], v[62:63] neg_lo:[0,1] neg_hi:[0,1]
	v_pk_add_f32 v[26:27], v[60:61], v[64:65] op_sel:[0,1] op_sel_hi:[1,0] neg_hi:[0,1]
	v_pk_add_f32 v[30:31], v[60:61], v[64:65] op_sel:[0,1] op_sel_hi:[1,0] neg_lo:[0,1]
	s_waitcnt vmcnt(0)
	v_cvt_f32_f16_e32 v72, v150
	v_cvt_f32_f16_sdwa v73, v150 dst_sel:DWORD dst_unused:UNUSED_PAD src0_sel:WORD_1
	s_nop 0
	v_pk_mul_f32 v[66:67], v[0:1], v[72:73] op_sel:[1,1] op_sel_hi:[1,0]
	v_pk_fma_f32 v[0:1], v[0:1], v[72:73], v[66:67] op_sel:[0,0,0] op_sel_hi:[0,1,1] neg_lo:[0,0,1]
	v_cvt_f32_f16_e32 v72, v151
	v_cvt_f32_f16_sdwa v73, v151 dst_sel:DWORD dst_unused:UNUSED_PAD src0_sel:WORD_1
	s_nop 0
	v_pk_mul_f32 v[66:67], v[2:3], v[72:73] op_sel:[1,1] op_sel_hi:[1,0]
	v_pk_fma_f32 v[2:3], v[2:3], v[72:73], v[66:67] op_sel:[0,0,0] op_sel_hi:[0,1,1] neg_lo:[0,0,1]
	v_cvt_f32_f16_e32 v72, v152
	v_cvt_f32_f16_sdwa v73, v152 dst_sel:DWORD dst_unused:UNUSED_PAD src0_sel:WORD_1
	s_nop 0
	v_pk_mul_f32 v[66:67], v[4:5], v[72:73] op_sel:[1,1] op_sel_hi:[1,0]
	v_pk_fma_f32 v[4:5], v[4:5], v[72:73], v[66:67] op_sel:[0,0,0] op_sel_hi:[0,1,1] neg_lo:[0,0,1]
	v_cvt_f32_f16_e32 v72, v153
	v_cvt_f32_f16_sdwa v73, v153 dst_sel:DWORD dst_unused:UNUSED_PAD src0_sel:WORD_1
	s_nop 0
	v_pk_mul_f32 v[66:67], v[6:7], v[72:73] op_sel:[1,1] op_sel_hi:[1,0]
	v_pk_fma_f32 v[6:7], v[6:7], v[72:73], v[66:67] op_sel:[0,0,0] op_sel_hi:[0,1,1] neg_lo:[0,0,1]
	v_cvt_f32_f16_e32 v72, v156
	v_cvt_f32_f16_sdwa v73, v156 dst_sel:DWORD dst_unused:UNUSED_PAD src0_sel:WORD_1
	s_nop 0
	v_pk_mul_f32 v[66:67], v[8:9], v[72:73] op_sel:[1,1] op_sel_hi:[1,0]
	v_pk_fma_f32 v[8:9], v[8:9], v[72:73], v[66:67] op_sel:[0,0,0] op_sel_hi:[0,1,1] neg_lo:[0,0,1]
	v_cvt_f32_f16_e32 v72, v157
	v_cvt_f32_f16_sdwa v73, v157 dst_sel:DWORD dst_unused:UNUSED_PAD src0_sel:WORD_1
	s_nop 0
	v_pk_mul_f32 v[66:67], v[10:11], v[72:73] op_sel:[1,1] op_sel_hi:[1,0]
	v_pk_fma_f32 v[10:11], v[10:11], v[72:73], v[66:67] op_sel:[0,0,0] op_sel_hi:[0,1,1] neg_lo:[0,0,1]
	v_cvt_f32_f16_e32 v72, v158
	v_cvt_f32_f16_sdwa v73, v158 dst_sel:DWORD dst_unused:UNUSED_PAD src0_sel:WORD_1
	s_nop 0
	v_pk_mul_f32 v[66:67], v[12:13], v[72:73] op_sel:[1,1] op_sel_hi:[1,0]
	v_pk_fma_f32 v[12:13], v[12:13], v[72:73], v[66:67] op_sel:[0,0,0] op_sel_hi:[0,1,1] neg_lo:[0,0,1]
	v_cvt_f32_f16_e32 v72, v159
	v_cvt_f32_f16_sdwa v73, v159 dst_sel:DWORD dst_unused:UNUSED_PAD src0_sel:WORD_1
	s_nop 0
	v_pk_mul_f32 v[66:67], v[14:15], v[72:73] op_sel:[1,1] op_sel_hi:[1,0]
	v_pk_fma_f32 v[14:15], v[14:15], v[72:73], v[66:67] op_sel:[0,0,0] op_sel_hi:[0,1,1] neg_lo:[0,0,1]
	v_cvt_f32_f16_e32 v72, v160
	v_cvt_f32_f16_sdwa v73, v160 dst_sel:DWORD dst_unused:UNUSED_PAD src0_sel:WORD_1
	s_nop 0
	v_pk_mul_f32 v[66:67], v[16:17], v[72:73] op_sel:[1,1] op_sel_hi:[1,0]
	v_pk_fma_f32 v[16:17], v[16:17], v[72:73], v[66:67] op_sel:[0,0,0] op_sel_hi:[0,1,1] neg_lo:[0,0,1]
	v_cvt_f32_f16_e32 v72, v161
	v_cvt_f32_f16_sdwa v73, v161 dst_sel:DWORD dst_unused:UNUSED_PAD src0_sel:WORD_1
	s_nop 0
	v_pk_mul_f32 v[66:67], v[18:19], v[72:73] op_sel:[1,1] op_sel_hi:[1,0]
	v_pk_fma_f32 v[18:19], v[18:19], v[72:73], v[66:67] op_sel:[0,0,0] op_sel_hi:[0,1,1] neg_lo:[0,0,1]
	v_cvt_f32_f16_e32 v72, v162
	v_cvt_f32_f16_sdwa v73, v162 dst_sel:DWORD dst_unused:UNUSED_PAD src0_sel:WORD_1
; HD float2 cmul(float2 a, float2 b){ return make_float2(a.x*b.x - a.y*b.y, a.x*b.y + a.y*b.x); }
; __device__ __forceinline__ void fft_mid(float2* Z, const f16x2* Hp, int tid){
;     ...
;     f16x2 h0=__builtin_bit_cast(f16x2,hw0), h1=__builtin_bit_cast(f16x2,hw1), h2=__builtin_bit_cast(f16x2,hw2), h3=__builtin_bit_cast(f16x2,hw3);
;     float2 b0=cmul(y0,make_float2((float)h0[0],(float)h0[1])), b1=cmul(y1,make_float2((float)h1[0],(float)h1[1]));
;     float2 b2=cmul(y2,make_float2((float)h2[0],(float)h2[1])), b3=cmul(y3,make_float2((float)h3[0],(float)h3[1]));
;     float2 t02=make_float2(b0.x+b2.x,b0.y+b2.y), e02=make_float2(b0.x-b2.x,b0.y-b2.y);
;     float2 t13=make_float2(b1.x+b3.x,b1.y+b3.y), e13=make_float2(b1.x-b3.x,b1.y-b3.y);
;     Z[base]=make_float2(t02.x+t13.x,t02.y+t13.y); Z[base+2]=make_float2(t02.x-t13.x,t02.y-t13.y);
;     Z[base+1]=make_float2(e02.x-e13.y,e02.y+e13.x);
;     Z[base+3]=make_float2(e02.x+e13.y,e02.y-e13.x);
	s_nop 0
	v_pk_mul_f32 v[66:67], v[20:21], v[72:73] op_sel:[1,1] op_sel_hi:[1,0]
	v_pk_fma_f32 v[20:21], v[20:21], v[72:73], v[66:67] op_sel:[0,0,0] op_sel_hi:[0,1,1] neg_lo:[0,0,1]
	v_cvt_f32_f16_e32 v72, v163
	v_cvt_f32_f16_sdwa v73, v163 dst_sel:DWORD dst_unused:UNUSED_PAD src0_sel:WORD_1
	s_nop 0
	v_pk_mul_f32 v[66:67], v[22:23], v[72:73] op_sel:[1,1] op_sel_hi:[1,0]
	v_pk_fma_f32 v[22:23], v[22:23], v[72:73], v[66:67] op_sel:[0,0,0] op_sel_hi:[0,1,1] neg_lo:[0,0,1]
	v_cvt_f32_f16_e32 v72, v164
	v_cvt_f32_f16_sdwa v73, v164 dst_sel:DWORD dst_unused:UNUSED_PAD src0_sel:WORD_1
	s_nop 0
	v_pk_mul_f32 v[66:67], v[24:25], v[72:73] op_sel:[1,1] op_sel_hi:[1,0]
	v_pk_fma_f32 v[24:25], v[24:25], v[72:73], v[66:67] op_sel:[0,0,0] op_sel_hi:[0,1,1] neg_lo:[0,0,1]
	v_cvt_f32_f16_e32 v72, v165
	v_cvt_f32_f16_sdwa v73, v165 dst_sel:DWORD dst_unused:UNUSED_PAD src0_sel:WORD_1
	s_nop 0
	v_pk_mul_f32 v[66:67], v[26:27], v[72:73] op_sel:[1,1] op_sel_hi:[1,0]
	v_pk_fma_f32 v[26:27], v[26:27], v[72:73], v[66:67] op_sel:[0,0,0] op_sel_hi:[0,1,1] neg_lo:[0,0,1]
	v_cvt_f32_f16_e32 v72, v166
	v_cvt_f32_f16_sdwa v73, v166 dst_sel:DWORD dst_unused:UNUSED_PAD src0_sel:WORD_1
	s_nop 0
	v_pk_mul_f32 v[66:67], v[28:29], v[72:73] op_sel:[1,1] op_sel_hi:[1,0]
	v_pk_fma_f32 v[28:29], v[28:29], v[72:73], v[66:67] op_sel:[0,0,0] op_sel_hi:[0,1,1] neg_lo:[0,0,1]
	v_cvt_f32_f16_e32 v72, v167
	v_cvt_f32_f16_sdwa v73, v167 dst_sel:DWORD dst_unused:UNUSED_PAD src0_sel:WORD_1
	s_nop 0
	v_pk_mul_f32 v[66:67], v[30:31], v[72:73] op_sel:[1,1] op_sel_hi:[1,0]
	v_pk_fma_f32 v[30:31], v[30:31], v[72:73], v[66:67] op_sel:[0,0,0] op_sel_hi:[0,1,1] neg_lo:[0,0,1]
	v_pk_add_f32 v[58:59], v[0:1], v[4:5]
	v_pk_add_f32 v[60:61], v[0:1], v[4:5] neg_lo:[0,1] neg_hi:[0,1]
	v_pk_add_f32 v[62:63], v[2:3], v[6:7]
	v_pk_add_f32 v[64:65], v[2:3], v[6:7] neg_lo:[0,1] neg_hi:[0,1]
	v_pk_add_f32 v[0:1], v[58:59], v[62:63]
	v_pk_add_f32 v[4:5], v[58:59], v[62:63] neg_lo:[0,1] neg_hi:[0,1]
	v_pk_add_f32 v[2:3], v[60:61], v[64:65] op_sel:[0,1] op_sel_hi:[1,0] neg_lo:[0,1]
	v_pk_add_f32 v[6:7], v[60:61], v[64:65] op_sel:[0,1] op_sel_hi:[1,0] neg_hi:[0,1]
	v_pk_add_f32 v[58:59], v[8:9], v[12:13]
	v_pk_add_f32 v[60:61], v[8:9], v[12:13] neg_lo:[0,1] neg_hi:[0,1]
	v_pk_add_f32 v[62:63], v[10:11], v[14:15]
	v_pk_add_f32 v[64:65], v[10:11], v[14:15] neg_lo:[0,1] neg_hi:[0,1]
	v_pk_add_f32 v[8:9], v[58:59], v[62:63]
	v_pk_add_f32 v[12:13], v[58:59], v[62:63] neg_lo:[0,1] neg_hi:[0,1]
	v_pk_add_f32 v[10:11], v[60:61], v[64:65] op_sel:[0,1] op_sel_hi:[1,0] neg_lo:[0,1]
	v_pk_add_f32 v[14:15], v[60:61], v[64:65] op_sel:[0,1] op_sel_hi:[1,0] neg_hi:[0,1]
	v_pk_add_f32 v[58:59], v[16:17], v[20:21]
	v_pk_add_f32 v[60:61], v[16:17], v[20:21] neg_lo:[0,1] neg_hi:[0,1]
	v_pk_add_f32 v[62:63], v[18:19], v[22:23]
	v_pk_add_f32 v[64:65], v[18:19], v[22:23] neg_lo:[0,1] neg_hi:[0,1]
	v_pk_add_f32 v[16:17], v[58:59], v[62:63]
	v_pk_add_f32 v[20:21], v[58:59], v[62:63] neg_lo:[0,1] neg_hi:[0,1]
	v_pk_add_f32 v[18:19], v[60:61], v[64:65] op_sel:[0,1] op_sel_hi:[1,0] neg_lo:[0,1]
	v_pk_add_f32 v[22:23], v[60:61], v[64:65] op_sel:[0,1] op_sel_hi:[1,0] neg_hi:[0,1]
	v_pk_add_f32 v[58:59], v[24:25], v[28:29]
	v_pk_add_f32 v[60:61], v[24:25], v[28:29] neg_lo:[0,1] neg_hi:[0,1]
	v_pk_add_f32 v[62:63], v[26:27], v[30:31]
	v_pk_add_f32 v[64:65], v[26:27], v[30:31] neg_lo:[0,1] neg_hi:[0,1]
	v_pk_add_f32 v[24:25], v[58:59], v[62:63]
	v_pk_add_f32 v[28:29], v[58:59], v[62:63] neg_lo:[0,1] neg_hi:[0,1]
	v_pk_add_f32 v[26:27], v[60:61], v[64:65] op_sel:[0,1] op_sel_hi:[1,0] neg_lo:[0,1]
	v_pk_add_f32 v[30:31], v[60:61], v[64:65] op_sel:[0,1] op_sel_hi:[1,0] neg_hi:[0,1]
	v_pk_add_f32 v[58:59], v[0:1], v[16:17]
	v_pk_add_f32 v[60:61], v[0:1], v[16:17] neg_lo:[0,1] neg_hi:[0,1]
	v_pk_add_f32 v[62:63], v[8:9], v[24:25]
	v_pk_add_f32 v[64:65], v[8:9], v[24:25] neg_lo:[0,1] neg_hi:[0,1]
	v_pk_add_f32 v[0:1], v[58:59], v[62:63]
	v_pk_add_f32 v[16:17], v[58:59], v[62:63] neg_lo:[0,1] neg_hi:[0,1]
	v_pk_add_f32 v[8:9], v[60:61], v[64:65] op_sel:[0,1] op_sel_hi:[1,0] neg_lo:[0,1]
	v_pk_add_f32 v[24:25], v[60:61], v[64:65] op_sel:[0,1] op_sel_hi:[1,0] neg_hi:[0,1]
	v_pk_mul_f32 v[66:67], v[10:11], v[68:69] op_sel:[1,1] op_sel_hi:[1,0] neg_lo:[0,0] neg_hi:[0,0]
	v_pk_fma_f32 v[10:11], v[10:11], v[68:69], v[66:67] op_sel:[0,0,0] op_sel_hi:[0,1,1] neg_lo:[0,0,1] neg_hi:[0,0,0]
	v_pk_mul_f32 v[66:67], v[18:19], v[70:71] op_sel:[1,1] op_sel_hi:[1,0] neg_lo:[0,0] neg_hi:[0,0]
	v_pk_fma_f32 v[18:19], v[18:19], v[70:71], v[66:67] op_sel:[0,0,0] op_sel_hi:[0,1,1] neg_lo:[0,0,1] neg_hi:[0,0,0]
	v_pk_mul_f32 v[66:67], v[26:27], v[68:69] op_sel:[1,0] op_sel_hi:[1,1] neg_lo:[0,0] neg_hi:[0,0]
	v_pk_fma_f32 v[26:27], v[26:27], v[68:69], v[66:67] op_sel:[0,1,0] op_sel_hi:[0,0,1] neg_lo:[0,0,1] neg_hi:[0,0,0]
	v_pk_add_f32 v[58:59], v[2:3], v[18:19]
	v_pk_add_f32 v[60:61], v[2:3], v[18:19] neg_lo:[0,1] neg_hi:[0,1]
	v_pk_add_f32 v[62:63], v[10:11], v[26:27]
	v_pk_add_f32 v[64:65], v[10:11], v[26:27] neg_lo:[0,1] neg_hi:[0,1]
	v_pk_add_f32 v[2:3], v[58:59], v[62:63]
	v_pk_add_f32 v[18:19], v[58:59], v[62:63] neg_lo:[0,1] neg_hi:[0,1]
	v_pk_add_f32 v[10:11], v[60:61], v[64:65] op_sel:[0,1] op_sel_hi:[1,0] neg_lo:[0,1]
	v_pk_add_f32 v[26:27], v[60:61], v[64:65] op_sel:[0,1] op_sel_hi:[1,0] neg_hi:[0,1]
	v_pk_mul_f32 v[66:67], v[12:13], v[70:71] op_sel:[1,1] op_sel_hi:[1,0] neg_lo:[0,0] neg_hi:[0,0]
	v_pk_fma_f32 v[12:13], v[12:13], v[70:71], v[66:67] op_sel:[0,0,0] op_sel_hi:[0,1,1] neg_lo:[0,0,1] neg_hi:[0,0,0]
	v_pk_add_f32 v[20:21], v[20:21], 0 op_sel:[1,0] op_sel_hi:[0,0] neg_lo:[1,0]
	v_pk_mul_f32 v[66:67], v[28:29], v[70:71] op_sel:[1,1] op_sel_hi:[1,0] neg_lo:[0,0] neg_hi:[0,1]
; HD float2 cmul(float2 a, float2 b){ return make_float2(a.x*b.x - a.y*b.y, a.x*b.y + a.y*b.x); }
; template<bool INV, int LQ, bool BARRIER=true>
; HD void fft_pass(float2* Z, const float2* twA, const float2* twB, int tid){
;     ...
;   } else {
;     int j=tid&(q-1); int base0=((tid>>LQ)<<(LQ+2))+j;
;     float2 w1=make_float2(1.f,0.f), w2=w1, w3=w1;
;     if (LQ>0){ int k=j*tws; w1=cmul(twA[k>>6],twB[k&63]); w2=cmul(w1,w1); w3=cmul(w2,w1); }
;     _Pragma("unroll") for (int i=0;i<8;++i){ int base=base0+i*2048; bf4c<INV,(LQ==0)>(Z,base,base+q,base+2*q,base+3*q,w1,w2,w3); }
;   }
;   if (BARRIER) __syncthreads(); else asm volatile("s_waitcnt lgkmcnt(0)" ::: "memory");
; __device__ __forceinline__ void fft_inv_tail(float2* Z, const float2* twA, const float2* twB, int tid){
;   fft_pass<true,2,false>(Z,twA,twB,tid); fft_pass<true,4,false>(Z,twA,twB,tid); fft_pass<true,6>(Z,twA,twB,tid);
	v_pk_fma_f32 v[28:29], v[28:29], v[70:71], v[66:67] op_sel:[0,0,0] op_sel_hi:[0,1,1] neg_lo:[0,1,1] neg_hi:[0,0,0]
	v_pk_add_f32 v[58:59], v[4:5], v[20:21]
	v_pk_add_f32 v[60:61], v[4:5], v[20:21] neg_lo:[0,1] neg_hi:[0,1]
	v_pk_add_f32 v[62:63], v[12:13], v[28:29]
	v_pk_add_f32 v[64:65], v[12:13], v[28:29] neg_lo:[0,1] neg_hi:[0,1]
	v_pk_add_f32 v[4:5], v[58:59], v[62:63]
	v_pk_add_f32 v[20:21], v[58:59], v[62:63] neg_lo:[0,1] neg_hi:[0,1]
	v_pk_add_f32 v[12:13], v[60:61], v[64:65] op_sel:[0,1] op_sel_hi:[1,0] neg_lo:[0,1]
	v_pk_add_f32 v[28:29], v[60:61], v[64:65] op_sel:[0,1] op_sel_hi:[1,0] neg_hi:[0,1]
	v_pk_mul_f32 v[66:67], v[14:15], v[68:69] op_sel:[1,0] op_sel_hi:[1,1] neg_lo:[0,0] neg_hi:[0,0]
	v_pk_fma_f32 v[14:15], v[14:15], v[68:69], v[66:67] op_sel:[0,1,0] op_sel_hi:[0,0,1] neg_lo:[0,0,1] neg_hi:[0,0,0]
	v_pk_mul_f32 v[66:67], v[22:23], v[70:71] op_sel:[1,1] op_sel_hi:[1,0] neg_lo:[0,0] neg_hi:[0,1]
	v_pk_fma_f32 v[22:23], v[22:23], v[70:71], v[66:67] op_sel:[0,0,0] op_sel_hi:[0,1,1] neg_lo:[0,1,1] neg_hi:[0,0,0]
	v_pk_mul_f32 v[66:67], v[30:31], v[68:69] op_sel:[1,1] op_sel_hi:[1,0] neg_lo:[0,1] neg_hi:[0,1]
	v_pk_fma_f32 v[30:31], v[30:31], v[68:69], v[66:67] op_sel:[0,0,0] op_sel_hi:[0,1,1] neg_lo:[0,1,1] neg_hi:[0,1,0]
	v_pk_add_f32 v[58:59], v[6:7], v[22:23]
	v_pk_add_f32 v[60:61], v[6:7], v[22:23] neg_lo:[0,1] neg_hi:[0,1]
	v_pk_add_f32 v[62:63], v[14:15], v[30:31]
	v_pk_add_f32 v[64:65], v[14:15], v[30:31] neg_lo:[0,1] neg_hi:[0,1]
	v_pk_add_f32 v[6:7], v[58:59], v[62:63]
	v_pk_add_f32 v[22:23], v[58:59], v[62:63] neg_lo:[0,1] neg_hi:[0,1]
	v_pk_add_f32 v[14:15], v[60:61], v[64:65] op_sel:[0,1] op_sel_hi:[1,0] neg_lo:[0,1]
	v_pk_add_f32 v[30:31], v[60:61], v[64:65] op_sel:[0,1] op_sel_hi:[1,0] neg_hi:[0,1]
	s_mov_b64 exec, s[98:99]
	v_swap_b32 v0, v4
	v_swap_b32 v1, v5
	v_swap_b32 v2, v6
	v_swap_b32 v3, v7
	v_swap_b32 v8, v12
	v_swap_b32 v9, v13
	v_swap_b32 v10, v14
	v_swap_b32 v11, v15
	v_swap_b32 v16, v20
	v_swap_b32 v17, v21
	v_swap_b32 v18, v22
	v_swap_b32 v19, v23
	v_swap_b32 v24, v28
	v_swap_b32 v25, v29
	v_swap_b32 v26, v30
	v_swap_b32 v27, v31
	s_mov_b64 exec, -1
	ds_write_b128 v74, v[0:3] offset:0
	ds_write_b128 v75, v[4:7] offset:16
	ds_write_b128 v80, v[8:11] offset:32
	ds_write_b128 v81, v[12:15] offset:48
	ds_write_b128 v74, v[16:19] offset:64
	ds_write_b128 v75, v[20:23] offset:80
	ds_write_b128 v80, v[24:27] offset:96
	ds_write_b128 v81, v[28:31] offset:112
	s_waitcnt lgkmcnt(0)
	s_mov_b64 s[18:19], 0x8000
	v_lshlrev_b32_e32 v232, 4, v154
	s_lshl_b32 s100, s90, 15
	v_add_u32_e32 v233, 0x2000, v232
	v_add_u32_e32 v234, 0x4000, v232
	v_add_u32_e32 v235, 0x6000, v232
	s_add_u32 s98, s70, 0x42bd000
	s_addc_u32 s99, s71, 0
	s_add_u32 s98, s98, s100
	s_addc_u32 s99, s99, 0
	s_cmp_eq_u32 s89, 1
	s_cbranch_scc1 .Lmy_pf_st1
	s_add_u32 s98, s98, 0x2000000
	s_addc_u32 s99, s99, 0
	global_load_dwordx4 v[228:231], v232, s[98:99]
	global_load_dwordx4 v[228:231], v233, s[98:99]
	global_load_dwordx4 v[228:231], v234, s[98:99]
	global_load_dwordx4 v[228:231], v235, s[98:99]
.Lmy_pf_st1:
	s_add_u32 s98, s98, 0x1000000
	s_addc_u32 s99, s99, 0
	global_load_dwordx4 v[228:231], v232, s[98:99]
	global_load_dwordx4 v[228:231], v233, s[98:99]
	global_load_dwordx4 v[228:231], v234, s[98:99]
	global_load_dwordx4 v[228:231], v235, s[98:99]
	s_waitcnt lgkmcnt(0)
	v_mov_b32_e32 v222, 0x3f6c835e
	v_mov_b32_e32 v223, 0x3ec3ef15
	v_mov_b32_e32 v224, 0x3f3504f3
	v_mov_b32_e32 v225, 0x3f3504f3
	v_and_b32_e32 v8, 15, v154
	v_lshlrev_b32_e32 v9, 3, v8
	v_add_u32_e32 v9, 0x20800, v9
	v_mov_b32_e32 v10, 0x20a00
	ds_read_b64 v[0:1], v9
	ds_read_b64 v[2:3], v10
	s_waitcnt lgkmcnt(0)
	v_pk_mul_f32 v[250:251], v[0:1], v[2:3] op_sel:[1,1] op_sel_hi:[1,0]
	v_pk_fma_f32 v[80:81], v[0:1], v[2:3], v[250:251] op_sel:[0,0,0] op_sel_hi:[0,1,1] neg_lo:[0,0,1]
	v_pk_mul_f32 v[250:251], v[80:81], v[80:81] op_sel:[1,1] op_sel_hi:[1,0]
	v_pk_fma_f32 v[82:83], v[80:81], v[80:81], v[250:251] op_sel:[0,0,0] op_sel_hi:[0,1,1] neg_lo:[0,0,1]
	v_pk_mul_f32 v[250:251], v[82:83], v[80:81] op_sel:[1,1] op_sel_hi:[1,0]
	v_pk_fma_f32 v[84:85], v[82:83], v[80:81], v[250:251] op_sel:[0,0,0] op_sel_hi:[0,1,1] neg_lo:[0,0,1]
	v_lshlrev_b32_e32 v9, 5, v8
	v_add_u32_e32 v9, 0x20800, v9
	v_mov_b32_e32 v10, 0x20a00
	ds_read_b64 v[0:1], v9
	ds_read_b64 v[2:3], v10
	s_waitcnt lgkmcnt(0)
	v_pk_mul_f32 v[250:251], v[0:1], v[2:3] op_sel:[1,1] op_sel_hi:[1,0]
	v_pk_fma_f32 v[236:237], v[0:1], v[2:3], v[250:251] op_sel:[0,0,0] op_sel_hi:[0,1,1] neg_lo:[0,0,1]
	v_pk_mul_f32 v[250:251], v[236:237], v[236:237] op_sel:[1,1] op_sel_hi:[1,0]
	v_pk_fma_f32 v[238:239], v[236:237], v[236:237], v[250:251] op_sel:[0,0,0] op_sel_hi:[0,1,1] neg_lo:[0,0,1]
	v_pk_mul_f32 v[250:251], v[238:239], v[236:237] op_sel:[1,1] op_sel_hi:[1,0]
	v_pk_fma_f32 v[240:241], v[238:239], v[236:237], v[250:251] op_sel:[0,0,0] op_sel_hi:[0,1,1] neg_lo:[0,0,1]
	v_lshrrev_b32_e32 v226, 6, v154
	v_bfe_u32 v227, v154, 4, 2
	v_lshl_add_u32 v226, v227, 3, v226
	v_lshlrev_b32_e32 v226, 8, v226
	v_and_b32_e32 v227, 15, v154
	v_add_u32_e32 v226, v226, v227
	v_lshlrev_b32_e32 v226, 3, v226
	v_add_u32_e32 v227, 0x10000, v226
	ds_read_b64 v[0:1], v226 offset:0
	ds_read_b64 v[2:3], v226 offset:128
	ds_read_b64 v[4:5], v226 offset:256
	ds_read_b64 v[6:7], v226 offset:384
	ds_read_b64 v[8:9], v226 offset:512
	ds_read_b64 v[10:11], v226 offset:640
	ds_read_b64 v[12:13], v226 offset:768
	ds_read_b64 v[14:15], v226 offset:896
	ds_read_b64 v[16:17], v226 offset:1024
	ds_read_b64 v[18:19], v226 offset:1152
	ds_read_b64 v[20:21], v226 offset:1280
	ds_read_b64 v[22:23], v226 offset:1408
	ds_read_b64 v[24:25], v226 offset:1536
	ds_read_b64 v[26:27], v226 offset:1664
	ds_read_b64 v[28:29], v226 offset:1792
	ds_read_b64 v[30:31], v226 offset:1920
	s_waitcnt lgkmcnt(12)
; HD float2 cmul(float2 a, float2 b){ return make_float2(a.x*b.x - a.y*b.y, a.x*b.y + a.y*b.x); }
; HD float2 cmulc(float2 a, float2 b){ return make_float2(a.x*b.x + a.y*b.y, a.y*b.x - a.x*b.y); }
; template<bool INV, bool NOTW>
; HD void bf4c(float2* Z, int i0, int i1, int i2, int i3, float2 w1, float2 w2, float2 w3){
;   float2 a0=Z[i0], a1=Z[i1], a2=Z[i2], a3=Z[i3];
;   if (INV && !NOTW){ a1=cmulc(a1,w1); a2=cmulc(a2,w2); a3=cmulc(a3,w3); }
;   float2 s02=make_float2(a0.x+a2.x,a0.y+a2.y), d02=make_float2(a0.x-a2.x,a0.y-a2.y);
;   float2 s13=make_float2(a1.x+a3.x,a1.y+a3.y), d13=make_float2(a1.x-a3.x,a1.y-a3.y);
;   float2 y0=make_float2(s02.x+s13.x,s02.y+s13.y), y2=make_float2(s02.x-s13.x,s02.y-s13.y);
;   float2 ym=make_float2(d02.x+d13.y,d02.y-d13.x);
;   float2 yp=make_float2(d02.x-d13.y,d02.y+d13.x);
;   float2 y1, y3;
;   if (INV){ y1=yp; y3=ym; } else if (NOTW){ y1=ym; y3=yp; } else { y1=cmul(ym,w1); y2=cmul(y2,w2); y3=cmul(yp,w3); }
;   Z[i0]=y0; Z[i1]=y1; Z[i2]=y2; Z[i3]=y3;
; }
; template<bool INV, int LQ, bool BARRIER=true>
; HD void fft_pass(float2* Z, const float2* twA, const float2* twB, int tid){
;     ...
;   } else {
;     int j=tid&(q-1); int base0=((tid>>LQ)<<(LQ+2))+j;
;     float2 w1=make_float2(1.f,0.f), w2=w1, w3=w1;
;     if (LQ>0){ int k=j*tws; w1=cmul(twA[k>>6],twB[k&63]); w2=cmul(w1,w1); w3=cmul(w2,w1); }
;     _Pragma("unroll") for (int i=0;i<8;++i){ int base=base0+i*2048; bf4c<INV,(LQ==0)>(Z,base,base+q,base+2*q,base+3*q,w1,w2,w3); }
;   }
;   if (BARRIER) __syncthreads(); else asm volatile("s_waitcnt lgkmcnt(0)" ::: "memory");
	v_pk_mul_f32 v[250:251], v[4:5], v[238:239] op_sel:[1,1] op_sel_hi:[0,1]
	v_pk_fma_f32 v[4:5], v[4:5], v[238:239], v[250:251] op_sel:[0,0,0] op_sel_hi:[1,0,1] neg_hi:[0,0,1]
	v_pk_mul_f32 v[250:251], v[2:3], v[236:237] op_sel:[1,1] op_sel_hi:[0,1]
	v_pk_fma_f32 v[2:3], v[2:3], v[236:237], v[250:251] op_sel:[0,0,0] op_sel_hi:[1,0,1] neg_hi:[0,0,1]
	v_pk_mul_f32 v[250:251], v[6:7], v[240:241] op_sel:[1,1] op_sel_hi:[0,1]
	v_pk_fma_f32 v[6:7], v[6:7], v[240:241], v[250:251] op_sel:[0,0,0] op_sel_hi:[1,0,1] neg_hi:[0,0,1]
	v_pk_add_f32 v[242:243], v[0:1], v[4:5]
	v_pk_add_f32 v[244:245], v[0:1], v[4:5] neg_lo:[0,1] neg_hi:[0,1]
	v_pk_add_f32 v[246:247], v[2:3], v[6:7]
	v_pk_add_f32 v[248:249], v[2:3], v[6:7] neg_lo:[0,1] neg_hi:[0,1]
	v_pk_add_f32 v[0:1], v[242:243], v[246:247]
	v_pk_add_f32 v[2:3], v[244:245], v[248:249] op_sel:[0,1] op_sel_hi:[1,0] neg_lo:[0,1]
	v_pk_add_f32 v[4:5], v[242:243], v[246:247] neg_lo:[0,1] neg_hi:[0,1]
	v_pk_add_f32 v[6:7], v[244:245], v[248:249] op_sel:[0,1] op_sel_hi:[1,0] neg_hi:[0,1]
	s_waitcnt lgkmcnt(8)
	v_pk_mul_f32 v[250:251], v[12:13], v[238:239] op_sel:[1,1] op_sel_hi:[0,1]
	v_pk_fma_f32 v[12:13], v[12:13], v[238:239], v[250:251] op_sel:[0,0,0] op_sel_hi:[1,0,1] neg_hi:[0,0,1]
	v_pk_mul_f32 v[250:251], v[10:11], v[236:237] op_sel:[1,1] op_sel_hi:[0,1]
	v_pk_fma_f32 v[10:11], v[10:11], v[236:237], v[250:251] op_sel:[0,0,0] op_sel_hi:[1,0,1] neg_hi:[0,0,1]
	v_pk_mul_f32 v[250:251], v[14:15], v[240:241] op_sel:[1,1] op_sel_hi:[0,1]
	v_pk_fma_f32 v[14:15], v[14:15], v[240:241], v[250:251] op_sel:[0,0,0] op_sel_hi:[1,0,1] neg_hi:[0,0,1]
	v_pk_add_f32 v[242:243], v[8:9], v[12:13]
	v_pk_add_f32 v[244:245], v[8:9], v[12:13] neg_lo:[0,1] neg_hi:[0,1]
	v_pk_add_f32 v[246:247], v[10:11], v[14:15]
	v_pk_add_f32 v[248:249], v[10:11], v[14:15] neg_lo:[0,1] neg_hi:[0,1]
	v_pk_add_f32 v[8:9], v[242:243], v[246:247]
	v_pk_add_f32 v[10:11], v[244:245], v[248:249] op_sel:[0,1] op_sel_hi:[1,0] neg_lo:[0,1]
	v_pk_add_f32 v[12:13], v[242:243], v[246:247] neg_lo:[0,1] neg_hi:[0,1]
	v_pk_add_f32 v[14:15], v[244:245], v[248:249] op_sel:[0,1] op_sel_hi:[1,0] neg_hi:[0,1]
	s_waitcnt lgkmcnt(4)
	v_pk_mul_f32 v[250:251], v[20:21], v[238:239] op_sel:[1,1] op_sel_hi:[0,1]
	v_pk_fma_f32 v[20:21], v[20:21], v[238:239], v[250:251] op_sel:[0,0,0] op_sel_hi:[1,0,1] neg_hi:[0,0,1]
	v_pk_mul_f32 v[250:251], v[18:19], v[236:237] op_sel:[1,1] op_sel_hi:[0,1]
	v_pk_fma_f32 v[18:19], v[18:19], v[236:237], v[250:251] op_sel:[0,0,0] op_sel_hi:[1,0,1] neg_hi:[0,0,1]
	v_pk_mul_f32 v[250:251], v[22:23], v[240:241] op_sel:[1,1] op_sel_hi:[0,1]
	v_pk_fma_f32 v[22:23], v[22:23], v[240:241], v[250:251] op_sel:[0,0,0] op_sel_hi:[1,0,1] neg_hi:[0,0,1]
	v_pk_add_f32 v[242:243], v[16:17], v[20:21]
	v_pk_add_f32 v[244:245], v[16:17], v[20:21] neg_lo:[0,1] neg_hi:[0,1]
	v_pk_add_f32 v[246:247], v[18:19], v[22:23]
	v_pk_add_f32 v[248:249], v[18:19], v[22:23] neg_lo:[0,1] neg_hi:[0,1]
	v_pk_add_f32 v[16:17], v[242:243], v[246:247]
	v_pk_add_f32 v[18:19], v[244:245], v[248:249] op_sel:[0,1] op_sel_hi:[1,0] neg_lo:[0,1]
	v_pk_add_f32 v[20:21], v[242:243], v[246:247] neg_lo:[0,1] neg_hi:[0,1]
	v_pk_add_f32 v[22:23], v[244:245], v[248:249] op_sel:[0,1] op_sel_hi:[1,0] neg_hi:[0,1]
	s_waitcnt lgkmcnt(0)
	v_pk_mul_f32 v[250:251], v[28:29], v[238:239] op_sel:[1,1] op_sel_hi:[0,1]
	v_pk_fma_f32 v[28:29], v[28:29], v[238:239], v[250:251] op_sel:[0,0,0] op_sel_hi:[1,0,1] neg_hi:[0,0,1]
	v_pk_mul_f32 v[250:251], v[26:27], v[236:237] op_sel:[1,1] op_sel_hi:[0,1]
	v_pk_fma_f32 v[26:27], v[26:27], v[236:237], v[250:251] op_sel:[0,0,0] op_sel_hi:[1,0,1] neg_hi:[0,0,1]
	v_pk_mul_f32 v[250:251], v[30:31], v[240:241] op_sel:[1,1] op_sel_hi:[0,1]
	v_pk_fma_f32 v[30:31], v[30:31], v[240:241], v[250:251] op_sel:[0,0,0] op_sel_hi:[1,0,1] neg_hi:[0,0,1]
	v_pk_add_f32 v[242:243], v[24:25], v[28:29]
	v_pk_add_f32 v[244:245], v[24:25], v[28:29] neg_lo:[0,1] neg_hi:[0,1]
	v_pk_add_f32 v[246:247], v[26:27], v[30:31]
	v_pk_add_f32 v[248:249], v[26:27], v[30:31] neg_lo:[0,1] neg_hi:[0,1]
	v_pk_add_f32 v[24:25], v[242:243], v[246:247]
	v_pk_add_f32 v[26:27], v[244:245], v[248:249] op_sel:[0,1] op_sel_hi:[1,0] neg_lo:[0,1]
	v_pk_add_f32 v[28:29], v[242:243], v[246:247] neg_lo:[0,1] neg_hi:[0,1]
	v_pk_add_f32 v[30:31], v[244:245], v[248:249] op_sel:[0,1] op_sel_hi:[1,0] neg_hi:[0,1]
	v_pk_mul_f32 v[250:251], v[16:17], v[82:83] op_sel:[1,1] op_sel_hi:[0,1]
	v_pk_fma_f32 v[16:17], v[16:17], v[82:83], v[250:251] op_sel:[0,0,0] op_sel_hi:[1,0,1] neg_hi:[0,0,1]
	v_pk_mul_f32 v[250:251], v[8:9], v[80:81] op_sel:[1,1] op_sel_hi:[0,1]
	v_pk_fma_f32 v[8:9], v[8:9], v[80:81], v[250:251] op_sel:[0,0,0] op_sel_hi:[1,0,1] neg_hi:[0,0,1]
	v_pk_mul_f32 v[250:251], v[24:25], v[84:85] op_sel:[1,1] op_sel_hi:[0,1]
	v_pk_fma_f32 v[24:25], v[24:25], v[84:85], v[250:251] op_sel:[0,0,0] op_sel_hi:[1,0,1] neg_hi:[0,0,1]
	v_pk_add_f32 v[242:243], v[0:1], v[16:17]
	v_pk_add_f32 v[244:245], v[0:1], v[16:17] neg_lo:[0,1] neg_hi:[0,1]
	v_pk_add_f32 v[246:247], v[8:9], v[24:25]
	v_pk_add_f32 v[248:249], v[8:9], v[24:25] neg_lo:[0,1] neg_hi:[0,1]
	v_pk_add_f32 v[0:1], v[242:243], v[246:247]
	ds_write_b64 v226, v[0:1] offset:0
	v_pk_add_f32 v[8:9], v[244:245], v[248:249] op_sel:[0,1] op_sel_hi:[1,0] neg_lo:[0,1]
	ds_write_b64 v226, v[8:9] offset:512
	v_pk_add_f32 v[16:17], v[242:243], v[246:247] neg_lo:[0,1] neg_hi:[0,1]
	ds_write_b64 v226, v[16:17] offset:1024
	v_pk_add_f32 v[24:25], v[244:245], v[248:249] op_sel:[0,1] op_sel_hi:[1,0] neg_hi:[0,1]
	ds_write_b64 v226, v[24:25] offset:1536
	v_pk_mul_f32 v[250:251], v[18:19], v[224:225] op_sel:[1,1] op_sel_hi:[1,0] neg_lo:[0,0] neg_hi:[0,0]
; HD float2 cmul(float2 a, float2 b){ return make_float2(a.x*b.x - a.y*b.y, a.x*b.y + a.y*b.x); }
; HD float2 cmulc(float2 a, float2 b){ return make_float2(a.x*b.x + a.y*b.y, a.y*b.x - a.x*b.y); }
; template<bool INV, bool NOTW>
; HD void bf4c(float2* Z, int i0, int i1, int i2, int i3, float2 w1, float2 w2, float2 w3){
;   float2 a0=Z[i0], a1=Z[i1], a2=Z[i2], a3=Z[i3];
;   if (INV && !NOTW){ a1=cmulc(a1,w1); a2=cmulc(a2,w2); a3=cmulc(a3,w3); }
;   float2 s02=make_float2(a0.x+a2.x,a0.y+a2.y), d02=make_float2(a0.x-a2.x,a0.y-a2.y);
;   float2 s13=make_float2(a1.x+a3.x,a1.y+a3.y), d13=make_float2(a1.x-a3.x,a1.y-a3.y);
;   float2 y0=make_float2(s02.x+s13.x,s02.y+s13.y), y2=make_float2(s02.x-s13.x,s02.y-s13.y);
;   float2 ym=make_float2(d02.x+d13.y,d02.y-d13.x);
;   float2 yp=make_float2(d02.x-d13.y,d02.y+d13.x);
;   float2 y1, y3;
;   if (INV){ y1=yp; y3=ym; } else if (NOTW){ y1=ym; y3=yp; } else { y1=cmul(ym,w1); y2=cmul(y2,w2); y3=cmul(yp,w3); }
;   Z[i0]=y0; Z[i1]=y1; Z[i2]=y2; Z[i3]=y3;
; }
; template<bool INV, int LQ, bool BARRIER=true>
; HD void fft_pass(float2* Z, const float2* twA, const float2* twB, int tid){
;     ...
;   } else {
;     int j=tid&(q-1); int base0=((tid>>LQ)<<(LQ+2))+j;
;     float2 w1=make_float2(1.f,0.f), w2=w1, w3=w1;
;     if (LQ>0){ int k=j*tws; w1=cmul(twA[k>>6],twB[k&63]); w2=cmul(w1,w1); w3=cmul(w2,w1); }
;     _Pragma("unroll") for (int i=0;i<8;++i){ int base=base0+i*2048; bf4c<INV,(LQ==0)>(Z,base,base+q,base+2*q,base+3*q,w1,w2,w3); }
;   }
;   if (BARRIER) __syncthreads(); else asm volatile("s_waitcnt lgkmcnt(0)" ::: "memory");
	v_pk_fma_f32 v[18:19], v[18:19], v[224:225], v[250:251] op_sel:[0,0,0] op_sel_hi:[0,1,1] neg_lo:[0,0,1] neg_hi:[0,0,0]
	v_pk_mul_f32 v[250:251], v[18:19], v[82:83] op_sel:[1,1] op_sel_hi:[0,1]
	v_pk_fma_f32 v[18:19], v[18:19], v[82:83], v[250:251] op_sel:[0,0,0] op_sel_hi:[1,0,1] neg_hi:[0,0,1]
	v_pk_mul_f32 v[250:251], v[10:11], v[222:223] op_sel:[1,1] op_sel_hi:[1,0] neg_lo:[0,0] neg_hi:[0,0]
	v_pk_fma_f32 v[10:11], v[10:11], v[222:223], v[250:251] op_sel:[0,0,0] op_sel_hi:[0,1,1] neg_lo:[0,0,1] neg_hi:[0,0,0]
	v_pk_mul_f32 v[250:251], v[10:11], v[80:81] op_sel:[1,1] op_sel_hi:[0,1]
	v_pk_fma_f32 v[10:11], v[10:11], v[80:81], v[250:251] op_sel:[0,0,0] op_sel_hi:[1,0,1] neg_hi:[0,0,1]
	v_pk_mul_f32 v[250:251], v[26:27], v[222:223] op_sel:[1,0] op_sel_hi:[1,1] neg_lo:[0,0] neg_hi:[0,0]
	v_pk_fma_f32 v[26:27], v[26:27], v[222:223], v[250:251] op_sel:[0,1,0] op_sel_hi:[0,0,1] neg_lo:[0,0,1] neg_hi:[0,0,0]
	v_pk_mul_f32 v[250:251], v[26:27], v[84:85] op_sel:[1,1] op_sel_hi:[0,1]
	v_pk_fma_f32 v[26:27], v[26:27], v[84:85], v[250:251] op_sel:[0,0,0] op_sel_hi:[1,0,1] neg_hi:[0,0,1]
	v_pk_add_f32 v[242:243], v[2:3], v[18:19]
	v_pk_add_f32 v[244:245], v[2:3], v[18:19] neg_lo:[0,1] neg_hi:[0,1]
	v_pk_add_f32 v[246:247], v[10:11], v[26:27]
	v_pk_add_f32 v[248:249], v[10:11], v[26:27] neg_lo:[0,1] neg_hi:[0,1]
	v_pk_add_f32 v[2:3], v[242:243], v[246:247]
	ds_write_b64 v226, v[2:3] offset:128
	v_pk_add_f32 v[10:11], v[244:245], v[248:249] op_sel:[0,1] op_sel_hi:[1,0] neg_lo:[0,1]
	ds_write_b64 v226, v[10:11] offset:640
	v_pk_add_f32 v[18:19], v[242:243], v[246:247] neg_lo:[0,1] neg_hi:[0,1]
	ds_write_b64 v226, v[18:19] offset:1152
	v_pk_add_f32 v[26:27], v[244:245], v[248:249] op_sel:[0,1] op_sel_hi:[1,0] neg_hi:[0,1]
	ds_write_b64 v226, v[26:27] offset:1664
	v_pk_add_f32 v[20:21], v[20:21], 0 op_sel:[1,0] op_sel_hi:[0,0] neg_lo:[1,0]
	v_pk_mul_f32 v[250:251], v[20:21], v[82:83] op_sel:[1,1] op_sel_hi:[0,1]
	v_pk_fma_f32 v[20:21], v[20:21], v[82:83], v[250:251] op_sel:[0,0,0] op_sel_hi:[1,0,1] neg_hi:[0,0,1]
	v_pk_mul_f32 v[250:251], v[12:13], v[224:225] op_sel:[1,1] op_sel_hi:[1,0] neg_lo:[0,0] neg_hi:[0,0]
	v_pk_fma_f32 v[12:13], v[12:13], v[224:225], v[250:251] op_sel:[0,0,0] op_sel_hi:[0,1,1] neg_lo:[0,0,1] neg_hi:[0,0,0]
	v_pk_mul_f32 v[250:251], v[12:13], v[80:81] op_sel:[1,1] op_sel_hi:[0,1]
	v_pk_fma_f32 v[12:13], v[12:13], v[80:81], v[250:251] op_sel:[0,0,0] op_sel_hi:[1,0,1] neg_hi:[0,0,1]
	v_pk_mul_f32 v[250:251], v[28:29], v[224:225] op_sel:[1,1] op_sel_hi:[1,0] neg_lo:[0,0] neg_hi:[0,1]
	v_pk_fma_f32 v[28:29], v[28:29], v[224:225], v[250:251] op_sel:[0,0,0] op_sel_hi:[0,1,1] neg_lo:[0,1,1] neg_hi:[0,0,0]
	v_pk_mul_f32 v[250:251], v[28:29], v[84:85] op_sel:[1,1] op_sel_hi:[0,1]
	v_pk_fma_f32 v[28:29], v[28:29], v[84:85], v[250:251] op_sel:[0,0,0] op_sel_hi:[1,0,1] neg_hi:[0,0,1]
	v_pk_add_f32 v[242:243], v[4:5], v[20:21]
	v_pk_add_f32 v[244:245], v[4:5], v[20:21] neg_lo:[0,1] neg_hi:[0,1]
	v_pk_add_f32 v[246:247], v[12:13], v[28:29]
	v_pk_add_f32 v[248:249], v[12:13], v[28:29] neg_lo:[0,1] neg_hi:[0,1]
	v_pk_add_f32 v[4:5], v[242:243], v[246:247]
	ds_write_b64 v226, v[4:5] offset:256
	v_pk_add_f32 v[12:13], v[244:245], v[248:249] op_sel:[0,1] op_sel_hi:[1,0] neg_lo:[0,1]
	ds_write_b64 v226, v[12:13] offset:768
	v_pk_add_f32 v[20:21], v[242:243], v[246:247] neg_lo:[0,1] neg_hi:[0,1]
	ds_write_b64 v226, v[20:21] offset:1280
	v_pk_add_f32 v[28:29], v[244:245], v[248:249] op_sel:[0,1] op_sel_hi:[1,0] neg_hi:[0,1]
	ds_write_b64 v226, v[28:29] offset:1792
	v_pk_mul_f32 v[250:251], v[22:23], v[224:225] op_sel:[1,1] op_sel_hi:[1,0] neg_lo:[0,0] neg_hi:[0,1]
	v_pk_fma_f32 v[22:23], v[22:23], v[224:225], v[250:251] op_sel:[0,0,0] op_sel_hi:[0,1,1] neg_lo:[0,1,1] neg_hi:[0,0,0]
	v_pk_mul_f32 v[250:251], v[22:23], v[82:83] op_sel:[1,1] op_sel_hi:[0,1]
	v_pk_fma_f32 v[22:23], v[22:23], v[82:83], v[250:251] op_sel:[0,0,0] op_sel_hi:[1,0,1] neg_hi:[0,0,1]
	v_pk_mul_f32 v[250:251], v[14:15], v[222:223] op_sel:[1,0] op_sel_hi:[1,1] neg_lo:[0,0] neg_hi:[0,0]
	v_pk_fma_f32 v[14:15], v[14:15], v[222:223], v[250:251] op_sel:[0,1,0] op_sel_hi:[0,0,1] neg_lo:[0,0,1] neg_hi:[0,0,0]
	v_pk_mul_f32 v[250:251], v[14:15], v[80:81] op_sel:[1,1] op_sel_hi:[0,1]
	v_pk_fma_f32 v[14:15], v[14:15], v[80:81], v[250:251] op_sel:[0,0,0] op_sel_hi:[1,0,1] neg_hi:[0,0,1]
	v_pk_mul_f32 v[250:251], v[30:31], v[222:223] op_sel:[1,1] op_sel_hi:[1,0] neg_lo:[0,1] neg_hi:[0,1]
	v_pk_fma_f32 v[30:31], v[30:31], v[222:223], v[250:251] op_sel:[0,0,0] op_sel_hi:[0,1,1] neg_lo:[0,1,1] neg_hi:[0,1,0]
	v_pk_mul_f32 v[250:251], v[30:31], v[84:85] op_sel:[1,1] op_sel_hi:[0,1]
	v_pk_fma_f32 v[30:31], v[30:31], v[84:85], v[250:251] op_sel:[0,0,0] op_sel_hi:[1,0,1] neg_hi:[0,0,1]
	v_pk_add_f32 v[242:243], v[6:7], v[22:23]
	v_pk_add_f32 v[244:245], v[6:7], v[22:23] neg_lo:[0,1] neg_hi:[0,1]
	v_pk_add_f32 v[246:247], v[14:15], v[30:31]
	v_pk_add_f32 v[248:249], v[14:15], v[30:31] neg_lo:[0,1] neg_hi:[0,1]
	v_pk_add_f32 v[6:7], v[242:243], v[246:247]
	ds_write_b64 v226, v[6:7] offset:384
	v_pk_add_f32 v[14:15], v[244:245], v[248:249] op_sel:[0,1] op_sel_hi:[1,0] neg_lo:[0,1]
	ds_write_b64 v226, v[14:15] offset:896
	v_pk_add_f32 v[22:23], v[242:243], v[246:247] neg_lo:[0,1] neg_hi:[0,1]
	ds_write_b64 v226, v[22:23] offset:1408
	v_pk_add_f32 v[30:31], v[244:245], v[248:249] op_sel:[0,1] op_sel_hi:[1,0] neg_hi:[0,1]
	ds_write_b64 v226, v[30:31] offset:1920
	ds_read_b64 v[0:1], v227 offset:0
	ds_read_b64 v[2:3], v227 offset:128
	ds_read_b64 v[4:5], v227 offset:256
	ds_read_b64 v[6:7], v227 offset:384
	ds_read_b64 v[8:9], v227 offset:512
	ds_read_b64 v[10:11], v227 offset:640
	ds_read_b64 v[12:13], v227 offset:768
	ds_read_b64 v[14:15], v227 offset:896
	ds_read_b64 v[16:17], v227 offset:1024
	ds_read_b64 v[18:19], v227 offset:1152
	ds_read_b64 v[20:21], v227 offset:1280
	ds_read_b64 v[22:23], v227 offset:1408
	ds_read_b64 v[24:25], v227 offset:1536
	ds_read_b64 v[26:27], v227 offset:1664
	ds_read_b64 v[28:29], v227 offset:1792
	ds_read_b64 v[30:31], v227 offset:1920
	s_waitcnt lgkmcnt(12)
; HD float2 cmul(float2 a, float2 b){ return make_float2(a.x*b.x - a.y*b.y, a.x*b.y + a.y*b.x); }
; HD float2 cmulc(float2 a, float2 b){ return make_float2(a.x*b.x + a.y*b.y, a.y*b.x - a.x*b.y); }
; template<bool INV, bool NOTW>
; HD void bf4c(float2* Z, int i0, int i1, int i2, int i3, float2 w1, float2 w2, float2 w3){
;   float2 a0=Z[i0], a1=Z[i1], a2=Z[i2], a3=Z[i3];
;   if (INV && !NOTW){ a1=cmulc(a1,w1); a2=cmulc(a2,w2); a3=cmulc(a3,w3); }
;   float2 s02=make_float2(a0.x+a2.x,a0.y+a2.y), d02=make_float2(a0.x-a2.x,a0.y-a2.y);
;   float2 s13=make_float2(a1.x+a3.x,a1.y+a3.y), d13=make_float2(a1.x-a3.x,a1.y-a3.y);
;   float2 y0=make_float2(s02.x+s13.x,s02.y+s13.y), y2=make_float2(s02.x-s13.x,s02.y-s13.y);
;   float2 ym=make_float2(d02.x+d13.y,d02.y-d13.x);
;   float2 yp=make_float2(d02.x-d13.y,d02.y+d13.x);
;   float2 y1, y3;
;   if (INV){ y1=yp; y3=ym; } else if (NOTW){ y1=ym; y3=yp; } else { y1=cmul(ym,w1); y2=cmul(y2,w2); y3=cmul(yp,w3); }
;   Z[i0]=y0; Z[i1]=y1; Z[i2]=y2; Z[i3]=y3;
; }
; template<bool INV, int LQ, bool BARRIER=true>
; HD void fft_pass(float2* Z, const float2* twA, const float2* twB, int tid){
;     ...
;   } else {
;     int j=tid&(q-1); int base0=((tid>>LQ)<<(LQ+2))+j;
;     float2 w1=make_float2(1.f,0.f), w2=w1, w3=w1;
;     if (LQ>0){ int k=j*tws; w1=cmul(twA[k>>6],twB[k&63]); w2=cmul(w1,w1); w3=cmul(w2,w1); }
;     _Pragma("unroll") for (int i=0;i<8;++i){ int base=base0+i*2048; bf4c<INV,(LQ==0)>(Z,base,base+q,base+2*q,base+3*q,w1,w2,w3); }
;   }
;   if (BARRIER) __syncthreads(); else asm volatile("s_waitcnt lgkmcnt(0)" ::: "memory");
	v_pk_mul_f32 v[250:251], v[4:5], v[238:239] op_sel:[1,1] op_sel_hi:[0,1]
	v_pk_fma_f32 v[4:5], v[4:5], v[238:239], v[250:251] op_sel:[0,0,0] op_sel_hi:[1,0,1] neg_hi:[0,0,1]
	v_pk_mul_f32 v[250:251], v[2:3], v[236:237] op_sel:[1,1] op_sel_hi:[0,1]
	v_pk_fma_f32 v[2:3], v[2:3], v[236:237], v[250:251] op_sel:[0,0,0] op_sel_hi:[1,0,1] neg_hi:[0,0,1]
	v_pk_mul_f32 v[250:251], v[6:7], v[240:241] op_sel:[1,1] op_sel_hi:[0,1]
	v_pk_fma_f32 v[6:7], v[6:7], v[240:241], v[250:251] op_sel:[0,0,0] op_sel_hi:[1,0,1] neg_hi:[0,0,1]
	v_pk_add_f32 v[242:243], v[0:1], v[4:5]
	v_pk_add_f32 v[244:245], v[0:1], v[4:5] neg_lo:[0,1] neg_hi:[0,1]
	v_pk_add_f32 v[246:247], v[2:3], v[6:7]
	v_pk_add_f32 v[248:249], v[2:3], v[6:7] neg_lo:[0,1] neg_hi:[0,1]
	v_pk_add_f32 v[0:1], v[242:243], v[246:247]
	v_pk_add_f32 v[2:3], v[244:245], v[248:249] op_sel:[0,1] op_sel_hi:[1,0] neg_lo:[0,1]
	v_pk_add_f32 v[4:5], v[242:243], v[246:247] neg_lo:[0,1] neg_hi:[0,1]
	v_pk_add_f32 v[6:7], v[244:245], v[248:249] op_sel:[0,1] op_sel_hi:[1,0] neg_hi:[0,1]
	s_waitcnt lgkmcnt(8)
	v_pk_mul_f32 v[250:251], v[12:13], v[238:239] op_sel:[1,1] op_sel_hi:[0,1]
	v_pk_fma_f32 v[12:13], v[12:13], v[238:239], v[250:251] op_sel:[0,0,0] op_sel_hi:[1,0,1] neg_hi:[0,0,1]
	v_pk_mul_f32 v[250:251], v[10:11], v[236:237] op_sel:[1,1] op_sel_hi:[0,1]
	v_pk_fma_f32 v[10:11], v[10:11], v[236:237], v[250:251] op_sel:[0,0,0] op_sel_hi:[1,0,1] neg_hi:[0,0,1]
	v_pk_mul_f32 v[250:251], v[14:15], v[240:241] op_sel:[1,1] op_sel_hi:[0,1]
	v_pk_fma_f32 v[14:15], v[14:15], v[240:241], v[250:251] op_sel:[0,0,0] op_sel_hi:[1,0,1] neg_hi:[0,0,1]
	v_pk_add_f32 v[242:243], v[8:9], v[12:13]
	v_pk_add_f32 v[244:245], v[8:9], v[12:13] neg_lo:[0,1] neg_hi:[0,1]
	v_pk_add_f32 v[246:247], v[10:11], v[14:15]
	v_pk_add_f32 v[248:249], v[10:11], v[14:15] neg_lo:[0,1] neg_hi:[0,1]
	v_pk_add_f32 v[8:9], v[242:243], v[246:247]
	v_pk_add_f32 v[10:11], v[244:245], v[248:249] op_sel:[0,1] op_sel_hi:[1,0] neg_lo:[0,1]
	v_pk_add_f32 v[12:13], v[242:243], v[246:247] neg_lo:[0,1] neg_hi:[0,1]
	v_pk_add_f32 v[14:15], v[244:245], v[248:249] op_sel:[0,1] op_sel_hi:[1,0] neg_hi:[0,1]
	s_waitcnt lgkmcnt(4)
	v_pk_mul_f32 v[250:251], v[20:21], v[238:239] op_sel:[1,1] op_sel_hi:[0,1]
	v_pk_fma_f32 v[20:21], v[20:21], v[238:239], v[250:251] op_sel:[0,0,0] op_sel_hi:[1,0,1] neg_hi:[0,0,1]
	v_pk_mul_f32 v[250:251], v[18:19], v[236:237] op_sel:[1,1] op_sel_hi:[0,1]
	v_pk_fma_f32 v[18:19], v[18:19], v[236:237], v[250:251] op_sel:[0,0,0] op_sel_hi:[1,0,1] neg_hi:[0,0,1]
	v_pk_mul_f32 v[250:251], v[22:23], v[240:241] op_sel:[1,1] op_sel_hi:[0,1]
	v_pk_fma_f32 v[22:23], v[22:23], v[240:241], v[250:251] op_sel:[0,0,0] op_sel_hi:[1,0,1] neg_hi:[0,0,1]
	v_pk_add_f32 v[242:243], v[16:17], v[20:21]
	v_pk_add_f32 v[244:245], v[16:17], v[20:21] neg_lo:[0,1] neg_hi:[0,1]
	v_pk_add_f32 v[246:247], v[18:19], v[22:23]
	v_pk_add_f32 v[248:249], v[18:19], v[22:23] neg_lo:[0,1] neg_hi:[0,1]
	v_pk_add_f32 v[16:17], v[242:243], v[246:247]
	v_pk_add_f32 v[18:19], v[244:245], v[248:249] op_sel:[0,1] op_sel_hi:[1,0] neg_lo:[0,1]
	v_pk_add_f32 v[20:21], v[242:243], v[246:247] neg_lo:[0,1] neg_hi:[0,1]
	v_pk_add_f32 v[22:23], v[244:245], v[248:249] op_sel:[0,1] op_sel_hi:[1,0] neg_hi:[0,1]
	s_waitcnt lgkmcnt(0)
	v_pk_mul_f32 v[250:251], v[28:29], v[238:239] op_sel:[1,1] op_sel_hi:[0,1]
	v_pk_fma_f32 v[28:29], v[28:29], v[238:239], v[250:251] op_sel:[0,0,0] op_sel_hi:[1,0,1] neg_hi:[0,0,1]
	v_pk_mul_f32 v[250:251], v[26:27], v[236:237] op_sel:[1,1] op_sel_hi:[0,1]
	v_pk_fma_f32 v[26:27], v[26:27], v[236:237], v[250:251] op_sel:[0,0,0] op_sel_hi:[1,0,1] neg_hi:[0,0,1]
	v_pk_mul_f32 v[250:251], v[30:31], v[240:241] op_sel:[1,1] op_sel_hi:[0,1]
	v_pk_fma_f32 v[30:31], v[30:31], v[240:241], v[250:251] op_sel:[0,0,0] op_sel_hi:[1,0,1] neg_hi:[0,0,1]
	v_pk_add_f32 v[242:243], v[24:25], v[28:29]
	v_pk_add_f32 v[244:245], v[24:25], v[28:29] neg_lo:[0,1] neg_hi:[0,1]
	v_pk_add_f32 v[246:247], v[26:27], v[30:31]
	v_pk_add_f32 v[248:249], v[26:27], v[30:31] neg_lo:[0,1] neg_hi:[0,1]
	v_pk_add_f32 v[24:25], v[242:243], v[246:247]
	v_pk_add_f32 v[26:27], v[244:245], v[248:249] op_sel:[0,1] op_sel_hi:[1,0] neg_lo:[0,1]
	v_pk_add_f32 v[28:29], v[242:243], v[246:247] neg_lo:[0,1] neg_hi:[0,1]
	v_pk_add_f32 v[30:31], v[244:245], v[248:249] op_sel:[0,1] op_sel_hi:[1,0] neg_hi:[0,1]
	v_pk_mul_f32 v[250:251], v[16:17], v[82:83] op_sel:[1,1] op_sel_hi:[0,1]
	v_pk_fma_f32 v[16:17], v[16:17], v[82:83], v[250:251] op_sel:[0,0,0] op_sel_hi:[1,0,1] neg_hi:[0,0,1]
	v_pk_mul_f32 v[250:251], v[8:9], v[80:81] op_sel:[1,1] op_sel_hi:[0,1]
	v_pk_fma_f32 v[8:9], v[8:9], v[80:81], v[250:251] op_sel:[0,0,0] op_sel_hi:[1,0,1] neg_hi:[0,0,1]
	v_pk_mul_f32 v[250:251], v[24:25], v[84:85] op_sel:[1,1] op_sel_hi:[0,1]
	v_pk_fma_f32 v[24:25], v[24:25], v[84:85], v[250:251] op_sel:[0,0,0] op_sel_hi:[1,0,1] neg_hi:[0,0,1]
	v_pk_add_f32 v[242:243], v[0:1], v[16:17]
	v_pk_add_f32 v[244:245], v[0:1], v[16:17] neg_lo:[0,1] neg_hi:[0,1]
	v_pk_add_f32 v[246:247], v[8:9], v[24:25]
	v_pk_add_f32 v[248:249], v[8:9], v[24:25] neg_lo:[0,1] neg_hi:[0,1]
	v_pk_add_f32 v[0:1], v[242:243], v[246:247]
	ds_write_b64 v227, v[0:1] offset:0
	v_pk_add_f32 v[8:9], v[244:245], v[248:249] op_sel:[0,1] op_sel_hi:[1,0] neg_lo:[0,1]
	ds_write_b64 v227, v[8:9] offset:512
	v_pk_add_f32 v[16:17], v[242:243], v[246:247] neg_lo:[0,1] neg_hi:[0,1]
	ds_write_b64 v227, v[16:17] offset:1024
	v_pk_add_f32 v[24:25], v[244:245], v[248:249] op_sel:[0,1] op_sel_hi:[1,0] neg_hi:[0,1]
	ds_write_b64 v227, v[24:25] offset:1536
	v_pk_mul_f32 v[250:251], v[18:19], v[224:225] op_sel:[1,1] op_sel_hi:[1,0] neg_lo:[0,0] neg_hi:[0,0]
; HD float2 cmul(float2 a, float2 b){ return make_float2(a.x*b.x - a.y*b.y, a.x*b.y + a.y*b.x); }
; HD float2 cmulc(float2 a, float2 b){ return make_float2(a.x*b.x + a.y*b.y, a.y*b.x - a.x*b.y); }
; template<bool INV, bool NOTW>
; HD void bf4c(float2* Z, int i0, int i1, int i2, int i3, float2 w1, float2 w2, float2 w3){
;   float2 a0=Z[i0], a1=Z[i1], a2=Z[i2], a3=Z[i3];
;   if (INV && !NOTW){ a1=cmulc(a1,w1); a2=cmulc(a2,w2); a3=cmulc(a3,w3); }
;   float2 s02=make_float2(a0.x+a2.x,a0.y+a2.y), d02=make_float2(a0.x-a2.x,a0.y-a2.y);
;   float2 s13=make_float2(a1.x+a3.x,a1.y+a3.y), d13=make_float2(a1.x-a3.x,a1.y-a3.y);
;   float2 y0=make_float2(s02.x+s13.x,s02.y+s13.y), y2=make_float2(s02.x-s13.x,s02.y-s13.y);
;   float2 ym=make_float2(d02.x+d13.y,d02.y-d13.x);
;   float2 yp=make_float2(d02.x-d13.y,d02.y+d13.x);
;   float2 y1, y3;
;   if (INV){ y1=yp; y3=ym; } else if (NOTW){ y1=ym; y3=yp; } else { y1=cmul(ym,w1); y2=cmul(y2,w2); y3=cmul(yp,w3); }
;   Z[i0]=y0; Z[i1]=y1; Z[i2]=y2; Z[i3]=y3;
; }
; template<bool INV, int LQ, bool BARRIER=true>
; HD void fft_pass(float2* Z, const float2* twA, const float2* twB, int tid){
;     ...
;   } else {
;     int j=tid&(q-1); int base0=((tid>>LQ)<<(LQ+2))+j;
;     float2 w1=make_float2(1.f,0.f), w2=w1, w3=w1;
;     if (LQ>0){ int k=j*tws; w1=cmul(twA[k>>6],twB[k&63]); w2=cmul(w1,w1); w3=cmul(w2,w1); }
;     _Pragma("unroll") for (int i=0;i<8;++i){ int base=base0+i*2048; bf4c<INV,(LQ==0)>(Z,base,base+q,base+2*q,base+3*q,w1,w2,w3); }
;   }
;   if (BARRIER) __syncthreads(); else asm volatile("s_waitcnt lgkmcnt(0)" ::: "memory");
	v_pk_fma_f32 v[18:19], v[18:19], v[224:225], v[250:251] op_sel:[0,0,0] op_sel_hi:[0,1,1] neg_lo:[0,0,1] neg_hi:[0,0,0]
	v_pk_mul_f32 v[250:251], v[18:19], v[82:83] op_sel:[1,1] op_sel_hi:[0,1]
	v_pk_fma_f32 v[18:19], v[18:19], v[82:83], v[250:251] op_sel:[0,0,0] op_sel_hi:[1,0,1] neg_hi:[0,0,1]
	v_pk_mul_f32 v[250:251], v[10:11], v[222:223] op_sel:[1,1] op_sel_hi:[1,0] neg_lo:[0,0] neg_hi:[0,0]
	v_pk_fma_f32 v[10:11], v[10:11], v[222:223], v[250:251] op_sel:[0,0,0] op_sel_hi:[0,1,1] neg_lo:[0,0,1] neg_hi:[0,0,0]
	v_pk_mul_f32 v[250:251], v[10:11], v[80:81] op_sel:[1,1] op_sel_hi:[0,1]
	v_pk_fma_f32 v[10:11], v[10:11], v[80:81], v[250:251] op_sel:[0,0,0] op_sel_hi:[1,0,1] neg_hi:[0,0,1]
	v_pk_mul_f32 v[250:251], v[26:27], v[222:223] op_sel:[1,0] op_sel_hi:[1,1] neg_lo:[0,0] neg_hi:[0,0]
	v_pk_fma_f32 v[26:27], v[26:27], v[222:223], v[250:251] op_sel:[0,1,0] op_sel_hi:[0,0,1] neg_lo:[0,0,1] neg_hi:[0,0,0]
	v_pk_mul_f32 v[250:251], v[26:27], v[84:85] op_sel:[1,1] op_sel_hi:[0,1]
	v_pk_fma_f32 v[26:27], v[26:27], v[84:85], v[250:251] op_sel:[0,0,0] op_sel_hi:[1,0,1] neg_hi:[0,0,1]
	v_pk_add_f32 v[242:243], v[2:3], v[18:19]
	v_pk_add_f32 v[244:245], v[2:3], v[18:19] neg_lo:[0,1] neg_hi:[0,1]
	v_pk_add_f32 v[246:247], v[10:11], v[26:27]
	v_pk_add_f32 v[248:249], v[10:11], v[26:27] neg_lo:[0,1] neg_hi:[0,1]
	v_pk_add_f32 v[2:3], v[242:243], v[246:247]
	ds_write_b64 v227, v[2:3] offset:128
	v_pk_add_f32 v[10:11], v[244:245], v[248:249] op_sel:[0,1] op_sel_hi:[1,0] neg_lo:[0,1]
	ds_write_b64 v227, v[10:11] offset:640
	v_pk_add_f32 v[18:19], v[242:243], v[246:247] neg_lo:[0,1] neg_hi:[0,1]
	ds_write_b64 v227, v[18:19] offset:1152
	v_pk_add_f32 v[26:27], v[244:245], v[248:249] op_sel:[0,1] op_sel_hi:[1,0] neg_hi:[0,1]
	ds_write_b64 v227, v[26:27] offset:1664
	v_pk_add_f32 v[20:21], v[20:21], 0 op_sel:[1,0] op_sel_hi:[0,0] neg_lo:[1,0]
	v_pk_mul_f32 v[250:251], v[20:21], v[82:83] op_sel:[1,1] op_sel_hi:[0,1]
	v_pk_fma_f32 v[20:21], v[20:21], v[82:83], v[250:251] op_sel:[0,0,0] op_sel_hi:[1,0,1] neg_hi:[0,0,1]
	v_pk_mul_f32 v[250:251], v[12:13], v[224:225] op_sel:[1,1] op_sel_hi:[1,0] neg_lo:[0,0] neg_hi:[0,0]
	v_pk_fma_f32 v[12:13], v[12:13], v[224:225], v[250:251] op_sel:[0,0,0] op_sel_hi:[0,1,1] neg_lo:[0,0,1] neg_hi:[0,0,0]
	v_pk_mul_f32 v[250:251], v[12:13], v[80:81] op_sel:[1,1] op_sel_hi:[0,1]
	v_pk_fma_f32 v[12:13], v[12:13], v[80:81], v[250:251] op_sel:[0,0,0] op_sel_hi:[1,0,1] neg_hi:[0,0,1]
	v_pk_mul_f32 v[250:251], v[28:29], v[224:225] op_sel:[1,1] op_sel_hi:[1,0] neg_lo:[0,0] neg_hi:[0,1]
	v_pk_fma_f32 v[28:29], v[28:29], v[224:225], v[250:251] op_sel:[0,0,0] op_sel_hi:[0,1,1] neg_lo:[0,1,1] neg_hi:[0,0,0]
	v_pk_mul_f32 v[250:251], v[28:29], v[84:85] op_sel:[1,1] op_sel_hi:[0,1]
	v_pk_fma_f32 v[28:29], v[28:29], v[84:85], v[250:251] op_sel:[0,0,0] op_sel_hi:[1,0,1] neg_hi:[0,0,1]
	v_pk_add_f32 v[242:243], v[4:5], v[20:21]
	v_pk_add_f32 v[244:245], v[4:5], v[20:21] neg_lo:[0,1] neg_hi:[0,1]
	v_pk_add_f32 v[246:247], v[12:13], v[28:29]
	v_pk_add_f32 v[248:249], v[12:13], v[28:29] neg_lo:[0,1] neg_hi:[0,1]
	v_pk_add_f32 v[4:5], v[242:243], v[246:247]
	ds_write_b64 v227, v[4:5] offset:256
	v_pk_add_f32 v[12:13], v[244:245], v[248:249] op_sel:[0,1] op_sel_hi:[1,0] neg_lo:[0,1]
	ds_write_b64 v227, v[12:13] offset:768
	v_pk_add_f32 v[20:21], v[242:243], v[246:247] neg_lo:[0,1] neg_hi:[0,1]
	ds_write_b64 v227, v[20:21] offset:1280
	v_pk_add_f32 v[28:29], v[244:245], v[248:249] op_sel:[0,1] op_sel_hi:[1,0] neg_hi:[0,1]
	ds_write_b64 v227, v[28:29] offset:1792
	v_pk_mul_f32 v[250:251], v[22:23], v[224:225] op_sel:[1,1] op_sel_hi:[1,0] neg_lo:[0,0] neg_hi:[0,1]
	v_pk_fma_f32 v[22:23], v[22:23], v[224:225], v[250:251] op_sel:[0,0,0] op_sel_hi:[0,1,1] neg_lo:[0,1,1] neg_hi:[0,0,0]
	v_pk_mul_f32 v[250:251], v[22:23], v[82:83] op_sel:[1,1] op_sel_hi:[0,1]
	v_pk_fma_f32 v[22:23], v[22:23], v[82:83], v[250:251] op_sel:[0,0,0] op_sel_hi:[1,0,1] neg_hi:[0,0,1]
	v_pk_mul_f32 v[250:251], v[14:15], v[222:223] op_sel:[1,0] op_sel_hi:[1,1] neg_lo:[0,0] neg_hi:[0,0]
	v_pk_fma_f32 v[14:15], v[14:15], v[222:223], v[250:251] op_sel:[0,1,0] op_sel_hi:[0,0,1] neg_lo:[0,0,1] neg_hi:[0,0,0]
	v_pk_mul_f32 v[250:251], v[14:15], v[80:81] op_sel:[1,1] op_sel_hi:[0,1]
	v_pk_fma_f32 v[14:15], v[14:15], v[80:81], v[250:251] op_sel:[0,0,0] op_sel_hi:[1,0,1] neg_hi:[0,0,1]
	v_pk_mul_f32 v[250:251], v[30:31], v[222:223] op_sel:[1,1] op_sel_hi:[1,0] neg_lo:[0,1] neg_hi:[0,1]
	v_pk_fma_f32 v[30:31], v[30:31], v[222:223], v[250:251] op_sel:[0,0,0] op_sel_hi:[0,1,1] neg_lo:[0,1,1] neg_hi:[0,1,0]
	v_pk_mul_f32 v[250:251], v[30:31], v[84:85] op_sel:[1,1] op_sel_hi:[0,1]
	v_pk_fma_f32 v[30:31], v[30:31], v[84:85], v[250:251] op_sel:[0,0,0] op_sel_hi:[1,0,1] neg_hi:[0,0,1]
	v_pk_add_f32 v[242:243], v[6:7], v[22:23]
	v_pk_add_f32 v[244:245], v[6:7], v[22:23] neg_lo:[0,1] neg_hi:[0,1]
	v_pk_add_f32 v[246:247], v[14:15], v[30:31]
	v_pk_add_f32 v[248:249], v[14:15], v[30:31] neg_lo:[0,1] neg_hi:[0,1]
	v_pk_add_f32 v[6:7], v[242:243], v[246:247]
	ds_write_b64 v227, v[6:7] offset:384
	v_pk_add_f32 v[14:15], v[244:245], v[248:249] op_sel:[0,1] op_sel_hi:[1,0] neg_lo:[0,1]
	ds_write_b64 v227, v[14:15] offset:896
	v_pk_add_f32 v[22:23], v[242:243], v[246:247] neg_lo:[0,1] neg_hi:[0,1]
	ds_write_b64 v227, v[22:23] offset:1408
	v_pk_add_f32 v[30:31], v[244:245], v[248:249] op_sel:[0,1] op_sel_hi:[1,0] neg_hi:[0,1]
	ds_write_b64 v227, v[30:31] offset:1920
	s_waitcnt lgkmcnt(0)
	s_barrier
; HD float2 cmul(float2 a, float2 b){ return make_float2(a.x*b.x - a.y*b.y, a.x*b.y + a.y*b.x); }
; HD float2 cmulc(float2 a, float2 b){ return make_float2(a.x*b.x + a.y*b.y, a.y*b.x - a.x*b.y); }
; template<bool INV, bool NOTW>
; HD void bf4c(float2* Z, int i0, int i1, int i2, int i3, float2 w1, float2 w2, float2 w3){
;   float2 a0=Z[i0], a1=Z[i1], a2=Z[i2], a3=Z[i3];
;   if (INV && !NOTW){ a1=cmulc(a1,w1); a2=cmulc(a2,w2); a3=cmulc(a3,w3); }
;   float2 s02=make_float2(a0.x+a2.x,a0.y+a2.y), d02=make_float2(a0.x-a2.x,a0.y-a2.y);
;   float2 s13=make_float2(a1.x+a3.x,a1.y+a3.y), d13=make_float2(a1.x-a3.x,a1.y-a3.y);
;   float2 y0=make_float2(s02.x+s13.x,s02.y+s13.y), y2=make_float2(s02.x-s13.x,s02.y-s13.y);
;   float2 ym=make_float2(d02.x+d13.y,d02.y-d13.x);
;   float2 yp=make_float2(d02.x-d13.y,d02.y+d13.x);
;   float2 y1, y3;
;   if (INV){ y1=yp; y3=ym; } else if (NOTW){ y1=ym; y3=yp; } else { y1=cmul(ym,w1); y2=cmul(y2,w2); y3=cmul(yp,w3); }
;   Z[i0]=y0; Z[i1]=y1; Z[i2]=y2; Z[i3]=y3;
; }
; HD int rev4_14(int p){ unsigned r = __brev((unsigned)p) >> 18; return (int)(((r & 0x2AAAu) >> 1) | ((r & 0x1555u) << 1)); }
; template<bool INV, int LQ, bool BARRIER=true>
; HD void fft_pass(float2* Z, const float2* twA, const float2* twB, int tid){
;   constexpr int q=1<<LQ; constexpr int tws=4096>>LQ;
;   if (LQ==12){
;     _Pragma("unroll 2") for (int i=0;i<8;++i){ int t=tid+512*i; int k=t;
;       float2 w1=cmul(twA[k>>6],twB[k&63]), w2=cmul(w1,w1), w3=cmul(w2,w1);
;       bf4c<INV,false>(Z,t,t+q,t+2*q,t+3*q,w1,w2,w3); }
;   } else if (LQ==10){
;     _Pragma("unroll") for (int e=0;e<2;++e){ int j=tid+512*e; int k=j*tws;
;       float2 w1=cmul(twA[k>>6],twB[k&63]), w2=cmul(w1,w1), w3=cmul(w2,w1);
;       _Pragma("unroll") for (int ip=0;ip<4;++ip){ int base=ip*4096+j; bf4c<INV,false>(Z,base,base+q,base+2*q,base+3*q,w1,w2,w3); } }
;   } else {
;     int j=tid&(q-1); int base0=((tid>>LQ)<<(LQ+2))+j;
;     float2 w1=make_float2(1.f,0.f), w2=w1, w3=w1;
;     if (LQ>0){ int k=j*tws; w1=cmul(twA[k>>6],twB[k&63]); w2=cmul(w1,w1); w3=cmul(w2,w1); }
;     _Pragma("unroll") for (int i=0;i<8;++i){ int base=base0+i*2048; bf4c<INV,(LQ==0)>(Z,base,base+q,base+2*q,base+3*q,w1,w2,w3); }
;   }
;   if (BARRIER) __syncthreads(); else asm volatile("s_waitcnt lgkmcnt(0)" ::: "memory");
	v_and_b32_e32 v8, 255, v154
	v_lshrrev_b32_e32 v9, 4, v8
	v_lshlrev_b32_e32 v9, 3, v9
	v_add_u32_e32 v9, 0x20800, v9
	v_and_b32_e32 v10, 15, v8
	v_lshlrev_b32_e32 v10, 5, v10
	v_add_u32_e32 v10, 0x20a00, v10
	ds_read_b64 v[0:1], v9
	ds_read_b64 v[2:3], v10
	s_waitcnt lgkmcnt(0)
	v_pk_mul_f32 v[250:251], v[0:1], v[2:3] op_sel:[1,1] op_sel_hi:[1,0]
	v_pk_fma_f32 v[80:81], v[0:1], v[2:3], v[250:251] op_sel:[0,0,0] op_sel_hi:[0,1,1] neg_lo:[0,0,1]
	v_pk_mul_f32 v[250:251], v[80:81], v[80:81] op_sel:[1,1] op_sel_hi:[1,0]
	v_pk_fma_f32 v[82:83], v[80:81], v[80:81], v[250:251] op_sel:[0,0,0] op_sel_hi:[0,1,1] neg_lo:[0,0,1]
	v_pk_mul_f32 v[250:251], v[82:83], v[80:81] op_sel:[1,1] op_sel_hi:[1,0]
	v_pk_fma_f32 v[84:85], v[82:83], v[80:81], v[250:251] op_sel:[0,0,0] op_sel_hi:[0,1,1] neg_lo:[0,0,1]
	v_lshrrev_b32_e32 v9, 2, v8
	v_lshlrev_b32_e32 v9, 3, v9
	v_add_u32_e32 v9, 0x20800, v9
	v_and_b32_e32 v10, 3, v8
	v_lshlrev_b32_e32 v10, 7, v10
	v_add_u32_e32 v10, 0x20a00, v10
	ds_read_b64 v[0:1], v9
	ds_read_b64 v[2:3], v10
	s_waitcnt lgkmcnt(0)
	v_pk_mul_f32 v[250:251], v[0:1], v[2:3] op_sel:[1,1] op_sel_hi:[1,0]
	v_pk_fma_f32 v[236:237], v[0:1], v[2:3], v[250:251] op_sel:[0,0,0] op_sel_hi:[0,1,1] neg_lo:[0,0,1]
	v_pk_mul_f32 v[250:251], v[236:237], v[236:237] op_sel:[1,1] op_sel_hi:[1,0]
	v_pk_fma_f32 v[238:239], v[236:237], v[236:237], v[250:251] op_sel:[0,0,0] op_sel_hi:[0,1,1] neg_lo:[0,0,1]
	v_pk_mul_f32 v[250:251], v[238:239], v[236:237] op_sel:[1,1] op_sel_hi:[1,0]
	v_pk_fma_f32 v[240:241], v[238:239], v[236:237], v[250:251] op_sel:[0,0,0] op_sel_hi:[0,1,1] neg_lo:[0,0,1]
	v_lshrrev_b32_e32 v226, 8, v154
	v_lshlrev_b32_e32 v226, 12, v226
	v_and_b32_e32 v227, 255, v154
	v_add_u32_e32 v226, v226, v227
	v_lshlrev_b32_e32 v226, 3, v226
	v_add_u32_e32 v227, 0x10000, v226
	ds_read_b64 v[0:1], v226 offset:0
	ds_read_b64 v[2:3], v226 offset:2048
	ds_read_b64 v[4:5], v226 offset:4096
	ds_read_b64 v[6:7], v226 offset:6144
	ds_read_b64 v[8:9], v226 offset:8192
	ds_read_b64 v[10:11], v226 offset:10240
	ds_read_b64 v[12:13], v226 offset:12288
	ds_read_b64 v[14:15], v226 offset:14336
	ds_read_b64 v[16:17], v226 offset:16384
	ds_read_b64 v[18:19], v226 offset:18432
	ds_read_b64 v[20:21], v226 offset:20480
	ds_read_b64 v[22:23], v226 offset:22528
	ds_read_b64 v[24:25], v226 offset:24576
	ds_read_b64 v[26:27], v226 offset:26624
	ds_read_b64 v[28:29], v226 offset:28672
	ds_read_b64 v[30:31], v226 offset:30720
	s_waitcnt lgkmcnt(12)
	v_pk_mul_f32 v[250:251], v[4:5], v[238:239] op_sel:[1,1] op_sel_hi:[0,1]
	v_pk_fma_f32 v[4:5], v[4:5], v[238:239], v[250:251] op_sel:[0,0,0] op_sel_hi:[1,0,1] neg_hi:[0,0,1]
	v_pk_mul_f32 v[250:251], v[2:3], v[236:237] op_sel:[1,1] op_sel_hi:[0,1]
	v_pk_fma_f32 v[2:3], v[2:3], v[236:237], v[250:251] op_sel:[0,0,0] op_sel_hi:[1,0,1] neg_hi:[0,0,1]
	v_pk_mul_f32 v[250:251], v[6:7], v[240:241] op_sel:[1,1] op_sel_hi:[0,1]
	v_pk_fma_f32 v[6:7], v[6:7], v[240:241], v[250:251] op_sel:[0,0,0] op_sel_hi:[1,0,1] neg_hi:[0,0,1]
	v_pk_add_f32 v[242:243], v[0:1], v[4:5]
	v_pk_add_f32 v[244:245], v[0:1], v[4:5] neg_lo:[0,1] neg_hi:[0,1]
	v_pk_add_f32 v[246:247], v[2:3], v[6:7]
	v_pk_add_f32 v[248:249], v[2:3], v[6:7] neg_lo:[0,1] neg_hi:[0,1]
	v_pk_add_f32 v[0:1], v[242:243], v[246:247]
	v_pk_add_f32 v[2:3], v[244:245], v[248:249] op_sel:[0,1] op_sel_hi:[1,0] neg_lo:[0,1]
	v_pk_add_f32 v[4:5], v[242:243], v[246:247] neg_lo:[0,1] neg_hi:[0,1]
	v_pk_add_f32 v[6:7], v[244:245], v[248:249] op_sel:[0,1] op_sel_hi:[1,0] neg_hi:[0,1]
	s_waitcnt lgkmcnt(8)
	v_pk_mul_f32 v[250:251], v[12:13], v[238:239] op_sel:[1,1] op_sel_hi:[0,1]
	v_pk_fma_f32 v[12:13], v[12:13], v[238:239], v[250:251] op_sel:[0,0,0] op_sel_hi:[1,0,1] neg_hi:[0,0,1]
	v_pk_mul_f32 v[250:251], v[10:11], v[236:237] op_sel:[1,1] op_sel_hi:[0,1]
	v_pk_fma_f32 v[10:11], v[10:11], v[236:237], v[250:251] op_sel:[0,0,0] op_sel_hi:[1,0,1] neg_hi:[0,0,1]
	v_pk_mul_f32 v[250:251], v[14:15], v[240:241] op_sel:[1,1] op_sel_hi:[0,1]
	v_pk_fma_f32 v[14:15], v[14:15], v[240:241], v[250:251] op_sel:[0,0,0] op_sel_hi:[1,0,1] neg_hi:[0,0,1]
	v_pk_add_f32 v[242:243], v[8:9], v[12:13]
	v_pk_add_f32 v[244:245], v[8:9], v[12:13] neg_lo:[0,1] neg_hi:[0,1]
	v_pk_add_f32 v[246:247], v[10:11], v[14:15]
	v_pk_add_f32 v[248:249], v[10:11], v[14:15] neg_lo:[0,1] neg_hi:[0,1]
	v_pk_add_f32 v[8:9], v[242:243], v[246:247]
	v_pk_add_f32 v[10:11], v[244:245], v[248:249] op_sel:[0,1] op_sel_hi:[1,0] neg_lo:[0,1]
	v_pk_add_f32 v[12:13], v[242:243], v[246:247] neg_lo:[0,1] neg_hi:[0,1]
	v_pk_add_f32 v[14:15], v[244:245], v[248:249] op_sel:[0,1] op_sel_hi:[1,0] neg_hi:[0,1]
	s_waitcnt lgkmcnt(4)
	v_pk_mul_f32 v[250:251], v[20:21], v[238:239] op_sel:[1,1] op_sel_hi:[0,1]
	v_pk_fma_f32 v[20:21], v[20:21], v[238:239], v[250:251] op_sel:[0,0,0] op_sel_hi:[1,0,1] neg_hi:[0,0,1]
	v_pk_mul_f32 v[250:251], v[18:19], v[236:237] op_sel:[1,1] op_sel_hi:[0,1]
	v_pk_fma_f32 v[18:19], v[18:19], v[236:237], v[250:251] op_sel:[0,0,0] op_sel_hi:[1,0,1] neg_hi:[0,0,1]
	v_pk_mul_f32 v[250:251], v[22:23], v[240:241] op_sel:[1,1] op_sel_hi:[0,1]
	v_pk_fma_f32 v[22:23], v[22:23], v[240:241], v[250:251] op_sel:[0,0,0] op_sel_hi:[1,0,1] neg_hi:[0,0,1]
	v_pk_add_f32 v[242:243], v[16:17], v[20:21]
	v_pk_add_f32 v[244:245], v[16:17], v[20:21] neg_lo:[0,1] neg_hi:[0,1]
	v_pk_add_f32 v[246:247], v[18:19], v[22:23]
	v_pk_add_f32 v[248:249], v[18:19], v[22:23] neg_lo:[0,1] neg_hi:[0,1]
	v_pk_add_f32 v[16:17], v[242:243], v[246:247]
	v_pk_add_f32 v[18:19], v[244:245], v[248:249] op_sel:[0,1] op_sel_hi:[1,0] neg_lo:[0,1]
	v_pk_add_f32 v[20:21], v[242:243], v[246:247] neg_lo:[0,1] neg_hi:[0,1]
	v_pk_add_f32 v[22:23], v[244:245], v[248:249] op_sel:[0,1] op_sel_hi:[1,0] neg_hi:[0,1]
	s_waitcnt lgkmcnt(0)
; HD float2 cmul(float2 a, float2 b){ return make_float2(a.x*b.x - a.y*b.y, a.x*b.y + a.y*b.x); }
; HD float2 cmulc(float2 a, float2 b){ return make_float2(a.x*b.x + a.y*b.y, a.y*b.x - a.x*b.y); }
; template<bool INV, bool NOTW>
; HD void bf4c(float2* Z, int i0, int i1, int i2, int i3, float2 w1, float2 w2, float2 w3){
;   float2 a0=Z[i0], a1=Z[i1], a2=Z[i2], a3=Z[i3];
;   if (INV && !NOTW){ a1=cmulc(a1,w1); a2=cmulc(a2,w2); a3=cmulc(a3,w3); }
;   float2 s02=make_float2(a0.x+a2.x,a0.y+a2.y), d02=make_float2(a0.x-a2.x,a0.y-a2.y);
;   float2 s13=make_float2(a1.x+a3.x,a1.y+a3.y), d13=make_float2(a1.x-a3.x,a1.y-a3.y);
;   float2 y0=make_float2(s02.x+s13.x,s02.y+s13.y), y2=make_float2(s02.x-s13.x,s02.y-s13.y);
;   float2 ym=make_float2(d02.x+d13.y,d02.y-d13.x);
;   float2 yp=make_float2(d02.x-d13.y,d02.y+d13.x);
;   float2 y1, y3;
;   if (INV){ y1=yp; y3=ym; } else if (NOTW){ y1=ym; y3=yp; } else { y1=cmul(ym,w1); y2=cmul(y2,w2); y3=cmul(yp,w3); }
;   Z[i0]=y0; Z[i1]=y1; Z[i2]=y2; Z[i3]=y3;
; }
; HD int rev4_14(int p){ unsigned r = __brev((unsigned)p) >> 18; return (int)(((r & 0x2AAAu) >> 1) | ((r & 0x1555u) << 1)); }
; template<bool INV, int LQ, bool BARRIER=true>
; HD void fft_pass(float2* Z, const float2* twA, const float2* twB, int tid){
;   constexpr int q=1<<LQ; constexpr int tws=4096>>LQ;
;   if (LQ==12){
;     _Pragma("unroll 2") for (int i=0;i<8;++i){ int t=tid+512*i; int k=t;
;       float2 w1=cmul(twA[k>>6],twB[k&63]), w2=cmul(w1,w1), w3=cmul(w2,w1);
;       bf4c<INV,false>(Z,t,t+q,t+2*q,t+3*q,w1,w2,w3); }
;   } else if (LQ==10){
;     _Pragma("unroll") for (int e=0;e<2;++e){ int j=tid+512*e; int k=j*tws;
;       float2 w1=cmul(twA[k>>6],twB[k&63]), w2=cmul(w1,w1), w3=cmul(w2,w1);
;       _Pragma("unroll") for (int ip=0;ip<4;++ip){ int base=ip*4096+j; bf4c<INV,false>(Z,base,base+q,base+2*q,base+3*q,w1,w2,w3); } }
;   } else {
;     int j=tid&(q-1); int base0=((tid>>LQ)<<(LQ+2))+j;
;     float2 w1=make_float2(1.f,0.f), w2=w1, w3=w1;
;     if (LQ>0){ int k=j*tws; w1=cmul(twA[k>>6],twB[k&63]); w2=cmul(w1,w1); w3=cmul(w2,w1); }
;     _Pragma("unroll") for (int i=0;i<8;++i){ int base=base0+i*2048; bf4c<INV,(LQ==0)>(Z,base,base+q,base+2*q,base+3*q,w1,w2,w3); }
;   }
;   if (BARRIER) __syncthreads(); else asm volatile("s_waitcnt lgkmcnt(0)" ::: "memory");
	v_pk_mul_f32 v[250:251], v[28:29], v[238:239] op_sel:[1,1] op_sel_hi:[0,1]
	v_pk_fma_f32 v[28:29], v[28:29], v[238:239], v[250:251] op_sel:[0,0,0] op_sel_hi:[1,0,1] neg_hi:[0,0,1]
	v_pk_mul_f32 v[250:251], v[26:27], v[236:237] op_sel:[1,1] op_sel_hi:[0,1]
	v_pk_fma_f32 v[26:27], v[26:27], v[236:237], v[250:251] op_sel:[0,0,0] op_sel_hi:[1,0,1] neg_hi:[0,0,1]
	v_pk_mul_f32 v[250:251], v[30:31], v[240:241] op_sel:[1,1] op_sel_hi:[0,1]
	v_pk_fma_f32 v[30:31], v[30:31], v[240:241], v[250:251] op_sel:[0,0,0] op_sel_hi:[1,0,1] neg_hi:[0,0,1]
	v_pk_add_f32 v[242:243], v[24:25], v[28:29]
	v_pk_add_f32 v[244:245], v[24:25], v[28:29] neg_lo:[0,1] neg_hi:[0,1]
	v_pk_add_f32 v[246:247], v[26:27], v[30:31]
	v_pk_add_f32 v[248:249], v[26:27], v[30:31] neg_lo:[0,1] neg_hi:[0,1]
	v_pk_add_f32 v[24:25], v[242:243], v[246:247]
	v_pk_add_f32 v[26:27], v[244:245], v[248:249] op_sel:[0,1] op_sel_hi:[1,0] neg_lo:[0,1]
	v_pk_add_f32 v[28:29], v[242:243], v[246:247] neg_lo:[0,1] neg_hi:[0,1]
	v_pk_add_f32 v[30:31], v[244:245], v[248:249] op_sel:[0,1] op_sel_hi:[1,0] neg_hi:[0,1]
	v_pk_mul_f32 v[250:251], v[16:17], v[82:83] op_sel:[1,1] op_sel_hi:[0,1]
	v_pk_fma_f32 v[16:17], v[16:17], v[82:83], v[250:251] op_sel:[0,0,0] op_sel_hi:[1,0,1] neg_hi:[0,0,1]
	v_pk_mul_f32 v[250:251], v[8:9], v[80:81] op_sel:[1,1] op_sel_hi:[0,1]
	v_pk_fma_f32 v[8:9], v[8:9], v[80:81], v[250:251] op_sel:[0,0,0] op_sel_hi:[1,0,1] neg_hi:[0,0,1]
	v_pk_mul_f32 v[250:251], v[24:25], v[84:85] op_sel:[1,1] op_sel_hi:[0,1]
	v_pk_fma_f32 v[24:25], v[24:25], v[84:85], v[250:251] op_sel:[0,0,0] op_sel_hi:[1,0,1] neg_hi:[0,0,1]
	v_pk_add_f32 v[242:243], v[0:1], v[16:17]
	v_pk_add_f32 v[244:245], v[0:1], v[16:17] neg_lo:[0,1] neg_hi:[0,1]
	v_pk_add_f32 v[246:247], v[8:9], v[24:25]
	v_pk_add_f32 v[248:249], v[8:9], v[24:25] neg_lo:[0,1] neg_hi:[0,1]
	v_pk_add_f32 v[0:1], v[242:243], v[246:247]
	ds_write_b64 v226, v[0:1] offset:0
	v_pk_add_f32 v[8:9], v[244:245], v[248:249] op_sel:[0,1] op_sel_hi:[1,0] neg_lo:[0,1]
	ds_write_b64 v226, v[8:9] offset:8192
	v_pk_add_f32 v[16:17], v[242:243], v[246:247] neg_lo:[0,1] neg_hi:[0,1]
	ds_write_b64 v226, v[16:17] offset:16384
	v_pk_add_f32 v[24:25], v[244:245], v[248:249] op_sel:[0,1] op_sel_hi:[1,0] neg_hi:[0,1]
	ds_write_b64 v226, v[24:25] offset:24576
	v_pk_mul_f32 v[250:251], v[18:19], v[224:225] op_sel:[1,1] op_sel_hi:[1,0] neg_lo:[0,0] neg_hi:[0,0]
	v_pk_fma_f32 v[18:19], v[18:19], v[224:225], v[250:251] op_sel:[0,0,0] op_sel_hi:[0,1,1] neg_lo:[0,0,1] neg_hi:[0,0,0]
	v_pk_mul_f32 v[250:251], v[18:19], v[82:83] op_sel:[1,1] op_sel_hi:[0,1]
	v_pk_fma_f32 v[18:19], v[18:19], v[82:83], v[250:251] op_sel:[0,0,0] op_sel_hi:[1,0,1] neg_hi:[0,0,1]
	v_pk_mul_f32 v[250:251], v[10:11], v[222:223] op_sel:[1,1] op_sel_hi:[1,0] neg_lo:[0,0] neg_hi:[0,0]
	v_pk_fma_f32 v[10:11], v[10:11], v[222:223], v[250:251] op_sel:[0,0,0] op_sel_hi:[0,1,1] neg_lo:[0,0,1] neg_hi:[0,0,0]
	v_pk_mul_f32 v[250:251], v[10:11], v[80:81] op_sel:[1,1] op_sel_hi:[0,1]
	v_pk_fma_f32 v[10:11], v[10:11], v[80:81], v[250:251] op_sel:[0,0,0] op_sel_hi:[1,0,1] neg_hi:[0,0,1]
	v_pk_mul_f32 v[250:251], v[26:27], v[222:223] op_sel:[1,0] op_sel_hi:[1,1] neg_lo:[0,0] neg_hi:[0,0]
	v_pk_fma_f32 v[26:27], v[26:27], v[222:223], v[250:251] op_sel:[0,1,0] op_sel_hi:[0,0,1] neg_lo:[0,0,1] neg_hi:[0,0,0]
	v_pk_mul_f32 v[250:251], v[26:27], v[84:85] op_sel:[1,1] op_sel_hi:[0,1]
	v_pk_fma_f32 v[26:27], v[26:27], v[84:85], v[250:251] op_sel:[0,0,0] op_sel_hi:[1,0,1] neg_hi:[0,0,1]
	v_pk_add_f32 v[242:243], v[2:3], v[18:19]
	v_pk_add_f32 v[244:245], v[2:3], v[18:19] neg_lo:[0,1] neg_hi:[0,1]
	v_pk_add_f32 v[246:247], v[10:11], v[26:27]
	v_pk_add_f32 v[248:249], v[10:11], v[26:27] neg_lo:[0,1] neg_hi:[0,1]
	v_pk_add_f32 v[2:3], v[242:243], v[246:247]
	ds_write_b64 v226, v[2:3] offset:2048
	v_pk_add_f32 v[10:11], v[244:245], v[248:249] op_sel:[0,1] op_sel_hi:[1,0] neg_lo:[0,1]
	ds_write_b64 v226, v[10:11] offset:10240
	v_pk_add_f32 v[18:19], v[242:243], v[246:247] neg_lo:[0,1] neg_hi:[0,1]
	ds_write_b64 v226, v[18:19] offset:18432
	v_pk_add_f32 v[26:27], v[244:245], v[248:249] op_sel:[0,1] op_sel_hi:[1,0] neg_hi:[0,1]
	ds_write_b64 v226, v[26:27] offset:26624
	v_pk_add_f32 v[20:21], v[20:21], 0 op_sel:[1,0] op_sel_hi:[0,0] neg_lo:[1,0]
	v_pk_mul_f32 v[250:251], v[20:21], v[82:83] op_sel:[1,1] op_sel_hi:[0,1]
	v_pk_fma_f32 v[20:21], v[20:21], v[82:83], v[250:251] op_sel:[0,0,0] op_sel_hi:[1,0,1] neg_hi:[0,0,1]
	v_pk_mul_f32 v[250:251], v[12:13], v[224:225] op_sel:[1,1] op_sel_hi:[1,0] neg_lo:[0,0] neg_hi:[0,0]
	v_pk_fma_f32 v[12:13], v[12:13], v[224:225], v[250:251] op_sel:[0,0,0] op_sel_hi:[0,1,1] neg_lo:[0,0,1] neg_hi:[0,0,0]
	v_pk_mul_f32 v[250:251], v[12:13], v[80:81] op_sel:[1,1] op_sel_hi:[0,1]
	v_pk_fma_f32 v[12:13], v[12:13], v[80:81], v[250:251] op_sel:[0,0,0] op_sel_hi:[1,0,1] neg_hi:[0,0,1]
	v_pk_mul_f32 v[250:251], v[28:29], v[224:225] op_sel:[1,1] op_sel_hi:[1,0] neg_lo:[0,0] neg_hi:[0,1]
	v_pk_fma_f32 v[28:29], v[28:29], v[224:225], v[250:251] op_sel:[0,0,0] op_sel_hi:[0,1,1] neg_lo:[0,1,1] neg_hi:[0,0,0]
	v_pk_mul_f32 v[250:251], v[28:29], v[84:85] op_sel:[1,1] op_sel_hi:[0,1]
	v_pk_fma_f32 v[28:29], v[28:29], v[84:85], v[250:251] op_sel:[0,0,0] op_sel_hi:[1,0,1] neg_hi:[0,0,1]
	v_pk_add_f32 v[242:243], v[4:5], v[20:21]
	v_pk_add_f32 v[244:245], v[4:5], v[20:21] neg_lo:[0,1] neg_hi:[0,1]
	v_pk_add_f32 v[246:247], v[12:13], v[28:29]
	v_pk_add_f32 v[248:249], v[12:13], v[28:29] neg_lo:[0,1] neg_hi:[0,1]
	v_pk_add_f32 v[4:5], v[242:243], v[246:247]
	ds_write_b64 v226, v[4:5] offset:4096
	v_pk_add_f32 v[12:13], v[244:245], v[248:249] op_sel:[0,1] op_sel_hi:[1,0] neg_lo:[0,1]
	ds_write_b64 v226, v[12:13] offset:12288
; HD float2 cmul(float2 a, float2 b){ return make_float2(a.x*b.x - a.y*b.y, a.x*b.y + a.y*b.x); }
; HD float2 cmulc(float2 a, float2 b){ return make_float2(a.x*b.x + a.y*b.y, a.y*b.x - a.x*b.y); }
; template<bool INV, bool NOTW>
; HD void bf4c(float2* Z, int i0, int i1, int i2, int i3, float2 w1, float2 w2, float2 w3){
;   float2 a0=Z[i0], a1=Z[i1], a2=Z[i2], a3=Z[i3];
;   if (INV && !NOTW){ a1=cmulc(a1,w1); a2=cmulc(a2,w2); a3=cmulc(a3,w3); }
;   float2 s02=make_float2(a0.x+a2.x,a0.y+a2.y), d02=make_float2(a0.x-a2.x,a0.y-a2.y);
;   float2 s13=make_float2(a1.x+a3.x,a1.y+a3.y), d13=make_float2(a1.x-a3.x,a1.y-a3.y);
;   float2 y0=make_float2(s02.x+s13.x,s02.y+s13.y), y2=make_float2(s02.x-s13.x,s02.y-s13.y);
;   float2 ym=make_float2(d02.x+d13.y,d02.y-d13.x);
;   float2 yp=make_float2(d02.x-d13.y,d02.y+d13.x);
;   float2 y1, y3;
;   if (INV){ y1=yp; y3=ym; } else if (NOTW){ y1=ym; y3=yp; } else { y1=cmul(ym,w1); y2=cmul(y2,w2); y3=cmul(yp,w3); }
;   Z[i0]=y0; Z[i1]=y1; Z[i2]=y2; Z[i3]=y3;
; }
; HD int rev4_14(int p){ unsigned r = __brev((unsigned)p) >> 18; return (int)(((r & 0x2AAAu) >> 1) | ((r & 0x1555u) << 1)); }
; template<bool INV, int LQ, bool BARRIER=true>
; HD void fft_pass(float2* Z, const float2* twA, const float2* twB, int tid){
;   constexpr int q=1<<LQ; constexpr int tws=4096>>LQ;
;   if (LQ==12){
;     _Pragma("unroll 2") for (int i=0;i<8;++i){ int t=tid+512*i; int k=t;
;       float2 w1=cmul(twA[k>>6],twB[k&63]), w2=cmul(w1,w1), w3=cmul(w2,w1);
;       bf4c<INV,false>(Z,t,t+q,t+2*q,t+3*q,w1,w2,w3); }
;   } else if (LQ==10){
;     _Pragma("unroll") for (int e=0;e<2;++e){ int j=tid+512*e; int k=j*tws;
;       float2 w1=cmul(twA[k>>6],twB[k&63]), w2=cmul(w1,w1), w3=cmul(w2,w1);
;       _Pragma("unroll") for (int ip=0;ip<4;++ip){ int base=ip*4096+j; bf4c<INV,false>(Z,base,base+q,base+2*q,base+3*q,w1,w2,w3); } }
;   } else {
;     int j=tid&(q-1); int base0=((tid>>LQ)<<(LQ+2))+j;
;     float2 w1=make_float2(1.f,0.f), w2=w1, w3=w1;
;     if (LQ>0){ int k=j*tws; w1=cmul(twA[k>>6],twB[k&63]); w2=cmul(w1,w1); w3=cmul(w2,w1); }
;     _Pragma("unroll") for (int i=0;i<8;++i){ int base=base0+i*2048; bf4c<INV,(LQ==0)>(Z,base,base+q,base+2*q,base+3*q,w1,w2,w3); }
;   }
;   if (BARRIER) __syncthreads(); else asm volatile("s_waitcnt lgkmcnt(0)" ::: "memory");
	v_pk_add_f32 v[20:21], v[242:243], v[246:247] neg_lo:[0,1] neg_hi:[0,1]
	ds_write_b64 v226, v[20:21] offset:20480
	v_pk_add_f32 v[28:29], v[244:245], v[248:249] op_sel:[0,1] op_sel_hi:[1,0] neg_hi:[0,1]
	ds_write_b64 v226, v[28:29] offset:28672
	v_pk_mul_f32 v[250:251], v[22:23], v[224:225] op_sel:[1,1] op_sel_hi:[1,0] neg_lo:[0,0] neg_hi:[0,1]
	v_pk_fma_f32 v[22:23], v[22:23], v[224:225], v[250:251] op_sel:[0,0,0] op_sel_hi:[0,1,1] neg_lo:[0,1,1] neg_hi:[0,0,0]
	v_pk_mul_f32 v[250:251], v[22:23], v[82:83] op_sel:[1,1] op_sel_hi:[0,1]
	v_pk_fma_f32 v[22:23], v[22:23], v[82:83], v[250:251] op_sel:[0,0,0] op_sel_hi:[1,0,1] neg_hi:[0,0,1]
	v_pk_mul_f32 v[250:251], v[14:15], v[222:223] op_sel:[1,0] op_sel_hi:[1,1] neg_lo:[0,0] neg_hi:[0,0]
	v_pk_fma_f32 v[14:15], v[14:15], v[222:223], v[250:251] op_sel:[0,1,0] op_sel_hi:[0,0,1] neg_lo:[0,0,1] neg_hi:[0,0,0]
	v_pk_mul_f32 v[250:251], v[14:15], v[80:81] op_sel:[1,1] op_sel_hi:[0,1]
	v_pk_fma_f32 v[14:15], v[14:15], v[80:81], v[250:251] op_sel:[0,0,0] op_sel_hi:[1,0,1] neg_hi:[0,0,1]
	v_pk_mul_f32 v[250:251], v[30:31], v[222:223] op_sel:[1,1] op_sel_hi:[1,0] neg_lo:[0,1] neg_hi:[0,1]
	v_pk_fma_f32 v[30:31], v[30:31], v[222:223], v[250:251] op_sel:[0,0,0] op_sel_hi:[0,1,1] neg_lo:[0,1,1] neg_hi:[0,1,0]
	v_pk_mul_f32 v[250:251], v[30:31], v[84:85] op_sel:[1,1] op_sel_hi:[0,1]
	v_pk_fma_f32 v[30:31], v[30:31], v[84:85], v[250:251] op_sel:[0,0,0] op_sel_hi:[1,0,1] neg_hi:[0,0,1]
	v_pk_add_f32 v[242:243], v[6:7], v[22:23]
	v_pk_add_f32 v[244:245], v[6:7], v[22:23] neg_lo:[0,1] neg_hi:[0,1]
	v_pk_add_f32 v[246:247], v[14:15], v[30:31]
	v_pk_add_f32 v[248:249], v[14:15], v[30:31] neg_lo:[0,1] neg_hi:[0,1]
	v_pk_add_f32 v[6:7], v[242:243], v[246:247]
	ds_write_b64 v226, v[6:7] offset:6144
	v_pk_add_f32 v[14:15], v[244:245], v[248:249] op_sel:[0,1] op_sel_hi:[1,0] neg_lo:[0,1]
	ds_write_b64 v226, v[14:15] offset:14336
	v_pk_add_f32 v[22:23], v[242:243], v[246:247] neg_lo:[0,1] neg_hi:[0,1]
	ds_write_b64 v226, v[22:23] offset:22528
	v_pk_add_f32 v[30:31], v[244:245], v[248:249] op_sel:[0,1] op_sel_hi:[1,0] neg_hi:[0,1]
	ds_write_b64 v226, v[30:31] offset:30720
	ds_read_b64 v[0:1], v227 offset:0
	ds_read_b64 v[2:3], v227 offset:2048
	ds_read_b64 v[4:5], v227 offset:4096
	ds_read_b64 v[6:7], v227 offset:6144
	ds_read_b64 v[8:9], v227 offset:8192
	ds_read_b64 v[10:11], v227 offset:10240
	ds_read_b64 v[12:13], v227 offset:12288
	ds_read_b64 v[14:15], v227 offset:14336
	ds_read_b64 v[16:17], v227 offset:16384
	ds_read_b64 v[18:19], v227 offset:18432
	ds_read_b64 v[20:21], v227 offset:20480
	ds_read_b64 v[22:23], v227 offset:22528
	ds_read_b64 v[24:25], v227 offset:24576
	ds_read_b64 v[26:27], v227 offset:26624
	ds_read_b64 v[28:29], v227 offset:28672
	ds_read_b64 v[30:31], v227 offset:30720
	s_waitcnt lgkmcnt(12)
	v_pk_mul_f32 v[250:251], v[4:5], v[238:239] op_sel:[1,1] op_sel_hi:[0,1]
	v_pk_fma_f32 v[4:5], v[4:5], v[238:239], v[250:251] op_sel:[0,0,0] op_sel_hi:[1,0,1] neg_hi:[0,0,1]
	v_pk_mul_f32 v[250:251], v[2:3], v[236:237] op_sel:[1,1] op_sel_hi:[0,1]
	v_pk_fma_f32 v[2:3], v[2:3], v[236:237], v[250:251] op_sel:[0,0,0] op_sel_hi:[1,0,1] neg_hi:[0,0,1]
	v_pk_mul_f32 v[250:251], v[6:7], v[240:241] op_sel:[1,1] op_sel_hi:[0,1]
	v_pk_fma_f32 v[6:7], v[6:7], v[240:241], v[250:251] op_sel:[0,0,0] op_sel_hi:[1,0,1] neg_hi:[0,0,1]
	v_pk_add_f32 v[242:243], v[0:1], v[4:5]
	v_pk_add_f32 v[244:245], v[0:1], v[4:5] neg_lo:[0,1] neg_hi:[0,1]
	v_pk_add_f32 v[246:247], v[2:3], v[6:7]
	v_pk_add_f32 v[248:249], v[2:3], v[6:7] neg_lo:[0,1] neg_hi:[0,1]
	v_pk_add_f32 v[0:1], v[242:243], v[246:247]
	v_pk_add_f32 v[2:3], v[244:245], v[248:249] op_sel:[0,1] op_sel_hi:[1,0] neg_lo:[0,1]
	v_pk_add_f32 v[4:5], v[242:243], v[246:247] neg_lo:[0,1] neg_hi:[0,1]
	v_pk_add_f32 v[6:7], v[244:245], v[248:249] op_sel:[0,1] op_sel_hi:[1,0] neg_hi:[0,1]
	s_waitcnt lgkmcnt(8)
	v_pk_mul_f32 v[250:251], v[12:13], v[238:239] op_sel:[1,1] op_sel_hi:[0,1]
	v_pk_fma_f32 v[12:13], v[12:13], v[238:239], v[250:251] op_sel:[0,0,0] op_sel_hi:[1,0,1] neg_hi:[0,0,1]
	v_pk_mul_f32 v[250:251], v[10:11], v[236:237] op_sel:[1,1] op_sel_hi:[0,1]
	v_pk_fma_f32 v[10:11], v[10:11], v[236:237], v[250:251] op_sel:[0,0,0] op_sel_hi:[1,0,1] neg_hi:[0,0,1]
	v_pk_mul_f32 v[250:251], v[14:15], v[240:241] op_sel:[1,1] op_sel_hi:[0,1]
	v_pk_fma_f32 v[14:15], v[14:15], v[240:241], v[250:251] op_sel:[0,0,0] op_sel_hi:[1,0,1] neg_hi:[0,0,1]
	v_pk_add_f32 v[242:243], v[8:9], v[12:13]
	v_pk_add_f32 v[244:245], v[8:9], v[12:13] neg_lo:[0,1] neg_hi:[0,1]
	v_pk_add_f32 v[246:247], v[10:11], v[14:15]
	v_pk_add_f32 v[248:249], v[10:11], v[14:15] neg_lo:[0,1] neg_hi:[0,1]
	v_pk_add_f32 v[8:9], v[242:243], v[246:247]
	v_pk_add_f32 v[10:11], v[244:245], v[248:249] op_sel:[0,1] op_sel_hi:[1,0] neg_lo:[0,1]
	v_pk_add_f32 v[12:13], v[242:243], v[246:247] neg_lo:[0,1] neg_hi:[0,1]
	v_pk_add_f32 v[14:15], v[244:245], v[248:249] op_sel:[0,1] op_sel_hi:[1,0] neg_hi:[0,1]
	s_waitcnt lgkmcnt(4)
	v_pk_mul_f32 v[250:251], v[20:21], v[238:239] op_sel:[1,1] op_sel_hi:[0,1]
	v_pk_fma_f32 v[20:21], v[20:21], v[238:239], v[250:251] op_sel:[0,0,0] op_sel_hi:[1,0,1] neg_hi:[0,0,1]
	v_pk_mul_f32 v[250:251], v[18:19], v[236:237] op_sel:[1,1] op_sel_hi:[0,1]
	v_pk_fma_f32 v[18:19], v[18:19], v[236:237], v[250:251] op_sel:[0,0,0] op_sel_hi:[1,0,1] neg_hi:[0,0,1]
	v_pk_mul_f32 v[250:251], v[22:23], v[240:241] op_sel:[1,1] op_sel_hi:[0,1]
	v_pk_fma_f32 v[22:23], v[22:23], v[240:241], v[250:251] op_sel:[0,0,0] op_sel_hi:[1,0,1] neg_hi:[0,0,1]
	v_pk_add_f32 v[242:243], v[16:17], v[20:21]
	v_pk_add_f32 v[244:245], v[16:17], v[20:21] neg_lo:[0,1] neg_hi:[0,1]
	v_pk_add_f32 v[246:247], v[18:19], v[22:23]
	v_pk_add_f32 v[248:249], v[18:19], v[22:23] neg_lo:[0,1] neg_hi:[0,1]
	v_pk_add_f32 v[16:17], v[242:243], v[246:247]
	v_pk_add_f32 v[18:19], v[244:245], v[248:249] op_sel:[0,1] op_sel_hi:[1,0] neg_lo:[0,1]
	v_pk_add_f32 v[20:21], v[242:243], v[246:247] neg_lo:[0,1] neg_hi:[0,1]
	v_pk_add_f32 v[22:23], v[244:245], v[248:249] op_sel:[0,1] op_sel_hi:[1,0] neg_hi:[0,1]
	s_waitcnt lgkmcnt(0)
; HD float2 cmul(float2 a, float2 b){ return make_float2(a.x*b.x - a.y*b.y, a.x*b.y + a.y*b.x); }
; HD float2 cmulc(float2 a, float2 b){ return make_float2(a.x*b.x + a.y*b.y, a.y*b.x - a.x*b.y); }
; template<bool INV, bool NOTW>
; HD void bf4c(float2* Z, int i0, int i1, int i2, int i3, float2 w1, float2 w2, float2 w3){
;   float2 a0=Z[i0], a1=Z[i1], a2=Z[i2], a3=Z[i3];
;   if (INV && !NOTW){ a1=cmulc(a1,w1); a2=cmulc(a2,w2); a3=cmulc(a3,w3); }
;   float2 s02=make_float2(a0.x+a2.x,a0.y+a2.y), d02=make_float2(a0.x-a2.x,a0.y-a2.y);
;   float2 s13=make_float2(a1.x+a3.x,a1.y+a3.y), d13=make_float2(a1.x-a3.x,a1.y-a3.y);
;   float2 y0=make_float2(s02.x+s13.x,s02.y+s13.y), y2=make_float2(s02.x-s13.x,s02.y-s13.y);
;   float2 ym=make_float2(d02.x+d13.y,d02.y-d13.x);
;   float2 yp=make_float2(d02.x-d13.y,d02.y+d13.x);
;   float2 y1, y3;
;   if (INV){ y1=yp; y3=ym; } else if (NOTW){ y1=ym; y3=yp; } else { y1=cmul(ym,w1); y2=cmul(y2,w2); y3=cmul(yp,w3); }
;   Z[i0]=y0; Z[i1]=y1; Z[i2]=y2; Z[i3]=y3;
; }
; HD int rev4_14(int p){ unsigned r = __brev((unsigned)p) >> 18; return (int)(((r & 0x2AAAu) >> 1) | ((r & 0x1555u) << 1)); }
; template<bool INV, int LQ, bool BARRIER=true>
; HD void fft_pass(float2* Z, const float2* twA, const float2* twB, int tid){
;   constexpr int q=1<<LQ; constexpr int tws=4096>>LQ;
;   if (LQ==12){
;     _Pragma("unroll 2") for (int i=0;i<8;++i){ int t=tid+512*i; int k=t;
;       float2 w1=cmul(twA[k>>6],twB[k&63]), w2=cmul(w1,w1), w3=cmul(w2,w1);
;       bf4c<INV,false>(Z,t,t+q,t+2*q,t+3*q,w1,w2,w3); }
;   } else if (LQ==10){
;     _Pragma("unroll") for (int e=0;e<2;++e){ int j=tid+512*e; int k=j*tws;
;       float2 w1=cmul(twA[k>>6],twB[k&63]), w2=cmul(w1,w1), w3=cmul(w2,w1);
;       _Pragma("unroll") for (int ip=0;ip<4;++ip){ int base=ip*4096+j; bf4c<INV,false>(Z,base,base+q,base+2*q,base+3*q,w1,w2,w3); } }
;   } else {
;     int j=tid&(q-1); int base0=((tid>>LQ)<<(LQ+2))+j;
;     float2 w1=make_float2(1.f,0.f), w2=w1, w3=w1;
;     if (LQ>0){ int k=j*tws; w1=cmul(twA[k>>6],twB[k&63]); w2=cmul(w1,w1); w3=cmul(w2,w1); }
;     _Pragma("unroll") for (int i=0;i<8;++i){ int base=base0+i*2048; bf4c<INV,(LQ==0)>(Z,base,base+q,base+2*q,base+3*q,w1,w2,w3); }
;   }
;   if (BARRIER) __syncthreads(); else asm volatile("s_waitcnt lgkmcnt(0)" ::: "memory");
	v_pk_mul_f32 v[250:251], v[28:29], v[238:239] op_sel:[1,1] op_sel_hi:[0,1]
	v_pk_fma_f32 v[28:29], v[28:29], v[238:239], v[250:251] op_sel:[0,0,0] op_sel_hi:[1,0,1] neg_hi:[0,0,1]
	v_pk_mul_f32 v[250:251], v[26:27], v[236:237] op_sel:[1,1] op_sel_hi:[0,1]
	v_pk_fma_f32 v[26:27], v[26:27], v[236:237], v[250:251] op_sel:[0,0,0] op_sel_hi:[1,0,1] neg_hi:[0,0,1]
	v_pk_mul_f32 v[250:251], v[30:31], v[240:241] op_sel:[1,1] op_sel_hi:[0,1]
	v_pk_fma_f32 v[30:31], v[30:31], v[240:241], v[250:251] op_sel:[0,0,0] op_sel_hi:[1,0,1] neg_hi:[0,0,1]
	v_pk_add_f32 v[242:243], v[24:25], v[28:29]
	v_pk_add_f32 v[244:245], v[24:25], v[28:29] neg_lo:[0,1] neg_hi:[0,1]
	v_pk_add_f32 v[246:247], v[26:27], v[30:31]
	v_pk_add_f32 v[248:249], v[26:27], v[30:31] neg_lo:[0,1] neg_hi:[0,1]
	v_pk_add_f32 v[24:25], v[242:243], v[246:247]
	v_pk_add_f32 v[26:27], v[244:245], v[248:249] op_sel:[0,1] op_sel_hi:[1,0] neg_lo:[0,1]
	v_pk_add_f32 v[28:29], v[242:243], v[246:247] neg_lo:[0,1] neg_hi:[0,1]
	v_pk_add_f32 v[30:31], v[244:245], v[248:249] op_sel:[0,1] op_sel_hi:[1,0] neg_hi:[0,1]
	v_pk_mul_f32 v[250:251], v[16:17], v[82:83] op_sel:[1,1] op_sel_hi:[0,1]
	v_pk_fma_f32 v[16:17], v[16:17], v[82:83], v[250:251] op_sel:[0,0,0] op_sel_hi:[1,0,1] neg_hi:[0,0,1]
	v_pk_mul_f32 v[250:251], v[8:9], v[80:81] op_sel:[1,1] op_sel_hi:[0,1]
	v_pk_fma_f32 v[8:9], v[8:9], v[80:81], v[250:251] op_sel:[0,0,0] op_sel_hi:[1,0,1] neg_hi:[0,0,1]
	v_pk_mul_f32 v[250:251], v[24:25], v[84:85] op_sel:[1,1] op_sel_hi:[0,1]
	v_pk_fma_f32 v[24:25], v[24:25], v[84:85], v[250:251] op_sel:[0,0,0] op_sel_hi:[1,0,1] neg_hi:[0,0,1]
	v_pk_add_f32 v[242:243], v[0:1], v[16:17]
	v_pk_add_f32 v[244:245], v[0:1], v[16:17] neg_lo:[0,1] neg_hi:[0,1]
	v_pk_add_f32 v[246:247], v[8:9], v[24:25]
	v_pk_add_f32 v[248:249], v[8:9], v[24:25] neg_lo:[0,1] neg_hi:[0,1]
	v_pk_add_f32 v[0:1], v[242:243], v[246:247]
	ds_write_b64 v227, v[0:1] offset:0
	v_pk_add_f32 v[8:9], v[244:245], v[248:249] op_sel:[0,1] op_sel_hi:[1,0] neg_lo:[0,1]
	ds_write_b64 v227, v[8:9] offset:8192
	v_pk_add_f32 v[16:17], v[242:243], v[246:247] neg_lo:[0,1] neg_hi:[0,1]
	ds_write_b64 v227, v[16:17] offset:16384
	v_pk_add_f32 v[24:25], v[244:245], v[248:249] op_sel:[0,1] op_sel_hi:[1,0] neg_hi:[0,1]
	ds_write_b64 v227, v[24:25] offset:24576
	v_pk_mul_f32 v[250:251], v[18:19], v[224:225] op_sel:[1,1] op_sel_hi:[1,0] neg_lo:[0,0] neg_hi:[0,0]
	v_pk_fma_f32 v[18:19], v[18:19], v[224:225], v[250:251] op_sel:[0,0,0] op_sel_hi:[0,1,1] neg_lo:[0,0,1] neg_hi:[0,0,0]
	v_pk_mul_f32 v[250:251], v[18:19], v[82:83] op_sel:[1,1] op_sel_hi:[0,1]
	v_pk_fma_f32 v[18:19], v[18:19], v[82:83], v[250:251] op_sel:[0,0,0] op_sel_hi:[1,0,1] neg_hi:[0,0,1]
	v_pk_mul_f32 v[250:251], v[10:11], v[222:223] op_sel:[1,1] op_sel_hi:[1,0] neg_lo:[0,0] neg_hi:[0,0]
	v_pk_fma_f32 v[10:11], v[10:11], v[222:223], v[250:251] op_sel:[0,0,0] op_sel_hi:[0,1,1] neg_lo:[0,0,1] neg_hi:[0,0,0]
	v_pk_mul_f32 v[250:251], v[10:11], v[80:81] op_sel:[1,1] op_sel_hi:[0,1]
	v_pk_fma_f32 v[10:11], v[10:11], v[80:81], v[250:251] op_sel:[0,0,0] op_sel_hi:[1,0,1] neg_hi:[0,0,1]
	v_pk_mul_f32 v[250:251], v[26:27], v[222:223] op_sel:[1,0] op_sel_hi:[1,1] neg_lo:[0,0] neg_hi:[0,0]
	v_pk_fma_f32 v[26:27], v[26:27], v[222:223], v[250:251] op_sel:[0,1,0] op_sel_hi:[0,0,1] neg_lo:[0,0,1] neg_hi:[0,0,0]
	v_pk_mul_f32 v[250:251], v[26:27], v[84:85] op_sel:[1,1] op_sel_hi:[0,1]
	v_pk_fma_f32 v[26:27], v[26:27], v[84:85], v[250:251] op_sel:[0,0,0] op_sel_hi:[1,0,1] neg_hi:[0,0,1]
	v_pk_add_f32 v[242:243], v[2:3], v[18:19]
	v_pk_add_f32 v[244:245], v[2:3], v[18:19] neg_lo:[0,1] neg_hi:[0,1]
	v_pk_add_f32 v[246:247], v[10:11], v[26:27]
	v_pk_add_f32 v[248:249], v[10:11], v[26:27] neg_lo:[0,1] neg_hi:[0,1]
	v_pk_add_f32 v[2:3], v[242:243], v[246:247]
	ds_write_b64 v227, v[2:3] offset:2048
	v_pk_add_f32 v[10:11], v[244:245], v[248:249] op_sel:[0,1] op_sel_hi:[1,0] neg_lo:[0,1]
	ds_write_b64 v227, v[10:11] offset:10240
	v_pk_add_f32 v[18:19], v[242:243], v[246:247] neg_lo:[0,1] neg_hi:[0,1]
	ds_write_b64 v227, v[18:19] offset:18432
	v_pk_add_f32 v[26:27], v[244:245], v[248:249] op_sel:[0,1] op_sel_hi:[1,0] neg_hi:[0,1]
	ds_write_b64 v227, v[26:27] offset:26624
	v_pk_add_f32 v[20:21], v[20:21], 0 op_sel:[1,0] op_sel_hi:[0,0] neg_lo:[1,0]
	v_pk_mul_f32 v[250:251], v[20:21], v[82:83] op_sel:[1,1] op_sel_hi:[0,1]
	v_pk_fma_f32 v[20:21], v[20:21], v[82:83], v[250:251] op_sel:[0,0,0] op_sel_hi:[1,0,1] neg_hi:[0,0,1]
	v_pk_mul_f32 v[250:251], v[12:13], v[224:225] op_sel:[1,1] op_sel_hi:[1,0] neg_lo:[0,0] neg_hi:[0,0]
	v_pk_fma_f32 v[12:13], v[12:13], v[224:225], v[250:251] op_sel:[0,0,0] op_sel_hi:[0,1,1] neg_lo:[0,0,1] neg_hi:[0,0,0]
	v_pk_mul_f32 v[250:251], v[12:13], v[80:81] op_sel:[1,1] op_sel_hi:[0,1]
	v_pk_fma_f32 v[12:13], v[12:13], v[80:81], v[250:251] op_sel:[0,0,0] op_sel_hi:[1,0,1] neg_hi:[0,0,1]
	v_pk_mul_f32 v[250:251], v[28:29], v[224:225] op_sel:[1,1] op_sel_hi:[1,0] neg_lo:[0,0] neg_hi:[0,1]
	v_pk_fma_f32 v[28:29], v[28:29], v[224:225], v[250:251] op_sel:[0,0,0] op_sel_hi:[0,1,1] neg_lo:[0,1,1] neg_hi:[0,0,0]
	v_pk_mul_f32 v[250:251], v[28:29], v[84:85] op_sel:[1,1] op_sel_hi:[0,1]
	v_pk_fma_f32 v[28:29], v[28:29], v[84:85], v[250:251] op_sel:[0,0,0] op_sel_hi:[1,0,1] neg_hi:[0,0,1]
	v_pk_add_f32 v[242:243], v[4:5], v[20:21]
	v_pk_add_f32 v[244:245], v[4:5], v[20:21] neg_lo:[0,1] neg_hi:[0,1]
	v_pk_add_f32 v[246:247], v[12:13], v[28:29]
	v_pk_add_f32 v[248:249], v[12:13], v[28:29] neg_lo:[0,1] neg_hi:[0,1]
	v_pk_add_f32 v[4:5], v[242:243], v[246:247]
	ds_write_b64 v227, v[4:5] offset:4096
	v_pk_add_f32 v[12:13], v[244:245], v[248:249] op_sel:[0,1] op_sel_hi:[1,0] neg_lo:[0,1]
	ds_write_b64 v227, v[12:13] offset:12288
; __device__ __forceinline__ float bf2f(u16 h){ return __uint_as_float(((unsigned)h)<<16); }
; HD float2 cmul(float2 a, float2 b){ return make_float2(a.x*b.x - a.y*b.y, a.x*b.y + a.y*b.x); }
; HD float2 cmulc(float2 a, float2 b){ return make_float2(a.x*b.x + a.y*b.y, a.y*b.x - a.x*b.y); }
; HD void inv12_half(const float2* Z, const float2* twA, const float2* twB, int t, float2& x0, float2& x1){
;   float2 w1=cmul(twA[t>>6],twB[t&63]), w2=cmul(w1,w1), w3=cmul(w2,w1);
;   float2 b0=Z[t], b1=cmulc(Z[t+4096],w1), b2=cmulc(Z[t+8192],w2), b3=cmulc(Z[t+12288],w3);
;   float2 s02=make_float2(b0.x+b2.x,b0.y+b2.y), d02=make_float2(b0.x-b2.x,b0.y-b2.y);
;   float2 s13=make_float2(b1.x+b3.x,b1.y+b3.y), d13=make_float2(b1.x-b3.x,b1.y-b3.y);
;   x0=make_float2(s02.x+s13.x,s02.y+s13.y);
;   x1=make_float2(d02.x-d13.y,d02.y+d13.x);
; }
; __device__ __forceinline__ void phase_hyena(KP kp_, int hf){ asm volatile("" : "+s"(kp_)); const Params p=load_params(kp_);
;     ...
;         } else { int tq=tid; asm volatile("" : "+v"(tq));
;           _Pragma("unroll 4") for (int i=0;i<8;++i){ int tb=tq+512*i; float2 xr[2]; inv12_half(Z,twA,twB,tb,xr[0],xr[1]);
;             _Pragma("unroll") for (int hh=0;hh<2;++hh){ int t=tb+hh*4096;
;               float x0=hconv3(r2,t,wb0,wb1,wb2,bb_), x1=hconv3(r2+8192,t,wb0,wb1,wb2,bb_);
;               float2 y=xr[hh]; y.x*=(1.f/16384.f); y.y*=(1.f/16384.f); float2 z1=Zs[t];
;               float o0=x0*(y.x+z1.x*bias1)*bf2f(rz[t]); float o1=x1*(y.y+z1.y*bias1)*bf2f(rz[8192+t]);
;               ybT[(size_t)c*16384+t]=f2bf(o0); ybT[(size_t)c*16384+8192+t]=f2bf(o1); } }
	v_pk_add_f32 v[20:21], v[242:243], v[246:247] neg_lo:[0,1] neg_hi:[0,1]
	ds_write_b64 v227, v[20:21] offset:20480
	v_pk_add_f32 v[28:29], v[244:245], v[248:249] op_sel:[0,1] op_sel_hi:[1,0] neg_hi:[0,1]
	ds_write_b64 v227, v[28:29] offset:28672
	v_pk_mul_f32 v[250:251], v[22:23], v[224:225] op_sel:[1,1] op_sel_hi:[1,0] neg_lo:[0,0] neg_hi:[0,1]
	v_pk_fma_f32 v[22:23], v[22:23], v[224:225], v[250:251] op_sel:[0,0,0] op_sel_hi:[0,1,1] neg_lo:[0,1,1] neg_hi:[0,0,0]
	v_pk_mul_f32 v[250:251], v[22:23], v[82:83] op_sel:[1,1] op_sel_hi:[0,1]
	v_pk_fma_f32 v[22:23], v[22:23], v[82:83], v[250:251] op_sel:[0,0,0] op_sel_hi:[1,0,1] neg_hi:[0,0,1]
	v_pk_mul_f32 v[250:251], v[14:15], v[222:223] op_sel:[1,0] op_sel_hi:[1,1] neg_lo:[0,0] neg_hi:[0,0]
	v_pk_fma_f32 v[14:15], v[14:15], v[222:223], v[250:251] op_sel:[0,1,0] op_sel_hi:[0,0,1] neg_lo:[0,0,1] neg_hi:[0,0,0]
	v_pk_mul_f32 v[250:251], v[14:15], v[80:81] op_sel:[1,1] op_sel_hi:[0,1]
	v_pk_fma_f32 v[14:15], v[14:15], v[80:81], v[250:251] op_sel:[0,0,0] op_sel_hi:[1,0,1] neg_hi:[0,0,1]
	v_pk_mul_f32 v[250:251], v[30:31], v[222:223] op_sel:[1,1] op_sel_hi:[1,0] neg_lo:[0,1] neg_hi:[0,1]
	v_pk_fma_f32 v[30:31], v[30:31], v[222:223], v[250:251] op_sel:[0,0,0] op_sel_hi:[0,1,1] neg_lo:[0,1,1] neg_hi:[0,1,0]
	v_pk_mul_f32 v[250:251], v[30:31], v[84:85] op_sel:[1,1] op_sel_hi:[0,1]
	v_pk_fma_f32 v[30:31], v[30:31], v[84:85], v[250:251] op_sel:[0,0,0] op_sel_hi:[1,0,1] neg_hi:[0,0,1]
	v_pk_add_f32 v[242:243], v[6:7], v[22:23]
	v_pk_add_f32 v[244:245], v[6:7], v[22:23] neg_lo:[0,1] neg_hi:[0,1]
	v_pk_add_f32 v[246:247], v[14:15], v[30:31]
	v_pk_add_f32 v[248:249], v[14:15], v[30:31] neg_lo:[0,1] neg_hi:[0,1]
	v_pk_add_f32 v[6:7], v[242:243], v[246:247]
	ds_write_b64 v227, v[6:7] offset:6144
	v_pk_add_f32 v[14:15], v[244:245], v[248:249] op_sel:[0,1] op_sel_hi:[1,0] neg_lo:[0,1]
	ds_write_b64 v227, v[14:15] offset:14336
	v_pk_add_f32 v[22:23], v[242:243], v[246:247] neg_lo:[0,1] neg_hi:[0,1]
	ds_write_b64 v227, v[22:23] offset:22528
	v_pk_add_f32 v[30:31], v[244:245], v[248:249] op_sel:[0,1] op_sel_hi:[1,0] neg_hi:[0,1]
	ds_write_b64 v227, v[30:31] offset:30720
	s_waitcnt lgkmcnt(0)
	s_barrier
	s_mov_b64 s[12:13], -1
	s_and_b64 vcc, exec, s[50:51]
	s_cbranch_vccz .LBB0_1340
	v_lshlrev_b32_e32 v0, 1, v86
	v_add_u32_e32 v1, 0x1000, v0
	v_add_u32_e32 v2, 0x2000, v0
	v_add_u32_e32 v4, 0x3000, v0
	v_lshlrev_b32_e32 v5, 3, v86
	v_mov_b32_e32 v8, v5
	v_add_u32_e32 v9, 0x10000, v5
	v_lshrrev_b32_e32 v7, 6, v86
	v_lshl_add_u32 v7, v7, 3, s88
	v_and_b32_e32 v108, 63, v86
	v_lshl_add_u32 v108, v108, 3, s91
	ds_read_b64 v[10:11], v108
	s_add_u32 s12, s72, 0x4000
	s_addc_u32 s13, s73, 0
	s_add_u32 s50, s80, 0x8000
	s_addc_u32 s51, s81, 0
	v_mov_b32_e32 v107, 0
	v_mov_b32_e32 v160, 0x38800000
	v_mov_b32_e32 v161, 0x38800000
	v_mov_b32_e32 v106, v0
	v_lshl_add_u64 v[110:111], v[54:55], 0, v[106:107]
	v_lshl_add_u64 v[118:119], v[56:57], 0, v[106:107]
	v_mov_b32_e32 v106, v1
	v_lshl_add_u64 v[112:113], v[54:55], 0, v[106:107]
	v_lshl_add_u64 v[120:121], v[56:57], 0, v[106:107]
	v_mov_b32_e32 v106, v2
	v_lshl_add_u64 v[114:115], v[54:55], 0, v[106:107]
	v_lshl_add_u64 v[122:123], v[56:57], 0, v[106:107]
	v_mov_b32_e32 v106, v4
	v_lshl_add_u64 v[116:117], v[54:55], 0, v[106:107]
	v_lshl_add_u64 v[124:125], v[56:57], 0, v[106:107]
	global_load_ushort v228, v0, s[96:97] offset:0
	global_load_ushort v230, v0, s[74:75] offset:0
	global_load_ushort v232, v0, s[72:73] offset:0
	global_load_ushort v234, v0, s[12:13] offset:0
	global_load_ushort v229, v2, s[96:97] offset:0
	global_load_ushort v231, v2, s[74:75] offset:0
	global_load_ushort v233, v2, s[72:73] offset:0
	global_load_ushort v235, v2, s[12:13] offset:0
	v_mov_b32_e32 v6, v5
	global_load_dwordx2 v[236:237], v6, s[80:81] sc1
	global_load_dwordx2 v[238:239], v6, s[50:51] sc1
	ds_read_b64 v[12:13], v7 offset:0
	ds_read_b64 v[14:15], v8 offset:0
	ds_read_b64 v[16:17], v8 offset:32768
	ds_read_b64 v[18:19], v9 offset:0
	ds_read_b64 v[20:21], v9 offset:32768
	global_load_ushort v240, v0, s[96:97] offset:1024
	global_load_ushort v242, v0, s[74:75] offset:1024
	global_load_ushort v244, v0, s[72:73] offset:1024
	global_load_ushort v246, v0, s[12:13] offset:1024
	global_load_ushort v241, v2, s[96:97] offset:1024
	global_load_ushort v243, v2, s[74:75] offset:1024
	global_load_ushort v245, v2, s[72:73] offset:1024
	global_load_ushort v247, v2, s[12:13] offset:1024
	v_add_u32_e32 v6, 0x1000, v5
	global_load_dwordx2 v[248:249], v6, s[80:81] sc1
	global_load_dwordx2 v[250:251], v6, s[50:51] sc1
	ds_read_b64 v[58:59], v7 offset:64
	ds_read_b64 v[60:61], v8 offset:4096
	ds_read_b64 v[62:63], v8 offset:36864
	ds_read_b64 v[64:65], v9 offset:4096
	ds_read_b64 v[66:67], v9 offset:36864
	s_waitcnt lgkmcnt(5)
	v_pk_mul_f32 v[222:223], v[12:13], v[10:11] op_sel:[1,1] op_sel_hi:[1,0]
	v_pk_fma_f32 v[22:23], v[12:13], v[10:11], v[222:223] op_sel:[0,0,0] op_sel_hi:[0,1,1] neg_lo:[0,0,1]
	v_pk_mul_f32 v[222:223], v[22:23], v[22:23] op_sel:[1,1] op_sel_hi:[1,0]
	v_pk_fma_f32 v[24:25], v[22:23], v[22:23], v[222:223] op_sel:[0,0,0] op_sel_hi:[0,1,1] neg_lo:[0,0,1]
	v_pk_mul_f32 v[222:223], v[24:25], v[22:23] op_sel:[1,1] op_sel_hi:[1,0]
	v_pk_fma_f32 v[26:27], v[24:25], v[22:23], v[222:223] op_sel:[0,0,0] op_sel_hi:[0,1,1] neg_lo:[0,0,1]
	v_pk_mul_f32 v[222:223], v[16:17], v[22:23] op_sel:[1,1] op_sel_hi:[0,1]
	v_pk_fma_f32 v[28:29], v[16:17], v[22:23], v[222:223] op_sel:[0,0,0] op_sel_hi:[1,0,1] neg_hi:[0,0,1]
	v_pk_mul_f32 v[222:223], v[18:19], v[24:25] op_sel:[1,1] op_sel_hi:[0,1]
	v_pk_fma_f32 v[30:31], v[18:19], v[24:25], v[222:223] op_sel:[0,0,0] op_sel_hi:[1,0,1] neg_hi:[0,0,1]
	v_pk_mul_f32 v[222:223], v[20:21], v[26:27] op_sel:[1,1] op_sel_hi:[0,1]
	v_pk_fma_f32 v[68:69], v[20:21], v[26:27], v[222:223] op_sel:[0,0,0] op_sel_hi:[1,0,1] neg_hi:[0,0,1]
	v_pk_add_f32 v[70:71], v[14:15], v[30:31]
	v_pk_add_f32 v[72:73], v[14:15], v[30:31] neg_lo:[0,1] neg_hi:[0,1]
	v_pk_add_f32 v[74:75], v[28:29], v[68:69]
	v_pk_add_f32 v[80:81], v[28:29], v[68:69] neg_lo:[0,1] neg_hi:[0,1]
	v_pk_add_f32 v[82:83], v[70:71], v[74:75]
	v_pk_add_f32 v[84:85], v[72:73], v[80:81] op_sel:[0,1] op_sel_hi:[1,0] neg_lo:[0,1]
	s_waitcnt vmcnt(10)
; __device__ __forceinline__ float bf2f(u16 h){ return __uint_as_float(((unsigned)h)<<16); }
; __device__ __forceinline__ float hconv3(const u16* __restrict__ row, int t, float w0, float w1, float w2, float bias){
;   float m = bf2f(row[t]);
;   int mi=__float_as_int(m);
;   float l=__int_as_float(__builtin_amdgcn_update_dpp(0, mi, 0x138, 0xf, 0xf, false));
;   float r=__int_as_float(__builtin_amdgcn_update_dpp(0, mi, 0x130, 0xf, 0xf, false));
;   return w0*l+w1*m+w2*r+bias;
; __device__ __forceinline__ void phase_hyena(KP kp_, int hf){ asm volatile("" : "+s"(kp_)); const Params p=load_params(kp_);
;     ...
;           _Pragma("unroll 4") for (int i=0;i<8;++i){ int tb=tq+512*i; float2 xr[2]; inv12_half(Z,twA,twB,tb,xr[0],xr[1]);
;             _Pragma("unroll") for (int hh=0;hh<2;++hh){ int t=tb+hh*4096;
;               float x0=hconv3(r2,t,wb0,wb1,wb2,bb_), x1=hconv3(r2+8192,t,wb0,wb1,wb2,bb_);
;               float2 y=xr[hh]; y.x*=(1.f/16384.f); y.y*=(1.f/16384.f); float2 z1=Zs[t];
;               float o0=x0*(y.x+z1.x*bias1)*bf2f(rz[t]); float o1=x1*(y.y+z1.y*bias1)*bf2f(rz[8192+t]);
;               ybT[(size_t)c*16384+t]=f2bf(o0); ybT[(size_t)c*16384+8192+t]=f2bf(o1); } }
	v_lshlrev_b32_e32 v224, 16, v228
	v_mul_f32_e32 v227, v88, v224
	s_nop 0
	v_fmac_f32_dpp v227, v224, v87 wave_shr:1 row_mask:0xf bank_mask:0xf
	v_fmac_f32_dpp v227, v224, v89 wave_shl:1 row_mask:0xf bank_mask:0xf
	v_add_f32_e32 v150, v90, v227
	v_lshlrev_b32_e32 v224, 16, v230
	v_mul_f32_e32 v227, v88, v224
	s_nop 0
	v_fmac_f32_dpp v227, v224, v87 wave_shr:1 row_mask:0xf bank_mask:0xf
	v_fmac_f32_dpp v227, v224, v89 wave_shl:1 row_mask:0xf bank_mask:0xf
	v_add_f32_e32 v151, v90, v227
	v_lshlrev_b32_e32 v224, 16, v229
	v_mul_f32_e32 v227, v88, v224
	s_nop 0
	v_fmac_f32_dpp v227, v224, v87 wave_shr:1 row_mask:0xf bank_mask:0xf
	v_fmac_f32_dpp v227, v224, v89 wave_shl:1 row_mask:0xf bank_mask:0xf
	v_add_f32_e32 v152, v90, v227
	v_lshlrev_b32_e32 v224, 16, v231
	v_mul_f32_e32 v227, v88, v224
	s_nop 0
	v_fmac_f32_dpp v227, v224, v87 wave_shr:1 row_mask:0xf bank_mask:0xf
	v_fmac_f32_dpp v227, v224, v89 wave_shl:1 row_mask:0xf bank_mask:0xf
	v_add_f32_e32 v153, v90, v227
	v_pk_mul_f32 v[158:159], v[236:237], v[90:91] op_sel:[0,1] op_sel_hi:[1,1]
	v_pk_fma_f32 v[158:159], v[82:83], v[160:161], v[158:159]
	v_pk_mul_f32 v[158:159], v[150:151], v[158:159]
	v_lshlrev_b32_e32 v156, 16, v232
	v_lshlrev_b32_e32 v157, 16, v234
	v_pk_mul_f32 v[158:159], v[158:159], v[156:157]
	v_cvt_pk_bf16_f32 v224, v158, v159
	global_store_short v[110:111], v224, off offset:0
	global_store_short_d16_hi v[118:119], v224, off offset:0
	v_pk_mul_f32 v[158:159], v[238:239], v[90:91] op_sel:[0,1] op_sel_hi:[1,1]
	v_pk_fma_f32 v[158:159], v[84:85], v[160:161], v[158:159]
	v_pk_mul_f32 v[158:159], v[152:153], v[158:159]
	v_lshlrev_b32_e32 v156, 16, v233
	v_lshlrev_b32_e32 v157, 16, v235
	v_pk_mul_f32 v[158:159], v[158:159], v[156:157]
	v_cvt_pk_bf16_f32 v224, v158, v159
	global_store_short v[114:115], v224, off offset:0
	global_store_short_d16_hi v[122:123], v224, off offset:0
	global_load_ushort v228, v0, s[96:97] offset:2048
	global_load_ushort v230, v0, s[74:75] offset:2048
	global_load_ushort v232, v0, s[72:73] offset:2048
	global_load_ushort v234, v0, s[12:13] offset:2048
	global_load_ushort v229, v2, s[96:97] offset:2048
	global_load_ushort v231, v2, s[74:75] offset:2048
	global_load_ushort v233, v2, s[72:73] offset:2048
	global_load_ushort v235, v2, s[12:13] offset:2048
	v_add_u32_e32 v6, 0x2000, v5
	global_load_dwordx2 v[236:237], v6, s[80:81] sc1
	global_load_dwordx2 v[238:239], v6, s[50:51] sc1
	ds_read_b64 v[12:13], v7 offset:128
	ds_read_b64 v[14:15], v8 offset:8192
	ds_read_b64 v[16:17], v8 offset:40960
	ds_read_b64 v[18:19], v9 offset:8192
	ds_read_b64 v[20:21], v9 offset:40960
	s_waitcnt lgkmcnt(5)
	v_pk_mul_f32 v[222:223], v[58:59], v[10:11] op_sel:[1,1] op_sel_hi:[1,0]
	v_pk_fma_f32 v[22:23], v[58:59], v[10:11], v[222:223] op_sel:[0,0,0] op_sel_hi:[0,1,1] neg_lo:[0,0,1]
	v_pk_mul_f32 v[222:223], v[22:23], v[22:23] op_sel:[1,1] op_sel_hi:[1,0]
	v_pk_fma_f32 v[24:25], v[22:23], v[22:23], v[222:223] op_sel:[0,0,0] op_sel_hi:[0,1,1] neg_lo:[0,0,1]
	v_pk_mul_f32 v[222:223], v[24:25], v[22:23] op_sel:[1,1] op_sel_hi:[1,0]
	v_pk_fma_f32 v[26:27], v[24:25], v[22:23], v[222:223] op_sel:[0,0,0] op_sel_hi:[0,1,1] neg_lo:[0,0,1]
	v_pk_mul_f32 v[222:223], v[62:63], v[22:23] op_sel:[1,1] op_sel_hi:[0,1]
	v_pk_fma_f32 v[28:29], v[62:63], v[22:23], v[222:223] op_sel:[0,0,0] op_sel_hi:[1,0,1] neg_hi:[0,0,1]
	v_pk_mul_f32 v[222:223], v[64:65], v[24:25] op_sel:[1,1] op_sel_hi:[0,1]
	v_pk_fma_f32 v[30:31], v[64:65], v[24:25], v[222:223] op_sel:[0,0,0] op_sel_hi:[1,0,1] neg_hi:[0,0,1]
	v_pk_mul_f32 v[222:223], v[66:67], v[26:27] op_sel:[1,1] op_sel_hi:[0,1]
	v_pk_fma_f32 v[68:69], v[66:67], v[26:27], v[222:223] op_sel:[0,0,0] op_sel_hi:[1,0,1] neg_hi:[0,0,1]
	v_pk_add_f32 v[70:71], v[60:61], v[30:31]
	v_pk_add_f32 v[72:73], v[60:61], v[30:31] neg_lo:[0,1] neg_hi:[0,1]
	v_pk_add_f32 v[74:75], v[28:29], v[68:69]
	v_pk_add_f32 v[80:81], v[28:29], v[68:69] neg_lo:[0,1] neg_hi:[0,1]
	v_pk_add_f32 v[82:83], v[70:71], v[74:75]
	v_pk_add_f32 v[84:85], v[72:73], v[80:81] op_sel:[0,1] op_sel_hi:[1,0] neg_lo:[0,1]
	s_waitcnt vmcnt(14)
	v_lshlrev_b32_e32 v224, 16, v240
	v_mul_f32_e32 v227, v88, v224
	s_nop 0
	v_fmac_f32_dpp v227, v224, v87 wave_shr:1 row_mask:0xf bank_mask:0xf
	v_fmac_f32_dpp v227, v224, v89 wave_shl:1 row_mask:0xf bank_mask:0xf
	v_add_f32_e32 v150, v90, v227
	v_lshlrev_b32_e32 v224, 16, v242
	v_mul_f32_e32 v227, v88, v224
	s_nop 0
	v_fmac_f32_dpp v227, v224, v87 wave_shr:1 row_mask:0xf bank_mask:0xf
	v_fmac_f32_dpp v227, v224, v89 wave_shl:1 row_mask:0xf bank_mask:0xf
	v_add_f32_e32 v151, v90, v227
	v_lshlrev_b32_e32 v224, 16, v241
	v_mul_f32_e32 v227, v88, v224
	s_nop 0
	v_fmac_f32_dpp v227, v224, v87 wave_shr:1 row_mask:0xf bank_mask:0xf
	v_fmac_f32_dpp v227, v224, v89 wave_shl:1 row_mask:0xf bank_mask:0xf
	v_add_f32_e32 v152, v90, v227
	v_lshlrev_b32_e32 v224, 16, v243
	v_mul_f32_e32 v227, v88, v224
	s_nop 0
	v_fmac_f32_dpp v227, v224, v87 wave_shr:1 row_mask:0xf bank_mask:0xf
	v_fmac_f32_dpp v227, v224, v89 wave_shl:1 row_mask:0xf bank_mask:0xf
	v_add_f32_e32 v153, v90, v227
	v_pk_mul_f32 v[158:159], v[248:249], v[90:91] op_sel:[0,1] op_sel_hi:[1,1]
	v_pk_fma_f32 v[158:159], v[82:83], v[160:161], v[158:159]
	v_pk_mul_f32 v[158:159], v[150:151], v[158:159]
	v_lshlrev_b32_e32 v156, 16, v244
	v_lshlrev_b32_e32 v157, 16, v246
	v_pk_mul_f32 v[158:159], v[158:159], v[156:157]
	v_cvt_pk_bf16_f32 v224, v158, v159
	global_store_short v[110:111], v224, off offset:1024
	global_store_short_d16_hi v[118:119], v224, off offset:1024
	v_pk_mul_f32 v[158:159], v[250:251], v[90:91] op_sel:[0,1] op_sel_hi:[1,1]
	v_pk_fma_f32 v[158:159], v[84:85], v[160:161], v[158:159]
	v_pk_mul_f32 v[158:159], v[152:153], v[158:159]
	v_lshlrev_b32_e32 v156, 16, v245
	v_lshlrev_b32_e32 v157, 16, v247
	v_pk_mul_f32 v[158:159], v[158:159], v[156:157]
	v_cvt_pk_bf16_f32 v224, v158, v159
	global_store_short v[114:115], v224, off offset:1024
	global_store_short_d16_hi v[122:123], v224, off offset:1024
	global_load_ushort v240, v0, s[96:97] offset:3072
	global_load_ushort v242, v0, s[74:75] offset:3072
	global_load_ushort v244, v0, s[72:73] offset:3072
	global_load_ushort v246, v0, s[12:13] offset:3072
	global_load_ushort v241, v2, s[96:97] offset:3072
	global_load_ushort v243, v2, s[74:75] offset:3072
	global_load_ushort v245, v2, s[72:73] offset:3072
	global_load_ushort v247, v2, s[12:13] offset:3072
	v_add_u32_e32 v6, 0x3000, v5
	global_load_dwordx2 v[248:249], v6, s[80:81] sc1
	global_load_dwordx2 v[250:251], v6, s[50:51] sc1
	ds_read_b64 v[58:59], v7 offset:192
	ds_read_b64 v[60:61], v8 offset:12288
	ds_read_b64 v[62:63], v8 offset:45056
	ds_read_b64 v[64:65], v9 offset:12288
	ds_read_b64 v[66:67], v9 offset:45056
	s_waitcnt lgkmcnt(5)
; __device__ __forceinline__ float bf2f(u16 h){ return __uint_as_float(((unsigned)h)<<16); }
; HD float2 cmul(float2 a, float2 b){ return make_float2(a.x*b.x - a.y*b.y, a.x*b.y + a.y*b.x); }
; HD float2 cmulc(float2 a, float2 b){ return make_float2(a.x*b.x + a.y*b.y, a.y*b.x - a.x*b.y); }
; HD void inv12_half(const float2* Z, const float2* twA, const float2* twB, int t, float2& x0, float2& x1){
;   float2 w1=cmul(twA[t>>6],twB[t&63]), w2=cmul(w1,w1), w3=cmul(w2,w1);
;   float2 b0=Z[t], b1=cmulc(Z[t+4096],w1), b2=cmulc(Z[t+8192],w2), b3=cmulc(Z[t+12288],w3);
;   float2 s02=make_float2(b0.x+b2.x,b0.y+b2.y), d02=make_float2(b0.x-b2.x,b0.y-b2.y);
;   float2 s13=make_float2(b1.x+b3.x,b1.y+b3.y), d13=make_float2(b1.x-b3.x,b1.y-b3.y);
;   x0=make_float2(s02.x+s13.x,s02.y+s13.y);
;   x1=make_float2(d02.x-d13.y,d02.y+d13.x);
; }
; __device__ __forceinline__ void phase_hyena(KP kp_, int hf){ asm volatile("" : "+s"(kp_)); const Params p=load_params(kp_);
;     ...
;         } else { int tq=tid; asm volatile("" : "+v"(tq));
;           _Pragma("unroll 4") for (int i=0;i<8;++i){ int tb=tq+512*i; float2 xr[2]; inv12_half(Z,twA,twB,tb,xr[0],xr[1]);
;             _Pragma("unroll") for (int hh=0;hh<2;++hh){ int t=tb+hh*4096;
;               float x0=hconv3(r2,t,wb0,wb1,wb2,bb_), x1=hconv3(r2+8192,t,wb0,wb1,wb2,bb_);
;               float2 y=xr[hh]; y.x*=(1.f/16384.f); y.y*=(1.f/16384.f); float2 z1=Zs[t];
;               float o0=x0*(y.x+z1.x*bias1)*bf2f(rz[t]); float o1=x1*(y.y+z1.y*bias1)*bf2f(rz[8192+t]);
;               ybT[(size_t)c*16384+t]=f2bf(o0); ybT[(size_t)c*16384+8192+t]=f2bf(o1); } }
	v_pk_mul_f32 v[222:223], v[12:13], v[10:11] op_sel:[1,1] op_sel_hi:[1,0]
	v_pk_fma_f32 v[22:23], v[12:13], v[10:11], v[222:223] op_sel:[0,0,0] op_sel_hi:[0,1,1] neg_lo:[0,0,1]
	v_pk_mul_f32 v[222:223], v[22:23], v[22:23] op_sel:[1,1] op_sel_hi:[1,0]
	v_pk_fma_f32 v[24:25], v[22:23], v[22:23], v[222:223] op_sel:[0,0,0] op_sel_hi:[0,1,1] neg_lo:[0,0,1]
	v_pk_mul_f32 v[222:223], v[24:25], v[22:23] op_sel:[1,1] op_sel_hi:[1,0]
	v_pk_fma_f32 v[26:27], v[24:25], v[22:23], v[222:223] op_sel:[0,0,0] op_sel_hi:[0,1,1] neg_lo:[0,0,1]
	v_pk_mul_f32 v[222:223], v[16:17], v[22:23] op_sel:[1,1] op_sel_hi:[0,1]
	v_pk_fma_f32 v[28:29], v[16:17], v[22:23], v[222:223] op_sel:[0,0,0] op_sel_hi:[1,0,1] neg_hi:[0,0,1]
	v_pk_mul_f32 v[222:223], v[18:19], v[24:25] op_sel:[1,1] op_sel_hi:[0,1]
	v_pk_fma_f32 v[30:31], v[18:19], v[24:25], v[222:223] op_sel:[0,0,0] op_sel_hi:[1,0,1] neg_hi:[0,0,1]
	v_pk_mul_f32 v[222:223], v[20:21], v[26:27] op_sel:[1,1] op_sel_hi:[0,1]
	v_pk_fma_f32 v[68:69], v[20:21], v[26:27], v[222:223] op_sel:[0,0,0] op_sel_hi:[1,0,1] neg_hi:[0,0,1]
	v_pk_add_f32 v[70:71], v[14:15], v[30:31]
	v_pk_add_f32 v[72:73], v[14:15], v[30:31] neg_lo:[0,1] neg_hi:[0,1]
	v_pk_add_f32 v[74:75], v[28:29], v[68:69]
	v_pk_add_f32 v[80:81], v[28:29], v[68:69] neg_lo:[0,1] neg_hi:[0,1]
	v_pk_add_f32 v[82:83], v[70:71], v[74:75]
	v_pk_add_f32 v[84:85], v[72:73], v[80:81] op_sel:[0,1] op_sel_hi:[1,0] neg_lo:[0,1]
	s_waitcnt vmcnt(14)
	v_lshlrev_b32_e32 v224, 16, v228
	v_mul_f32_e32 v227, v88, v224
	s_nop 0
	v_fmac_f32_dpp v227, v224, v87 wave_shr:1 row_mask:0xf bank_mask:0xf
	v_fmac_f32_dpp v227, v224, v89 wave_shl:1 row_mask:0xf bank_mask:0xf
	v_add_f32_e32 v150, v90, v227
	v_lshlrev_b32_e32 v224, 16, v230
	v_mul_f32_e32 v227, v88, v224
	s_nop 0
	v_fmac_f32_dpp v227, v224, v87 wave_shr:1 row_mask:0xf bank_mask:0xf
	v_fmac_f32_dpp v227, v224, v89 wave_shl:1 row_mask:0xf bank_mask:0xf
	v_add_f32_e32 v151, v90, v227
	v_lshlrev_b32_e32 v224, 16, v229
	v_mul_f32_e32 v227, v88, v224
	s_nop 0
	v_fmac_f32_dpp v227, v224, v87 wave_shr:1 row_mask:0xf bank_mask:0xf
	v_fmac_f32_dpp v227, v224, v89 wave_shl:1 row_mask:0xf bank_mask:0xf
	v_add_f32_e32 v152, v90, v227
	v_lshlrev_b32_e32 v224, 16, v231
	v_mul_f32_e32 v227, v88, v224
	s_nop 0
	v_fmac_f32_dpp v227, v224, v87 wave_shr:1 row_mask:0xf bank_mask:0xf
	v_fmac_f32_dpp v227, v224, v89 wave_shl:1 row_mask:0xf bank_mask:0xf
	v_add_f32_e32 v153, v90, v227
	v_pk_mul_f32 v[158:159], v[236:237], v[90:91] op_sel:[0,1] op_sel_hi:[1,1]
	v_pk_fma_f32 v[158:159], v[82:83], v[160:161], v[158:159]
	v_pk_mul_f32 v[158:159], v[150:151], v[158:159]
	v_lshlrev_b32_e32 v156, 16, v232
	v_lshlrev_b32_e32 v157, 16, v234
	v_pk_mul_f32 v[158:159], v[158:159], v[156:157]
	v_cvt_pk_bf16_f32 v224, v158, v159
	global_store_short v[110:111], v224, off offset:2048
	global_store_short_d16_hi v[118:119], v224, off offset:2048
	v_pk_mul_f32 v[158:159], v[238:239], v[90:91] op_sel:[0,1] op_sel_hi:[1,1]
	v_pk_fma_f32 v[158:159], v[84:85], v[160:161], v[158:159]
	v_pk_mul_f32 v[158:159], v[152:153], v[158:159]
	v_lshlrev_b32_e32 v156, 16, v233
	v_lshlrev_b32_e32 v157, 16, v235
	v_pk_mul_f32 v[158:159], v[158:159], v[156:157]
	v_cvt_pk_bf16_f32 v224, v158, v159
	global_store_short v[114:115], v224, off offset:2048
	global_store_short_d16_hi v[122:123], v224, off offset:2048
	global_load_ushort v228, v1, s[96:97] offset:0
	global_load_ushort v230, v1, s[74:75] offset:0
	global_load_ushort v232, v1, s[72:73] offset:0
	global_load_ushort v234, v1, s[12:13] offset:0
	global_load_ushort v229, v4, s[96:97] offset:0
	global_load_ushort v231, v4, s[74:75] offset:0
	global_load_ushort v233, v4, s[72:73] offset:0
	global_load_ushort v235, v4, s[12:13] offset:0
	v_add_u32_e32 v6, 0x4000, v5
	global_load_dwordx2 v[236:237], v6, s[80:81] sc1
	global_load_dwordx2 v[238:239], v6, s[50:51] sc1
	ds_read_b64 v[12:13], v7 offset:256
	ds_read_b64 v[14:15], v8 offset:16384
	ds_read_b64 v[16:17], v8 offset:49152
	ds_read_b64 v[18:19], v9 offset:16384
	ds_read_b64 v[20:21], v9 offset:49152
	s_waitcnt lgkmcnt(5)
	v_pk_mul_f32 v[222:223], v[58:59], v[10:11] op_sel:[1,1] op_sel_hi:[1,0]
	v_pk_fma_f32 v[22:23], v[58:59], v[10:11], v[222:223] op_sel:[0,0,0] op_sel_hi:[0,1,1] neg_lo:[0,0,1]
	v_pk_mul_f32 v[222:223], v[22:23], v[22:23] op_sel:[1,1] op_sel_hi:[1,0]
	v_pk_fma_f32 v[24:25], v[22:23], v[22:23], v[222:223] op_sel:[0,0,0] op_sel_hi:[0,1,1] neg_lo:[0,0,1]
	v_pk_mul_f32 v[222:223], v[24:25], v[22:23] op_sel:[1,1] op_sel_hi:[1,0]
	v_pk_fma_f32 v[26:27], v[24:25], v[22:23], v[222:223] op_sel:[0,0,0] op_sel_hi:[0,1,1] neg_lo:[0,0,1]
	v_pk_mul_f32 v[222:223], v[62:63], v[22:23] op_sel:[1,1] op_sel_hi:[0,1]
	v_pk_fma_f32 v[28:29], v[62:63], v[22:23], v[222:223] op_sel:[0,0,0] op_sel_hi:[1,0,1] neg_hi:[0,0,1]
	v_pk_mul_f32 v[222:223], v[64:65], v[24:25] op_sel:[1,1] op_sel_hi:[0,1]
	v_pk_fma_f32 v[30:31], v[64:65], v[24:25], v[222:223] op_sel:[0,0,0] op_sel_hi:[1,0,1] neg_hi:[0,0,1]
	v_pk_mul_f32 v[222:223], v[66:67], v[26:27] op_sel:[1,1] op_sel_hi:[0,1]
	v_pk_fma_f32 v[68:69], v[66:67], v[26:27], v[222:223] op_sel:[0,0,0] op_sel_hi:[1,0,1] neg_hi:[0,0,1]
	v_pk_add_f32 v[70:71], v[60:61], v[30:31]
	v_pk_add_f32 v[72:73], v[60:61], v[30:31] neg_lo:[0,1] neg_hi:[0,1]
	v_pk_add_f32 v[74:75], v[28:29], v[68:69]
	v_pk_add_f32 v[80:81], v[28:29], v[68:69] neg_lo:[0,1] neg_hi:[0,1]
	v_pk_add_f32 v[82:83], v[70:71], v[74:75]
	v_pk_add_f32 v[84:85], v[72:73], v[80:81] op_sel:[0,1] op_sel_hi:[1,0] neg_lo:[0,1]
	s_waitcnt vmcnt(14)
; __device__ __forceinline__ float bf2f(u16 h){ return __uint_as_float(((unsigned)h)<<16); }
; HD float2 cmul(float2 a, float2 b){ return make_float2(a.x*b.x - a.y*b.y, a.x*b.y + a.y*b.x); }
; HD float2 cmulc(float2 a, float2 b){ return make_float2(a.x*b.x + a.y*b.y, a.y*b.x - a.x*b.y); }
; HD void inv12_half(const float2* Z, const float2* twA, const float2* twB, int t, float2& x0, float2& x1){
;   float2 w1=cmul(twA[t>>6],twB[t&63]), w2=cmul(w1,w1), w3=cmul(w2,w1);
;   float2 b0=Z[t], b1=cmulc(Z[t+4096],w1), b2=cmulc(Z[t+8192],w2), b3=cmulc(Z[t+12288],w3);
;   float2 s02=make_float2(b0.x+b2.x,b0.y+b2.y), d02=make_float2(b0.x-b2.x,b0.y-b2.y);
;   float2 s13=make_float2(b1.x+b3.x,b1.y+b3.y), d13=make_float2(b1.x-b3.x,b1.y-b3.y);
;   x0=make_float2(s02.x+s13.x,s02.y+s13.y);
;   x1=make_float2(d02.x-d13.y,d02.y+d13.x);
; }
; __device__ __forceinline__ void phase_hyena(KP kp_, int hf){ asm volatile("" : "+s"(kp_)); const Params p=load_params(kp_);
;     ...
;         } else { int tq=tid; asm volatile("" : "+v"(tq));
;           _Pragma("unroll 4") for (int i=0;i<8;++i){ int tb=tq+512*i; float2 xr[2]; inv12_half(Z,twA,twB,tb,xr[0],xr[1]);
;             _Pragma("unroll") for (int hh=0;hh<2;++hh){ int t=tb+hh*4096;
;               float x0=hconv3(r2,t,wb0,wb1,wb2,bb_), x1=hconv3(r2+8192,t,wb0,wb1,wb2,bb_);
;               float2 y=xr[hh]; y.x*=(1.f/16384.f); y.y*=(1.f/16384.f); float2 z1=Zs[t];
;               float o0=x0*(y.x+z1.x*bias1)*bf2f(rz[t]); float o1=x1*(y.y+z1.y*bias1)*bf2f(rz[8192+t]);
;               ybT[(size_t)c*16384+t]=f2bf(o0); ybT[(size_t)c*16384+8192+t]=f2bf(o1); } }
	v_lshlrev_b32_e32 v224, 16, v240
	v_mul_f32_e32 v227, v88, v224
	s_nop 0
	v_fmac_f32_dpp v227, v224, v87 wave_shr:1 row_mask:0xf bank_mask:0xf
	v_fmac_f32_dpp v227, v224, v89 wave_shl:1 row_mask:0xf bank_mask:0xf
	v_add_f32_e32 v150, v90, v227
	v_lshlrev_b32_e32 v224, 16, v242
	v_mul_f32_e32 v227, v88, v224
	s_nop 0
	v_fmac_f32_dpp v227, v224, v87 wave_shr:1 row_mask:0xf bank_mask:0xf
	v_fmac_f32_dpp v227, v224, v89 wave_shl:1 row_mask:0xf bank_mask:0xf
	v_add_f32_e32 v151, v90, v227
	v_lshlrev_b32_e32 v224, 16, v241
	v_mul_f32_e32 v227, v88, v224
	s_nop 0
	v_fmac_f32_dpp v227, v224, v87 wave_shr:1 row_mask:0xf bank_mask:0xf
	v_fmac_f32_dpp v227, v224, v89 wave_shl:1 row_mask:0xf bank_mask:0xf
	v_add_f32_e32 v152, v90, v227
	v_lshlrev_b32_e32 v224, 16, v243
	v_mul_f32_e32 v227, v88, v224
	s_nop 0
	v_fmac_f32_dpp v227, v224, v87 wave_shr:1 row_mask:0xf bank_mask:0xf
	v_fmac_f32_dpp v227, v224, v89 wave_shl:1 row_mask:0xf bank_mask:0xf
	v_add_f32_e32 v153, v90, v227
	v_pk_mul_f32 v[158:159], v[248:249], v[90:91] op_sel:[0,1] op_sel_hi:[1,1]
	v_pk_fma_f32 v[158:159], v[82:83], v[160:161], v[158:159]
	v_pk_mul_f32 v[158:159], v[150:151], v[158:159]
	v_lshlrev_b32_e32 v156, 16, v244
	v_lshlrev_b32_e32 v157, 16, v246
	v_pk_mul_f32 v[158:159], v[158:159], v[156:157]
	v_cvt_pk_bf16_f32 v224, v158, v159
	global_store_short v[110:111], v224, off offset:3072
	global_store_short_d16_hi v[118:119], v224, off offset:3072
	v_pk_mul_f32 v[158:159], v[250:251], v[90:91] op_sel:[0,1] op_sel_hi:[1,1]
	v_pk_fma_f32 v[158:159], v[84:85], v[160:161], v[158:159]
	v_pk_mul_f32 v[158:159], v[152:153], v[158:159]
	v_lshlrev_b32_e32 v156, 16, v245
	v_lshlrev_b32_e32 v157, 16, v247
	v_pk_mul_f32 v[158:159], v[158:159], v[156:157]
	v_cvt_pk_bf16_f32 v224, v158, v159
	global_store_short v[114:115], v224, off offset:3072
	global_store_short_d16_hi v[122:123], v224, off offset:3072
	global_load_ushort v240, v1, s[96:97] offset:1024
	global_load_ushort v242, v1, s[74:75] offset:1024
	global_load_ushort v244, v1, s[72:73] offset:1024
	global_load_ushort v246, v1, s[12:13] offset:1024
	global_load_ushort v241, v4, s[96:97] offset:1024
	global_load_ushort v243, v4, s[74:75] offset:1024
	global_load_ushort v245, v4, s[72:73] offset:1024
	global_load_ushort v247, v4, s[12:13] offset:1024
	v_add_u32_e32 v6, 0x5000, v5
	global_load_dwordx2 v[248:249], v6, s[80:81] sc1
	global_load_dwordx2 v[250:251], v6, s[50:51] sc1
	ds_read_b64 v[58:59], v7 offset:320
	ds_read_b64 v[60:61], v8 offset:20480
	ds_read_b64 v[62:63], v8 offset:53248
	ds_read_b64 v[64:65], v9 offset:20480
	ds_read_b64 v[66:67], v9 offset:53248
	s_waitcnt lgkmcnt(5)
	v_pk_mul_f32 v[222:223], v[12:13], v[10:11] op_sel:[1,1] op_sel_hi:[1,0]
	v_pk_fma_f32 v[22:23], v[12:13], v[10:11], v[222:223] op_sel:[0,0,0] op_sel_hi:[0,1,1] neg_lo:[0,0,1]
	v_pk_mul_f32 v[222:223], v[22:23], v[22:23] op_sel:[1,1] op_sel_hi:[1,0]
	v_pk_fma_f32 v[24:25], v[22:23], v[22:23], v[222:223] op_sel:[0,0,0] op_sel_hi:[0,1,1] neg_lo:[0,0,1]
	v_pk_mul_f32 v[222:223], v[24:25], v[22:23] op_sel:[1,1] op_sel_hi:[1,0]
	v_pk_fma_f32 v[26:27], v[24:25], v[22:23], v[222:223] op_sel:[0,0,0] op_sel_hi:[0,1,1] neg_lo:[0,0,1]
	v_pk_mul_f32 v[222:223], v[16:17], v[22:23] op_sel:[1,1] op_sel_hi:[0,1]
	v_pk_fma_f32 v[28:29], v[16:17], v[22:23], v[222:223] op_sel:[0,0,0] op_sel_hi:[1,0,1] neg_hi:[0,0,1]
	v_pk_mul_f32 v[222:223], v[18:19], v[24:25] op_sel:[1,1] op_sel_hi:[0,1]
	v_pk_fma_f32 v[30:31], v[18:19], v[24:25], v[222:223] op_sel:[0,0,0] op_sel_hi:[1,0,1] neg_hi:[0,0,1]
	v_pk_mul_f32 v[222:223], v[20:21], v[26:27] op_sel:[1,1] op_sel_hi:[0,1]
	v_pk_fma_f32 v[68:69], v[20:21], v[26:27], v[222:223] op_sel:[0,0,0] op_sel_hi:[1,0,1] neg_hi:[0,0,1]
	v_pk_add_f32 v[70:71], v[14:15], v[30:31]
	v_pk_add_f32 v[72:73], v[14:15], v[30:31] neg_lo:[0,1] neg_hi:[0,1]
	v_pk_add_f32 v[74:75], v[28:29], v[68:69]
	v_pk_add_f32 v[80:81], v[28:29], v[68:69] neg_lo:[0,1] neg_hi:[0,1]
	v_pk_add_f32 v[82:83], v[70:71], v[74:75]
	v_pk_add_f32 v[84:85], v[72:73], v[80:81] op_sel:[0,1] op_sel_hi:[1,0] neg_lo:[0,1]
	s_waitcnt vmcnt(14)
	v_lshlrev_b32_e32 v224, 16, v228
	v_mul_f32_e32 v227, v88, v224
	s_nop 0
	v_fmac_f32_dpp v227, v224, v87 wave_shr:1 row_mask:0xf bank_mask:0xf
	v_fmac_f32_dpp v227, v224, v89 wave_shl:1 row_mask:0xf bank_mask:0xf
	v_add_f32_e32 v150, v90, v227
	v_lshlrev_b32_e32 v224, 16, v230
	v_mul_f32_e32 v227, v88, v224
	s_nop 0
	v_fmac_f32_dpp v227, v224, v87 wave_shr:1 row_mask:0xf bank_mask:0xf
	v_fmac_f32_dpp v227, v224, v89 wave_shl:1 row_mask:0xf bank_mask:0xf
	v_add_f32_e32 v151, v90, v227
	v_lshlrev_b32_e32 v224, 16, v229
	v_mul_f32_e32 v227, v88, v224
	s_nop 0
	v_fmac_f32_dpp v227, v224, v87 wave_shr:1 row_mask:0xf bank_mask:0xf
	v_fmac_f32_dpp v227, v224, v89 wave_shl:1 row_mask:0xf bank_mask:0xf
	v_add_f32_e32 v152, v90, v227
	v_lshlrev_b32_e32 v224, 16, v231
	v_mul_f32_e32 v227, v88, v224
	s_nop 0
	v_fmac_f32_dpp v227, v224, v87 wave_shr:1 row_mask:0xf bank_mask:0xf
	v_fmac_f32_dpp v227, v224, v89 wave_shl:1 row_mask:0xf bank_mask:0xf
	v_add_f32_e32 v153, v90, v227
	v_pk_mul_f32 v[158:159], v[236:237], v[90:91] op_sel:[0,1] op_sel_hi:[1,1]
	v_pk_fma_f32 v[158:159], v[82:83], v[160:161], v[158:159]
	v_pk_mul_f32 v[158:159], v[150:151], v[158:159]
	v_lshlrev_b32_e32 v156, 16, v232
	v_lshlrev_b32_e32 v157, 16, v234
	v_pk_mul_f32 v[158:159], v[158:159], v[156:157]
	v_cvt_pk_bf16_f32 v224, v158, v159
	global_store_short v[112:113], v224, off offset:0
	global_store_short_d16_hi v[120:121], v224, off offset:0
	v_pk_mul_f32 v[158:159], v[238:239], v[90:91] op_sel:[0,1] op_sel_hi:[1,1]
	v_pk_fma_f32 v[158:159], v[84:85], v[160:161], v[158:159]
	v_pk_mul_f32 v[158:159], v[152:153], v[158:159]
	v_lshlrev_b32_e32 v156, 16, v233
	v_lshlrev_b32_e32 v157, 16, v235
	v_pk_mul_f32 v[158:159], v[158:159], v[156:157]
	v_cvt_pk_bf16_f32 v224, v158, v159
	global_store_short v[116:117], v224, off offset:0
	global_store_short_d16_hi v[124:125], v224, off offset:0
	global_load_ushort v228, v1, s[96:97] offset:2048
	global_load_ushort v230, v1, s[74:75] offset:2048
	global_load_ushort v232, v1, s[72:73] offset:2048
	global_load_ushort v234, v1, s[12:13] offset:2048
	global_load_ushort v229, v4, s[96:97] offset:2048
	global_load_ushort v231, v4, s[74:75] offset:2048
	global_load_ushort v233, v4, s[72:73] offset:2048
	global_load_ushort v235, v4, s[12:13] offset:2048
	v_add_u32_e32 v6, 0x6000, v5
	global_load_dwordx2 v[236:237], v6, s[80:81] sc1
	global_load_dwordx2 v[238:239], v6, s[50:51] sc1
	ds_read_b64 v[12:13], v7 offset:384
	ds_read_b64 v[14:15], v8 offset:24576
	ds_read_b64 v[16:17], v8 offset:57344
	ds_read_b64 v[18:19], v9 offset:24576
	ds_read_b64 v[20:21], v9 offset:57344
	s_waitcnt lgkmcnt(5)
; __device__ __forceinline__ float bf2f(u16 h){ return __uint_as_float(((unsigned)h)<<16); }
; HD float2 cmul(float2 a, float2 b){ return make_float2(a.x*b.x - a.y*b.y, a.x*b.y + a.y*b.x); }
; HD float2 cmulc(float2 a, float2 b){ return make_float2(a.x*b.x + a.y*b.y, a.y*b.x - a.x*b.y); }
; HD void inv12_half(const float2* Z, const float2* twA, const float2* twB, int t, float2& x0, float2& x1){
;   float2 w1=cmul(twA[t>>6],twB[t&63]), w2=cmul(w1,w1), w3=cmul(w2,w1);
;   float2 b0=Z[t], b1=cmulc(Z[t+4096],w1), b2=cmulc(Z[t+8192],w2), b3=cmulc(Z[t+12288],w3);
;   float2 s02=make_float2(b0.x+b2.x,b0.y+b2.y), d02=make_float2(b0.x-b2.x,b0.y-b2.y);
;   float2 s13=make_float2(b1.x+b3.x,b1.y+b3.y), d13=make_float2(b1.x-b3.x,b1.y-b3.y);
;   x0=make_float2(s02.x+s13.x,s02.y+s13.y);
;   x1=make_float2(d02.x-d13.y,d02.y+d13.x);
; }
; __device__ __forceinline__ void phase_hyena(KP kp_, int hf){ asm volatile("" : "+s"(kp_)); const Params p=load_params(kp_);
;     ...
;         } else { int tq=tid; asm volatile("" : "+v"(tq));
;           _Pragma("unroll 4") for (int i=0;i<8;++i){ int tb=tq+512*i; float2 xr[2]; inv12_half(Z,twA,twB,tb,xr[0],xr[1]);
;             _Pragma("unroll") for (int hh=0;hh<2;++hh){ int t=tb+hh*4096;
;               float x0=hconv3(r2,t,wb0,wb1,wb2,bb_), x1=hconv3(r2+8192,t,wb0,wb1,wb2,bb_);
;               float2 y=xr[hh]; y.x*=(1.f/16384.f); y.y*=(1.f/16384.f); float2 z1=Zs[t];
;               float o0=x0*(y.x+z1.x*bias1)*bf2f(rz[t]); float o1=x1*(y.y+z1.y*bias1)*bf2f(rz[8192+t]);
;               ybT[(size_t)c*16384+t]=f2bf(o0); ybT[(size_t)c*16384+8192+t]=f2bf(o1); } }
	v_pk_mul_f32 v[222:223], v[58:59], v[10:11] op_sel:[1,1] op_sel_hi:[1,0]
	v_pk_fma_f32 v[22:23], v[58:59], v[10:11], v[222:223] op_sel:[0,0,0] op_sel_hi:[0,1,1] neg_lo:[0,0,1]
	v_pk_mul_f32 v[222:223], v[22:23], v[22:23] op_sel:[1,1] op_sel_hi:[1,0]
	v_pk_fma_f32 v[24:25], v[22:23], v[22:23], v[222:223] op_sel:[0,0,0] op_sel_hi:[0,1,1] neg_lo:[0,0,1]
	v_pk_mul_f32 v[222:223], v[24:25], v[22:23] op_sel:[1,1] op_sel_hi:[1,0]
	v_pk_fma_f32 v[26:27], v[24:25], v[22:23], v[222:223] op_sel:[0,0,0] op_sel_hi:[0,1,1] neg_lo:[0,0,1]
	v_pk_mul_f32 v[222:223], v[62:63], v[22:23] op_sel:[1,1] op_sel_hi:[0,1]
	v_pk_fma_f32 v[28:29], v[62:63], v[22:23], v[222:223] op_sel:[0,0,0] op_sel_hi:[1,0,1] neg_hi:[0,0,1]
	v_pk_mul_f32 v[222:223], v[64:65], v[24:25] op_sel:[1,1] op_sel_hi:[0,1]
	v_pk_fma_f32 v[30:31], v[64:65], v[24:25], v[222:223] op_sel:[0,0,0] op_sel_hi:[1,0,1] neg_hi:[0,0,1]
	v_pk_mul_f32 v[222:223], v[66:67], v[26:27] op_sel:[1,1] op_sel_hi:[0,1]
	v_pk_fma_f32 v[68:69], v[66:67], v[26:27], v[222:223] op_sel:[0,0,0] op_sel_hi:[1,0,1] neg_hi:[0,0,1]
	v_pk_add_f32 v[70:71], v[60:61], v[30:31]
	v_pk_add_f32 v[72:73], v[60:61], v[30:31] neg_lo:[0,1] neg_hi:[0,1]
	v_pk_add_f32 v[74:75], v[28:29], v[68:69]
	v_pk_add_f32 v[80:81], v[28:29], v[68:69] neg_lo:[0,1] neg_hi:[0,1]
	v_pk_add_f32 v[82:83], v[70:71], v[74:75]
	v_pk_add_f32 v[84:85], v[72:73], v[80:81] op_sel:[0,1] op_sel_hi:[1,0] neg_lo:[0,1]
	s_waitcnt vmcnt(14)
	v_lshlrev_b32_e32 v224, 16, v240
	v_mul_f32_e32 v227, v88, v224
	s_nop 0
	v_fmac_f32_dpp v227, v224, v87 wave_shr:1 row_mask:0xf bank_mask:0xf
	v_fmac_f32_dpp v227, v224, v89 wave_shl:1 row_mask:0xf bank_mask:0xf
	v_add_f32_e32 v150, v90, v227
	v_lshlrev_b32_e32 v224, 16, v242
	v_mul_f32_e32 v227, v88, v224
	s_nop 0
	v_fmac_f32_dpp v227, v224, v87 wave_shr:1 row_mask:0xf bank_mask:0xf
	v_fmac_f32_dpp v227, v224, v89 wave_shl:1 row_mask:0xf bank_mask:0xf
	v_add_f32_e32 v151, v90, v227
	v_lshlrev_b32_e32 v224, 16, v241
	v_mul_f32_e32 v227, v88, v224
	s_nop 0
	v_fmac_f32_dpp v227, v224, v87 wave_shr:1 row_mask:0xf bank_mask:0xf
	v_fmac_f32_dpp v227, v224, v89 wave_shl:1 row_mask:0xf bank_mask:0xf
	v_add_f32_e32 v152, v90, v227
	v_lshlrev_b32_e32 v224, 16, v243
	v_mul_f32_e32 v227, v88, v224
	s_nop 0
	v_fmac_f32_dpp v227, v224, v87 wave_shr:1 row_mask:0xf bank_mask:0xf
	v_fmac_f32_dpp v227, v224, v89 wave_shl:1 row_mask:0xf bank_mask:0xf
	v_add_f32_e32 v153, v90, v227
	v_pk_mul_f32 v[158:159], v[248:249], v[90:91] op_sel:[0,1] op_sel_hi:[1,1]
	v_pk_fma_f32 v[158:159], v[82:83], v[160:161], v[158:159]
	v_pk_mul_f32 v[158:159], v[150:151], v[158:159]
	v_lshlrev_b32_e32 v156, 16, v244
	v_lshlrev_b32_e32 v157, 16, v246
	v_pk_mul_f32 v[158:159], v[158:159], v[156:157]
	v_cvt_pk_bf16_f32 v224, v158, v159
	global_store_short v[112:113], v224, off offset:1024
	global_store_short_d16_hi v[120:121], v224, off offset:1024
	v_pk_mul_f32 v[158:159], v[250:251], v[90:91] op_sel:[0,1] op_sel_hi:[1,1]
	v_pk_fma_f32 v[158:159], v[84:85], v[160:161], v[158:159]
	v_pk_mul_f32 v[158:159], v[152:153], v[158:159]
	v_lshlrev_b32_e32 v156, 16, v245
	v_lshlrev_b32_e32 v157, 16, v247
	v_pk_mul_f32 v[158:159], v[158:159], v[156:157]
	v_cvt_pk_bf16_f32 v224, v158, v159
	global_store_short v[116:117], v224, off offset:1024
	global_store_short_d16_hi v[124:125], v224, off offset:1024
	global_load_ushort v240, v1, s[96:97] offset:3072
	global_load_ushort v242, v1, s[74:75] offset:3072
	global_load_ushort v244, v1, s[72:73] offset:3072
	global_load_ushort v246, v1, s[12:13] offset:3072
	global_load_ushort v241, v4, s[96:97] offset:3072
	global_load_ushort v243, v4, s[74:75] offset:3072
	global_load_ushort v245, v4, s[72:73] offset:3072
	global_load_ushort v247, v4, s[12:13] offset:3072
	v_add_u32_e32 v6, 0x7000, v5
	global_load_dwordx2 v[248:249], v6, s[80:81] sc1
	global_load_dwordx2 v[250:251], v6, s[50:51] sc1
	ds_read_b64 v[58:59], v7 offset:448
	ds_read_b64 v[60:61], v8 offset:28672
	ds_read_b64 v[62:63], v8 offset:61440
	ds_read_b64 v[64:65], v9 offset:28672
	ds_read_b64 v[66:67], v9 offset:61440
	s_waitcnt lgkmcnt(5)
	v_pk_mul_f32 v[222:223], v[12:13], v[10:11] op_sel:[1,1] op_sel_hi:[1,0]
	v_pk_fma_f32 v[22:23], v[12:13], v[10:11], v[222:223] op_sel:[0,0,0] op_sel_hi:[0,1,1] neg_lo:[0,0,1]
	v_pk_mul_f32 v[222:223], v[22:23], v[22:23] op_sel:[1,1] op_sel_hi:[1,0]
	v_pk_fma_f32 v[24:25], v[22:23], v[22:23], v[222:223] op_sel:[0,0,0] op_sel_hi:[0,1,1] neg_lo:[0,0,1]
	v_pk_mul_f32 v[222:223], v[24:25], v[22:23] op_sel:[1,1] op_sel_hi:[1,0]
	v_pk_fma_f32 v[26:27], v[24:25], v[22:23], v[222:223] op_sel:[0,0,0] op_sel_hi:[0,1,1] neg_lo:[0,0,1]
	v_pk_mul_f32 v[222:223], v[16:17], v[22:23] op_sel:[1,1] op_sel_hi:[0,1]
	v_pk_fma_f32 v[28:29], v[16:17], v[22:23], v[222:223] op_sel:[0,0,0] op_sel_hi:[1,0,1] neg_hi:[0,0,1]
	v_pk_mul_f32 v[222:223], v[18:19], v[24:25] op_sel:[1,1] op_sel_hi:[0,1]
	v_pk_fma_f32 v[30:31], v[18:19], v[24:25], v[222:223] op_sel:[0,0,0] op_sel_hi:[1,0,1] neg_hi:[0,0,1]
	v_pk_mul_f32 v[222:223], v[20:21], v[26:27] op_sel:[1,1] op_sel_hi:[0,1]
	v_pk_fma_f32 v[68:69], v[20:21], v[26:27], v[222:223] op_sel:[0,0,0] op_sel_hi:[1,0,1] neg_hi:[0,0,1]
	v_pk_add_f32 v[70:71], v[14:15], v[30:31]
	v_pk_add_f32 v[72:73], v[14:15], v[30:31] neg_lo:[0,1] neg_hi:[0,1]
	v_pk_add_f32 v[74:75], v[28:29], v[68:69]
	v_pk_add_f32 v[80:81], v[28:29], v[68:69] neg_lo:[0,1] neg_hi:[0,1]
	v_pk_add_f32 v[82:83], v[70:71], v[74:75]
	v_pk_add_f32 v[84:85], v[72:73], v[80:81] op_sel:[0,1] op_sel_hi:[1,0] neg_lo:[0,1]
	s_waitcnt vmcnt(14)
; __device__ __forceinline__ float bf2f(u16 h){ return __uint_as_float(((unsigned)h)<<16); }
; HD float2 cmul(float2 a, float2 b){ return make_float2(a.x*b.x - a.y*b.y, a.x*b.y + a.y*b.x); }
; HD float2 cmulc(float2 a, float2 b){ return make_float2(a.x*b.x + a.y*b.y, a.y*b.x - a.x*b.y); }
; HD void inv12_half(const float2* Z, const float2* twA, const float2* twB, int t, float2& x0, float2& x1){
;   float2 w1=cmul(twA[t>>6],twB[t&63]), w2=cmul(w1,w1), w3=cmul(w2,w1);
;   float2 b0=Z[t], b1=cmulc(Z[t+4096],w1), b2=cmulc(Z[t+8192],w2), b3=cmulc(Z[t+12288],w3);
;   float2 s02=make_float2(b0.x+b2.x,b0.y+b2.y), d02=make_float2(b0.x-b2.x,b0.y-b2.y);
;   float2 s13=make_float2(b1.x+b3.x,b1.y+b3.y), d13=make_float2(b1.x-b3.x,b1.y-b3.y);
;   x0=make_float2(s02.x+s13.x,s02.y+s13.y);
;   x1=make_float2(d02.x-d13.y,d02.y+d13.x);
; }
; __device__ __forceinline__ void phase_hyena(KP kp_, int hf){ asm volatile("" : "+s"(kp_)); const Params p=load_params(kp_);
;     ...
;         } else { int tq=tid; asm volatile("" : "+v"(tq));
;           _Pragma("unroll 4") for (int i=0;i<8;++i){ int tb=tq+512*i; float2 xr[2]; inv12_half(Z,twA,twB,tb,xr[0],xr[1]);
;             _Pragma("unroll") for (int hh=0;hh<2;++hh){ int t=tb+hh*4096;
;               float x0=hconv3(r2,t,wb0,wb1,wb2,bb_), x1=hconv3(r2+8192,t,wb0,wb1,wb2,bb_);
;               float2 y=xr[hh]; y.x*=(1.f/16384.f); y.y*=(1.f/16384.f); float2 z1=Zs[t];
;               float o0=x0*(y.x+z1.x*bias1)*bf2f(rz[t]); float o1=x1*(y.y+z1.y*bias1)*bf2f(rz[8192+t]);
;               ybT[(size_t)c*16384+t]=f2bf(o0); ybT[(size_t)c*16384+8192+t]=f2bf(o1); } }
	v_lshlrev_b32_e32 v224, 16, v228
	v_mul_f32_e32 v227, v88, v224
	s_nop 0
	v_fmac_f32_dpp v227, v224, v87 wave_shr:1 row_mask:0xf bank_mask:0xf
	v_fmac_f32_dpp v227, v224, v89 wave_shl:1 row_mask:0xf bank_mask:0xf
	v_add_f32_e32 v150, v90, v227
	v_lshlrev_b32_e32 v224, 16, v230
	v_mul_f32_e32 v227, v88, v224
	s_nop 0
	v_fmac_f32_dpp v227, v224, v87 wave_shr:1 row_mask:0xf bank_mask:0xf
	v_fmac_f32_dpp v227, v224, v89 wave_shl:1 row_mask:0xf bank_mask:0xf
	v_add_f32_e32 v151, v90, v227
	v_lshlrev_b32_e32 v224, 16, v229
	v_mul_f32_e32 v227, v88, v224
	s_nop 0
	v_fmac_f32_dpp v227, v224, v87 wave_shr:1 row_mask:0xf bank_mask:0xf
	v_fmac_f32_dpp v227, v224, v89 wave_shl:1 row_mask:0xf bank_mask:0xf
	v_add_f32_e32 v152, v90, v227
	v_lshlrev_b32_e32 v224, 16, v231
	v_mul_f32_e32 v227, v88, v224
	s_nop 0
	v_fmac_f32_dpp v227, v224, v87 wave_shr:1 row_mask:0xf bank_mask:0xf
	v_fmac_f32_dpp v227, v224, v89 wave_shl:1 row_mask:0xf bank_mask:0xf
	v_add_f32_e32 v153, v90, v227
	v_pk_mul_f32 v[158:159], v[236:237], v[90:91] op_sel:[0,1] op_sel_hi:[1,1]
	v_pk_fma_f32 v[158:159], v[82:83], v[160:161], v[158:159]
	v_pk_mul_f32 v[158:159], v[150:151], v[158:159]
	v_lshlrev_b32_e32 v156, 16, v232
	v_lshlrev_b32_e32 v157, 16, v234
	v_pk_mul_f32 v[158:159], v[158:159], v[156:157]
	v_cvt_pk_bf16_f32 v224, v158, v159
	global_store_short v[112:113], v224, off offset:2048
	global_store_short_d16_hi v[120:121], v224, off offset:2048
	v_pk_mul_f32 v[158:159], v[238:239], v[90:91] op_sel:[0,1] op_sel_hi:[1,1]
	v_pk_fma_f32 v[158:159], v[84:85], v[160:161], v[158:159]
	v_pk_mul_f32 v[158:159], v[152:153], v[158:159]
	v_lshlrev_b32_e32 v156, 16, v233
	v_lshlrev_b32_e32 v157, 16, v235
	v_pk_mul_f32 v[158:159], v[158:159], v[156:157]
	v_cvt_pk_bf16_f32 v224, v158, v159
	global_store_short v[116:117], v224, off offset:2048
	global_store_short_d16_hi v[124:125], v224, off offset:2048
	s_waitcnt lgkmcnt(0)
	v_pk_mul_f32 v[222:223], v[58:59], v[10:11] op_sel:[1,1] op_sel_hi:[1,0]
	v_pk_fma_f32 v[22:23], v[58:59], v[10:11], v[222:223] op_sel:[0,0,0] op_sel_hi:[0,1,1] neg_lo:[0,0,1]
	v_pk_mul_f32 v[222:223], v[22:23], v[22:23] op_sel:[1,1] op_sel_hi:[1,0]
	v_pk_fma_f32 v[24:25], v[22:23], v[22:23], v[222:223] op_sel:[0,0,0] op_sel_hi:[0,1,1] neg_lo:[0,0,1]
	v_pk_mul_f32 v[222:223], v[24:25], v[22:23] op_sel:[1,1] op_sel_hi:[1,0]
	v_pk_fma_f32 v[26:27], v[24:25], v[22:23], v[222:223] op_sel:[0,0,0] op_sel_hi:[0,1,1] neg_lo:[0,0,1]
	v_pk_mul_f32 v[222:223], v[62:63], v[22:23] op_sel:[1,1] op_sel_hi:[0,1]
	v_pk_fma_f32 v[28:29], v[62:63], v[22:23], v[222:223] op_sel:[0,0,0] op_sel_hi:[1,0,1] neg_hi:[0,0,1]
	v_pk_mul_f32 v[222:223], v[64:65], v[24:25] op_sel:[1,1] op_sel_hi:[0,1]
	v_pk_fma_f32 v[30:31], v[64:65], v[24:25], v[222:223] op_sel:[0,0,0] op_sel_hi:[1,0,1] neg_hi:[0,0,1]
	v_pk_mul_f32 v[222:223], v[66:67], v[26:27] op_sel:[1,1] op_sel_hi:[0,1]
	v_pk_fma_f32 v[68:69], v[66:67], v[26:27], v[222:223] op_sel:[0,0,0] op_sel_hi:[1,0,1] neg_hi:[0,0,1]
	v_pk_add_f32 v[70:71], v[60:61], v[30:31]
	v_pk_add_f32 v[72:73], v[60:61], v[30:31] neg_lo:[0,1] neg_hi:[0,1]
	v_pk_add_f32 v[74:75], v[28:29], v[68:69]
	v_pk_add_f32 v[80:81], v[28:29], v[68:69] neg_lo:[0,1] neg_hi:[0,1]
	v_pk_add_f32 v[82:83], v[70:71], v[74:75]
	v_pk_add_f32 v[84:85], v[72:73], v[80:81] op_sel:[0,1] op_sel_hi:[1,0] neg_lo:[0,1]
	s_waitcnt vmcnt(4)
	v_lshlrev_b32_e32 v224, 16, v240
	v_mul_f32_e32 v227, v88, v224
	s_nop 0
	v_fmac_f32_dpp v227, v224, v87 wave_shr:1 row_mask:0xf bank_mask:0xf
	v_fmac_f32_dpp v227, v224, v89 wave_shl:1 row_mask:0xf bank_mask:0xf
	v_add_f32_e32 v150, v90, v227
	v_lshlrev_b32_e32 v224, 16, v242
	v_mul_f32_e32 v227, v88, v224
	s_nop 0
	v_fmac_f32_dpp v227, v224, v87 wave_shr:1 row_mask:0xf bank_mask:0xf
	v_fmac_f32_dpp v227, v224, v89 wave_shl:1 row_mask:0xf bank_mask:0xf
	v_add_f32_e32 v151, v90, v227
	v_lshlrev_b32_e32 v224, 16, v241
	v_mul_f32_e32 v227, v88, v224
	s_nop 0
	v_fmac_f32_dpp v227, v224, v87 wave_shr:1 row_mask:0xf bank_mask:0xf
	v_fmac_f32_dpp v227, v224, v89 wave_shl:1 row_mask:0xf bank_mask:0xf
	v_add_f32_e32 v152, v90, v227
	v_lshlrev_b32_e32 v224, 16, v243
	v_mul_f32_e32 v227, v88, v224
	s_nop 0
	v_fmac_f32_dpp v227, v224, v87 wave_shr:1 row_mask:0xf bank_mask:0xf
	v_fmac_f32_dpp v227, v224, v89 wave_shl:1 row_mask:0xf bank_mask:0xf
	v_add_f32_e32 v153, v90, v227
	v_pk_mul_f32 v[158:159], v[248:249], v[90:91] op_sel:[0,1] op_sel_hi:[1,1]
	v_pk_fma_f32 v[158:159], v[82:83], v[160:161], v[158:159]
	v_pk_mul_f32 v[158:159], v[150:151], v[158:159]
	v_lshlrev_b32_e32 v156, 16, v244
	v_lshlrev_b32_e32 v157, 16, v246
	v_pk_mul_f32 v[158:159], v[158:159], v[156:157]
	v_cvt_pk_bf16_f32 v224, v158, v159
	global_store_short v[112:113], v224, off offset:3072
	global_store_short_d16_hi v[120:121], v224, off offset:3072
	v_pk_mul_f32 v[158:159], v[250:251], v[90:91] op_sel:[0,1] op_sel_hi:[1,1]
	v_pk_fma_f32 v[158:159], v[84:85], v[160:161], v[158:159]
	v_pk_mul_f32 v[158:159], v[152:153], v[158:159]
	v_lshlrev_b32_e32 v156, 16, v245
	v_lshlrev_b32_e32 v157, 16, v247
	v_pk_mul_f32 v[158:159], v[158:159], v[156:157]
	v_cvt_pk_bf16_f32 v224, v158, v159
	global_store_short v[116:117], v224, off offset:3072
	global_store_short_d16_hi v[124:125], v224, off offset:3072
	s_mov_b32 s50, 0x2000
	s_mov_b32 s51, 0
	s_mov_b64 s[12:13], 0
